# K-loop exit test moved into the MFMA shadow of the last block (last 4 MFMAs duplicated on the exit path)
# speedup vs baseline: 1.0099x; 1.0014x over previous
; #define PG8_STAGE(bufoff, gbase, voff) do { _Pragma("unroll") for (int _i = 0; _i < 2; ++_i) \
;         __builtin_amdgcn_global_load_lds((const unsigned*)((const char*)(gbase) + (voff)[_i]), (PG8_LAS unsigned*)(lds + (bufoff) + ldsw + _i * 8192), 16, 0, 0); } while (0)
; #define PG8_LDA(dst, b, h) do { _Pragma("unroll") for (int m = 0; m < 4; ++m) _Pragma("unroll") for (int k = 0; k < 2; ++k) dst[m][k] = *(const PG8_LAS bf16x8*)(lds + PG8_SA(b, h) + aoff + m * 2048 + k * 1024); } while (0)
; #define PG8_LDB(dst, b, h) do { _Pragma("unroll") for (int n = 0; n < 2; ++n) _Pragma("unroll") for (int k = 0; k < 2; ++k) dst[n][k] = *(const PG8_LAS bf16x8*)(lds + PG8_SB(b, h) + boff + n * 2048 + k * 1024); } while (0)
; #define PG8_MMA(ai, bj, At, Bt) do { __builtin_amdgcn_s_setprio(1); _Pragma("unroll") for (int m = 0; m < 4; ++m) _Pragma("unroll") for (int n = 0; n < 2; ++n) _Pragma("unroll") for (int k = 0; k < 2; ++k) \
;         acc[ai][bj][m][n] = __builtin_amdgcn_mfma_f32_16x16x32_bf16(Bt[n][k], At[m][k], acc[ai][bj][m][n], 0, 0, 0); __builtin_amdgcn_s_setprio(0); } while (0)
; #define PG8_WAIT_V(n) asm volatile("s_waitcnt vmcnt(" #n ")" ::: "memory")
; template <class Epi, class Sched>
; __device__ __forceinline__ void gemm_phase(PG8_LAS unsigned char* lds, const Gemm g, const Sched& S, const Epi& E) {
;     ...
;         for (int t = 0; t < nt; t += 2) {
;             const bool last = (t == nt - 2);
;             const char* a1 = cA + (size_t)(t + 1) * kstep;
;             const char* a2 = last ? nA : cA + (size_t)(t + 2) * kstep; const char* b2 = last ? nB : cB + (size_t)(t + 2) * kstepB;
;             const char* a3 = a2 + kstep; const char* b3 = b2 + kstepB;
;             if (last && has_next) S.a_ready(nxt);
;             PG8_LDB(B0, 0, 0); PG8_SCHED; PG8_LDA(At, 0, 0); PG8_STAGE(PG8_SA(1, 1), a1 + hstep, voffA);
;             PG8_WAIT_L(8); PG8_BAR; PG8_WAIT_L(0); PG8_MMA(0, 0, At, B0); PG8_BAR; PG8_SCHED;
;             PG8_LDB(B1, 0, 1); PG8_STAGE(PG8_SB(0, 0), b2, voffB);
;             PG8_BAR; PG8_WAIT_L(0); PG8_MMA(0, 1, At, B1); PG8_BAR;
;             PG8_LDA(At, 0, 1); PG8_STAGE(PG8_SA(0, 0), a2, voffA);
;             PG8_BAR; PG8_WAIT_L(0); PG8_MMA(1, 0, At, B0); PG8_BAR; PG8_SCHED;
;             PG8_STAGE(PG8_SB(0, 1), b2 + hstepB, voffB);
;             PG8_WAIT_V(6); PG8_BAR; PG8_MMA(1, 1, At, B1); PG8_BAR;
.Lhalf_skip_y_0:
.LBB0_79:
	ds_read_b128 v[152:155], v149
	ds_read_b128 v[156:159], v149 offset:1024
	ds_read_b128 v[160:163], v149 offset:2048
	ds_read_b128 v[164:167], v149 offset:3072
	s_add_u32 s24, s22, 0xfff80080
	s_addc_u32 s25, s23, -1
	s_cmp_eq_u32 s61, 28
	s_cselect_b32 s27, s13, s25
	s_cselect_b32 s26, s57, s24
	s_cselect_b32 s25, s15, s60
	s_cselect_b32 s24, s58, s59
	s_add_i32 m0, s21, 0xc000
	ds_read_b128 v[168:171], v150
	ds_read_b128 v[172:175], v150 offset:1024
	ds_read_b128 v[176:179], v150 offset:2048
	ds_read_b128 v[180:183], v150 offset:3072
	ds_read_b128 v[184:187], v150 offset:4096
	ds_read_b128 v[188:191], v150 offset:5120
	ds_read_b128 v[192:195], v150 offset:6144
	ds_read_b128 v[196:199], v150 offset:7168
	global_load_lds_dwordx4 v136, s[22:23]
	s_add_i32 m0, s21, 0xe000
	s_nop 0
	global_load_lds_dwordx4 v138, s[22:23]
	s_add_i32 s62, s53, s38
	s_mov_b32 m0, s62
	ds_read_b128 v[200:203], v151
	ds_read_b128 v[204:207], v151 offset:1024
	ds_read_b128 v[208:211], v151 offset:2048
	ds_read_b128 v[212:215], v151 offset:3072
	s_waitcnt vmcnt(8)
	s_waitcnt lgkmcnt(0)
	s_barrier
	v_mfma_f32_16x16x32_bf16 v[124:127], v[152:155], v[168:171], v[124:127]
	v_mfma_f32_16x16x32_bf16 v[120:123], v[160:163], v[168:171], v[120:123]
	v_mfma_f32_16x16x32_bf16 v[108:111], v[152:155], v[176:179], v[108:111]
	v_mfma_f32_16x16x32_bf16 v[104:107], v[160:163], v[176:179], v[104:107]
	v_mfma_f32_16x16x32_bf16 v[92:95], v[152:155], v[184:187], v[92:95]
	v_mfma_f32_16x16x32_bf16 v[88:91], v[160:163], v[184:187], v[88:91]
	v_mfma_f32_16x16x32_bf16 v[76:79], v[152:155], v[192:195], v[76:79]
	v_mfma_f32_16x16x32_bf16 v[72:75], v[160:163], v[192:195], v[72:75]
	v_mfma_f32_16x16x32_bf16 v[124:127], v[156:159], v[172:175], v[124:127]
	v_mfma_f32_16x16x32_bf16 v[120:123], v[164:167], v[172:175], v[120:123]
	v_mfma_f32_16x16x32_bf16 v[108:111], v[156:159], v[180:183], v[108:111]
	v_mfma_f32_16x16x32_bf16 v[104:107], v[164:167], v[180:183], v[104:107]
	v_mfma_f32_16x16x32_bf16 v[92:95], v[156:159], v[188:191], v[92:95]
	v_mfma_f32_16x16x32_bf16 v[88:91], v[164:167], v[188:191], v[88:91]
	v_mfma_f32_16x16x32_bf16 v[76:79], v[156:159], v[196:199], v[76:79]
	v_mfma_f32_16x16x32_bf16 v[72:75], v[164:167], v[196:199], v[72:75]
	v_mfma_f32_16x16x32_bf16 v[116:119], v[200:203], v[168:171], v[116:119]
	v_mfma_f32_16x16x32_bf16 v[112:115], v[208:211], v[168:171], v[112:115]
	v_mfma_f32_16x16x32_bf16 v[100:103], v[200:203], v[176:179], v[100:103]
	v_mfma_f32_16x16x32_bf16 v[96:99], v[208:211], v[176:179], v[96:99]
	v_mfma_f32_16x16x32_bf16 v[84:87], v[200:203], v[184:187], v[84:87]
	v_mfma_f32_16x16x32_bf16 v[80:83], v[208:211], v[184:187], v[80:83]
	v_mfma_f32_16x16x32_bf16 v[68:71], v[200:203], v[192:195], v[68:71]
	v_mfma_f32_16x16x32_bf16 v[64:67], v[208:211], v[192:195], v[64:67]
	v_mfma_f32_16x16x32_bf16 v[116:119], v[204:207], v[172:175], v[116:119]
	v_mfma_f32_16x16x32_bf16 v[112:115], v[212:215], v[172:175], v[112:115]
	v_mfma_f32_16x16x32_bf16 v[100:103], v[204:207], v[180:183], v[100:103]
	v_mfma_f32_16x16x32_bf16 v[96:99], v[212:215], v[180:183], v[96:99]
	v_mfma_f32_16x16x32_bf16 v[84:87], v[204:207], v[188:191], v[84:87]
	v_mfma_f32_16x16x32_bf16 v[80:83], v[212:215], v[188:191], v[80:83]
	v_mfma_f32_16x16x32_bf16 v[68:71], v[204:207], v[196:199], v[68:71]
	v_mfma_f32_16x16x32_bf16 v[64:67], v[212:215], v[196:199], v[64:67]
	s_barrier
	global_load_lds_dwordx4 v128, s[24:25]
	s_add_i32 m0, s62, 0x2000
	s_nop 0
	global_load_lds_dwordx4 v130, s[24:25]
	s_mov_b32 m0, s21
	v_lshl_add_u64 v[144:145], s[26:27], 0, v[134:135]
	ds_read_b128 v[168:171], v150 offset:16384
	ds_read_b128 v[172:175], v150 offset:17408
	ds_read_b128 v[176:179], v150 offset:18432
	ds_read_b128 v[180:183], v150 offset:19456
	ds_read_b128 v[184:187], v150 offset:20480
	ds_read_b128 v[188:191], v150 offset:21504
	ds_read_b128 v[192:195], v150 offset:22528
	ds_read_b128 v[196:199], v150 offset:23552
	global_load_lds_dwordx4 v[144:145], off
	v_lshl_add_u64 v[216:217], s[26:27], 0, v[132:133]
	s_mov_b32 m0, s46
	s_nop 0
	global_load_lds_dwordx4 v[216:217], off
	s_add_u32 s62, s24, 0x4000
	s_addc_u32 s63, s25, 0
	s_add_i32 s64, s54, s38
	s_mov_b32 m0, s64
	s_nop 0
	global_load_lds_dwordx4 v128, s[62:63]
	s_add_i32 m0, s64, 0x2000
	s_nop 0
	global_load_lds_dwordx4 v130, s[62:63]
	s_waitcnt vmcnt(8)
	s_waitcnt lgkmcnt(0)
	s_barrier
	v_mfma_f32_16x16x32_bf16 v[60:63], v[152:155], v[168:171], v[60:63]
	v_mfma_f32_16x16x32_bf16 v[56:59], v[160:163], v[168:171], v[56:59]
	v_mfma_f32_16x16x32_bf16 v[44:47], v[152:155], v[176:179], v[44:47]
	v_mfma_f32_16x16x32_bf16 v[40:43], v[160:163], v[176:179], v[40:43]
	v_mfma_f32_16x16x32_bf16 v[28:31], v[152:155], v[184:187], v[28:31]
	v_mfma_f32_16x16x32_bf16 v[24:27], v[160:163], v[184:187], v[24:27]
	v_mfma_f32_16x16x32_bf16 v[12:15], v[152:155], v[192:195], v[12:15]
	v_mfma_f32_16x16x32_bf16 v[8:11], v[160:163], v[192:195], v[8:11]
	v_mfma_f32_16x16x32_bf16 v[60:63], v[156:159], v[172:175], v[60:63]
	v_mfma_f32_16x16x32_bf16 v[56:59], v[164:167], v[172:175], v[56:59]
	v_mfma_f32_16x16x32_bf16 v[44:47], v[156:159], v[180:183], v[44:47]
	v_mfma_f32_16x16x32_bf16 v[40:43], v[164:167], v[180:183], v[40:43]
	v_mfma_f32_16x16x32_bf16 v[28:31], v[156:159], v[188:191], v[28:31]
	v_mfma_f32_16x16x32_bf16 v[24:27], v[164:167], v[188:191], v[24:27]
	v_mfma_f32_16x16x32_bf16 v[12:15], v[156:159], v[196:199], v[12:15]
	v_mfma_f32_16x16x32_bf16 v[8:11], v[164:167], v[196:199], v[8:11]
	v_mfma_f32_16x16x32_bf16 v[52:55], v[200:203], v[168:171], v[52:55]
	v_mfma_f32_16x16x32_bf16 v[48:51], v[208:211], v[168:171], v[48:51]
	v_mfma_f32_16x16x32_bf16 v[36:39], v[200:203], v[176:179], v[36:39]
	v_mfma_f32_16x16x32_bf16 v[32:35], v[208:211], v[176:179], v[32:35]
	v_mfma_f32_16x16x32_bf16 v[20:23], v[200:203], v[184:187], v[20:23]
	v_mfma_f32_16x16x32_bf16 v[16:19], v[208:211], v[184:187], v[16:19]
	v_mfma_f32_16x16x32_bf16 v[4:7], v[200:203], v[192:195], v[4:7]
	v_mfma_f32_16x16x32_bf16 v[0:3], v[208:211], v[192:195], v[0:3]
	v_mfma_f32_16x16x32_bf16 v[52:55], v[204:207], v[172:175], v[52:55]
	v_mfma_f32_16x16x32_bf16 v[48:51], v[212:215], v[172:175], v[48:51]
	v_mfma_f32_16x16x32_bf16 v[36:39], v[204:207], v[180:183], v[36:39]
	v_mfma_f32_16x16x32_bf16 v[32:35], v[212:215], v[180:183], v[32:35]
	v_mfma_f32_16x16x32_bf16 v[20:23], v[204:207], v[188:191], v[20:23]
	v_mfma_f32_16x16x32_bf16 v[16:19], v[212:215], v[188:191], v[16:19]
	v_mfma_f32_16x16x32_bf16 v[4:7], v[204:207], v[196:199], v[4:7]
	v_mfma_f32_16x16x32_bf16 v[0:3], v[212:215], v[196:199], v[0:3]
	s_barrier
; #define PG8_STAGE(bufoff, gbase, voff) do { _Pragma("unroll") for (int _i = 0; _i < 2; ++_i) \
;         __builtin_amdgcn_global_load_lds((const unsigned*)((const char*)(gbase) + (voff)[_i]), (PG8_LAS unsigned*)(lds + (bufoff) + ldsw + _i * 8192), 16, 0, 0); } while (0)
; #define PG8_LDA(dst, b, h) do { _Pragma("unroll") for (int m = 0; m < 4; ++m) _Pragma("unroll") for (int k = 0; k < 2; ++k) dst[m][k] = *(const PG8_LAS bf16x8*)(lds + PG8_SA(b, h) + aoff + m * 2048 + k * 1024); } while (0)
; #define PG8_LDB(dst, b, h) do { _Pragma("unroll") for (int n = 0; n < 2; ++n) _Pragma("unroll") for (int k = 0; k < 2; ++k) dst[n][k] = *(const PG8_LAS bf16x8*)(lds + PG8_SB(b, h) + boff + n * 2048 + k * 1024); } while (0)
; #define PG8_MMA(ai, bj, At, Bt) do { __builtin_amdgcn_s_setprio(1); _Pragma("unroll") for (int m = 0; m < 4; ++m) _Pragma("unroll") for (int n = 0; n < 2; ++n) _Pragma("unroll") for (int k = 0; k < 2; ++k) \
;         acc[ai][bj][m][n] = __builtin_amdgcn_mfma_f32_16x16x32_bf16(Bt[n][k], At[m][k], acc[ai][bj][m][n], 0, 0, 0); __builtin_amdgcn_s_setprio(0); } while (0)
; #define PG8_WAIT_V(n) asm volatile("s_waitcnt vmcnt(" #n ")" ::: "memory")
; #define PG8_WAIT_L(n) asm volatile("s_waitcnt lgkmcnt(" #n ")" ::: "memory")
; #define PG8_BAR __builtin_amdgcn_s_barrier()
; #define PG8_SCHED __builtin_amdgcn_sched_barrier(0)
; template <class Epi, class Sched>
; __device__ __forceinline__ void gemm_phase(PG8_LAS unsigned char* lds, const Gemm g, const Sched& S, const Epi& E) {
;     ...
;             PG8_LDB(B0, 1, 0); PG8_SCHED; PG8_LDA(At, 1, 0); PG8_STAGE(PG8_SA(0, 1), a2 + hstep, voffA);
;             PG8_WAIT_L(8); PG8_BAR; PG8_WAIT_L(0); PG8_MMA(0, 0, At, B0); PG8_BAR; PG8_SCHED;
;             PG8_LDB(B1, 1, 1); PG8_STAGE(PG8_SB(1, 0), b3, voffB);
;             PG8_BAR; PG8_WAIT_L(0); PG8_MMA(0, 1, At, B1); PG8_BAR;
;             PG8_LDA(At, 1, 1); PG8_STAGE(PG8_SA(1, 0), a3, voffA);
;             PG8_BAR; PG8_WAIT_L(0); PG8_MMA(1, 0, At, B0); PG8_BAR; PG8_SCHED;
;             PG8_STAGE(PG8_SB(1, 1), b3 + hstepB, voffB);
;             PG8_WAIT_V(6); PG8_BAR; PG8_MMA(1, 1, At, B1); PG8_BAR;
	s_add_i32 s62, 0, 0x18000
	v_add_u32_e32 v164, s62, v147
	ds_read_b128 v[152:155], v164
	ds_read_b128 v[156:159], v164 offset:1024
	ds_read_b128 v[160:163], v164 offset:2048
	ds_read_b128 v[164:167], v164 offset:3072
	s_add_u32 s26, s26, 0x80000
	s_addc_u32 s27, s27, 0
	s_mov_b32 m0, s47
	ds_read_b128 v[168:171], v150 offset:32768
	ds_read_b128 v[172:175], v150 offset:33792
	ds_read_b128 v[176:179], v150 offset:34816
	ds_read_b128 v[180:183], v150 offset:35840
	ds_read_b128 v[184:187], v150 offset:36864
	ds_read_b128 v[188:191], v150 offset:37888
	ds_read_b128 v[192:195], v150 offset:38912
	ds_read_b128 v[196:199], v150 offset:39936
	global_load_lds_dwordx4 v134, s[26:27]
	s_mov_b32 m0, s48
	s_nop 0
	global_load_lds_dwordx4 v132, s[26:27]
	s_add_i32 s63, 0, 0x1c000
	s_add_u32 s26, s24, 0x8000
	s_addc_u32 s27, s25, 0
	s_add_i32 s62, s62, s38
	v_add_u32_e32 v212, s63, v147
	s_mov_b32 m0, s62
	ds_read_b128 v[200:203], v212
	ds_read_b128 v[204:207], v212 offset:1024
	ds_read_b128 v[208:211], v212 offset:2048
	ds_read_b128 v[212:215], v212 offset:3072
	s_waitcnt vmcnt(8)
	s_waitcnt lgkmcnt(0)
	s_barrier
	v_mfma_f32_16x16x32_bf16 v[124:127], v[152:155], v[168:171], v[124:127]
	v_mfma_f32_16x16x32_bf16 v[120:123], v[160:163], v[168:171], v[120:123]
	v_mfma_f32_16x16x32_bf16 v[108:111], v[152:155], v[176:179], v[108:111]
	v_mfma_f32_16x16x32_bf16 v[104:107], v[160:163], v[176:179], v[104:107]
	v_mfma_f32_16x16x32_bf16 v[92:95], v[152:155], v[184:187], v[92:95]
	v_mfma_f32_16x16x32_bf16 v[88:91], v[160:163], v[184:187], v[88:91]
	v_mfma_f32_16x16x32_bf16 v[76:79], v[152:155], v[192:195], v[76:79]
	v_mfma_f32_16x16x32_bf16 v[72:75], v[160:163], v[192:195], v[72:75]
	v_mfma_f32_16x16x32_bf16 v[124:127], v[156:159], v[172:175], v[124:127]
	v_mfma_f32_16x16x32_bf16 v[120:123], v[164:167], v[172:175], v[120:123]
	v_mfma_f32_16x16x32_bf16 v[108:111], v[156:159], v[180:183], v[108:111]
	v_mfma_f32_16x16x32_bf16 v[104:107], v[164:167], v[180:183], v[104:107]
	v_mfma_f32_16x16x32_bf16 v[92:95], v[156:159], v[188:191], v[92:95]
	v_mfma_f32_16x16x32_bf16 v[88:91], v[164:167], v[188:191], v[88:91]
	v_mfma_f32_16x16x32_bf16 v[76:79], v[156:159], v[196:199], v[76:79]
	v_mfma_f32_16x16x32_bf16 v[72:75], v[164:167], v[196:199], v[72:75]
	v_mfma_f32_16x16x32_bf16 v[116:119], v[200:203], v[168:171], v[116:119]
	v_mfma_f32_16x16x32_bf16 v[112:115], v[208:211], v[168:171], v[112:115]
	v_mfma_f32_16x16x32_bf16 v[100:103], v[200:203], v[176:179], v[100:103]
	v_mfma_f32_16x16x32_bf16 v[96:99], v[208:211], v[176:179], v[96:99]
	v_mfma_f32_16x16x32_bf16 v[84:87], v[200:203], v[184:187], v[84:87]
	v_mfma_f32_16x16x32_bf16 v[80:83], v[208:211], v[184:187], v[80:83]
	v_mfma_f32_16x16x32_bf16 v[68:71], v[200:203], v[192:195], v[68:71]
	v_mfma_f32_16x16x32_bf16 v[64:67], v[208:211], v[192:195], v[64:67]
	v_mfma_f32_16x16x32_bf16 v[116:119], v[204:207], v[172:175], v[116:119]
	v_mfma_f32_16x16x32_bf16 v[112:115], v[212:215], v[172:175], v[112:115]
	v_mfma_f32_16x16x32_bf16 v[100:103], v[204:207], v[180:183], v[100:103]
	v_mfma_f32_16x16x32_bf16 v[96:99], v[212:215], v[180:183], v[96:99]
	v_mfma_f32_16x16x32_bf16 v[84:87], v[204:207], v[188:191], v[84:87]
	v_mfma_f32_16x16x32_bf16 v[80:83], v[212:215], v[188:191], v[80:83]
	v_mfma_f32_16x16x32_bf16 v[68:71], v[204:207], v[196:199], v[68:71]
	v_mfma_f32_16x16x32_bf16 v[64:67], v[212:215], v[196:199], v[64:67]
	s_barrier
	global_load_lds_dwordx4 v128, s[26:27]
	s_add_i32 m0, s62, 0x2000
	s_nop 0
	global_load_lds_dwordx4 v130, s[26:27]
	s_mov_b32 m0, s50
	v_lshl_add_u64 v[144:145], v[144:145], 0, s[10:11]
	ds_read_b128 v[168:171], v150 offset:49152
	ds_read_b128 v[172:175], v150 offset:50176
	ds_read_b128 v[176:179], v150 offset:51200
	ds_read_b128 v[180:183], v150 offset:52224
	ds_read_b128 v[184:187], v150 offset:53248
	ds_read_b128 v[188:191], v150 offset:54272
	ds_read_b128 v[192:195], v150 offset:55296
	ds_read_b128 v[196:199], v150 offset:56320
	global_load_lds_dwordx4 v[144:145], off
	v_lshl_add_u64 v[144:145], v[216:217], 0, s[10:11]
	s_mov_b32 m0, s51
	s_nop 0
	global_load_lds_dwordx4 v[144:145], off
	s_add_u32 s24, s24, 0xc000
	s_addc_u32 s25, s25, 0
	s_add_i32 s26, s63, s38
	s_mov_b32 m0, s26
	s_nop 0
	global_load_lds_dwordx4 v128, s[24:25]
	s_add_i32 m0, s26, 0x2000
	s_nop 0
	global_load_lds_dwordx4 v130, s[24:25]
	s_add_i32 s61, s61, 2
	s_add_u32 s59, s59, 0x10000
	s_addc_u32 s60, s60, 0
	s_add_u32 s22, s22, 0x100
	s_addc_u32 s23, s23, 0
	s_cmp_gt_u32 s61, 29
	s_waitcnt vmcnt(8)
	s_waitcnt lgkmcnt(0)
	s_barrier
	v_mfma_f32_16x16x32_bf16 v[60:63], v[152:155], v[168:171], v[60:63]
	v_mfma_f32_16x16x32_bf16 v[56:59], v[160:163], v[168:171], v[56:59]
	v_mfma_f32_16x16x32_bf16 v[44:47], v[152:155], v[176:179], v[44:47]
	v_mfma_f32_16x16x32_bf16 v[40:43], v[160:163], v[176:179], v[40:43]
	v_mfma_f32_16x16x32_bf16 v[28:31], v[152:155], v[184:187], v[28:31]
	v_mfma_f32_16x16x32_bf16 v[24:27], v[160:163], v[184:187], v[24:27]
	v_mfma_f32_16x16x32_bf16 v[12:15], v[152:155], v[192:195], v[12:15]
	v_mfma_f32_16x16x32_bf16 v[8:11], v[160:163], v[192:195], v[8:11]
	v_mfma_f32_16x16x32_bf16 v[60:63], v[156:159], v[172:175], v[60:63]
	v_mfma_f32_16x16x32_bf16 v[56:59], v[164:167], v[172:175], v[56:59]
	v_mfma_f32_16x16x32_bf16 v[44:47], v[156:159], v[180:183], v[44:47]
	v_mfma_f32_16x16x32_bf16 v[40:43], v[164:167], v[180:183], v[40:43]
	v_mfma_f32_16x16x32_bf16 v[28:31], v[156:159], v[188:191], v[28:31]
	v_mfma_f32_16x16x32_bf16 v[24:27], v[164:167], v[188:191], v[24:27]
	v_mfma_f32_16x16x32_bf16 v[12:15], v[156:159], v[196:199], v[12:15]
	v_mfma_f32_16x16x32_bf16 v[8:11], v[164:167], v[196:199], v[8:11]
	v_mfma_f32_16x16x32_bf16 v[52:55], v[200:203], v[168:171], v[52:55]
	v_mfma_f32_16x16x32_bf16 v[48:51], v[208:211], v[168:171], v[48:51]
	v_mfma_f32_16x16x32_bf16 v[36:39], v[200:203], v[176:179], v[36:39]
	v_mfma_f32_16x16x32_bf16 v[32:35], v[208:211], v[176:179], v[32:35]
	v_mfma_f32_16x16x32_bf16 v[20:23], v[200:203], v[184:187], v[20:23]
	v_mfma_f32_16x16x32_bf16 v[16:19], v[208:211], v[184:187], v[16:19]
	v_mfma_f32_16x16x32_bf16 v[4:7], v[200:203], v[192:195], v[4:7]
	v_mfma_f32_16x16x32_bf16 v[0:3], v[208:211], v[192:195], v[0:3]
	v_mfma_f32_16x16x32_bf16 v[52:55], v[204:207], v[172:175], v[52:55]
	v_mfma_f32_16x16x32_bf16 v[48:51], v[212:215], v[172:175], v[48:51]
	v_mfma_f32_16x16x32_bf16 v[36:39], v[204:207], v[180:183], v[36:39]
	v_mfma_f32_16x16x32_bf16 v[32:35], v[212:215], v[180:183], v[32:35]
	s_cbranch_scc1 .Lunit_exit_0
	v_mfma_f32_16x16x32_bf16 v[20:23], v[204:207], v[188:191], v[20:23]
	v_mfma_f32_16x16x32_bf16 v[16:19], v[212:215], v[188:191], v[16:19]
	v_mfma_f32_16x16x32_bf16 v[4:7], v[204:207], v[196:199], v[4:7]
	v_mfma_f32_16x16x32_bf16 v[0:3], v[212:215], v[196:199], v[0:3]
	s_barrier
	s_branch .LBB0_79
; #define PG8_MMA(ai, bj, At, Bt) do { __builtin_amdgcn_s_setprio(1); _Pragma("unroll") for (int m = 0; m < 4; ++m) _Pragma("unroll") for (int n = 0; n < 2; ++n) _Pragma("unroll") for (int k = 0; k < 2; ++k) \
;         acc[ai][bj][m][n] = __builtin_amdgcn_mfma_f32_16x16x32_bf16(Bt[n][k], At[m][k], acc[ai][bj][m][n], 0, 0, 0); __builtin_amdgcn_s_setprio(0); } while (0)
; #define PG8_WAIT_V(n) asm volatile("s_waitcnt vmcnt(" #n ")" ::: "memory")
; #define PG8_BAR __builtin_amdgcn_s_barrier()
; template <class Epi, class Sched>
; __device__ __forceinline__ void gemm_phase(PG8_LAS unsigned char* lds, const Gemm g, const Sched& S, const Epi& E) {
;     ...
;             PG8_WAIT_V(6); PG8_BAR; PG8_MMA(1, 1, At, B1); PG8_BAR;
;         }
;         if constexpr (!Epi::AFTER_DRAIN) { E(acc, cur, wr, wc, fr, fq); if constexpr (Epi::IDEMP && EPI_REP > 1) { asm volatile("" ::: "memory"); E(acc, cur, wr, wc, fr, fq); } S.done(cur); }
;         if (!has_next) break;
.Lunit_exit_0:
	v_mfma_f32_16x16x32_bf16 v[20:23], v[204:207], v[188:191], v[20:23]
	v_mfma_f32_16x16x32_bf16 v[16:19], v[212:215], v[188:191], v[16:19]
	v_mfma_f32_16x16x32_bf16 v[4:7], v[204:207], v[196:199], v[4:7]
	v_mfma_f32_16x16x32_bf16 v[0:3], v[212:215], v[196:199], v[0:3]
	s_cmp_eq_u32 s78, 1
	s_cbranch_scc1 .Lunit_skipb_0
	s_barrier

; #define PG8_STAGE(bufoff, gbase, voff) do { _Pragma("unroll") for (int _i = 0; _i < 2; ++_i) \
;         __builtin_amdgcn_global_load_lds((const unsigned*)((const char*)(gbase) + (voff)[_i]), (PG8_LAS unsigned*)(lds + (bufoff) + ldsw + _i * 8192), 16, 0, 0); } while (0)
; #define PG8_LDA(dst, b, h) do { _Pragma("unroll") for (int m = 0; m < 4; ++m) _Pragma("unroll") for (int k = 0; k < 2; ++k) dst[m][k] = *(const PG8_LAS bf16x8*)(lds + PG8_SA(b, h) + aoff + m * 2048 + k * 1024); } while (0)
; #define PG8_LDB(dst, b, h) do { _Pragma("unroll") for (int n = 0; n < 2; ++n) _Pragma("unroll") for (int k = 0; k < 2; ++k) dst[n][k] = *(const PG8_LAS bf16x8*)(lds + PG8_SB(b, h) + boff + n * 2048 + k * 1024); } while (0)
; #define PG8_MMA(ai, bj, At, Bt) do { __builtin_amdgcn_s_setprio(1); _Pragma("unroll") for (int m = 0; m < 4; ++m) _Pragma("unroll") for (int n = 0; n < 2; ++n) _Pragma("unroll") for (int k = 0; k < 2; ++k) \
;         acc[ai][bj][m][n] = __builtin_amdgcn_mfma_f32_16x16x32_bf16(Bt[n][k], At[m][k], acc[ai][bj][m][n], 0, 0, 0); __builtin_amdgcn_s_setprio(0); } while (0)
; #define PG8_WAIT_V(n) asm volatile("s_waitcnt vmcnt(" #n ")" ::: "memory")
; template <class Epi, class Sched>
; __device__ __forceinline__ void gemm_phase(PG8_LAS unsigned char* lds, const Gemm g, const Sched& S, const Epi& E) {
;     ...
;         for (int t = 0; t < nt; t += 2) {
;             const bool last = (t == nt - 2);
;             const char* a1 = cA + (size_t)(t + 1) * kstep;
;             const char* a2 = last ? nA : cA + (size_t)(t + 2) * kstep; const char* b2 = last ? nB : cB + (size_t)(t + 2) * kstepB;
;             const char* a3 = a2 + kstep; const char* b3 = b2 + kstepB;
;             if (last && has_next) S.a_ready(nxt);
;             PG8_LDB(B0, 0, 0); PG8_SCHED; PG8_LDA(At, 0, 0); PG8_STAGE(PG8_SA(1, 1), a1 + hstep, voffA);
;             PG8_WAIT_L(8); PG8_BAR; PG8_WAIT_L(0); PG8_MMA(0, 0, At, B0); PG8_BAR; PG8_SCHED;
;             PG8_LDB(B1, 0, 1); PG8_STAGE(PG8_SB(0, 0), b2, voffB);
;             PG8_BAR; PG8_WAIT_L(0); PG8_MMA(0, 1, At, B1); PG8_BAR;
;             PG8_LDA(At, 0, 1); PG8_STAGE(PG8_SA(0, 0), a2, voffA);
;             PG8_BAR; PG8_WAIT_L(0); PG8_MMA(1, 0, At, B0); PG8_BAR; PG8_SCHED;
;             PG8_STAGE(PG8_SB(0, 1), b2 + hstepB, voffB);
;             PG8_WAIT_V(6); PG8_BAR; PG8_MMA(1, 1, At, B1); PG8_BAR;
.Lhalf_skip_y_1:
.LBB0_155:
	ds_read_b128 v[144:147], v153
	ds_read_b128 v[156:159], v153 offset:1024
	ds_read_b128 v[160:163], v153 offset:2048
	ds_read_b128 v[164:167], v153 offset:3072
	s_add_u32 s26, s24, 0x100
	s_addc_u32 s27, s25, 0
	s_cmpk_eq_i32 s67, 0x52
	s_cselect_b32 s31, s7, s27
	s_cselect_b32 s30, s6, s26
	s_cselect_b32 s29, s9, s66
	s_cselect_b32 s28, s8, s65
	v_lshl_add_u64 v[148:149], s[24:25], 0, v[136:137]
	s_add_i32 m0, s51, 0xc000
	ds_read_b128 v[168:171], v154
	ds_read_b128 v[172:175], v154 offset:1024
	ds_read_b128 v[176:179], v154 offset:2048
	ds_read_b128 v[180:183], v154 offset:3072
	ds_read_b128 v[184:187], v154 offset:4096
	ds_read_b128 v[188:191], v154 offset:5120
	ds_read_b128 v[192:195], v154 offset:6144
	ds_read_b128 v[196:199], v154 offset:7168
	global_load_lds_dwordx4 v[148:149], off
	v_lshl_add_u64 v[148:149], s[24:25], 0, v[138:139]
	s_add_i32 m0, s51, 0xe000
	s_nop 0
	global_load_lds_dwordx4 v[148:149], off
	s_add_i32 s24, s59, s50
	s_mov_b32 m0, s24
	ds_read_b128 v[200:203], v155
	ds_read_b128 v[204:207], v155 offset:1024
	ds_read_b128 v[208:211], v155 offset:2048
	ds_read_b128 v[212:215], v155 offset:3072
	s_waitcnt vmcnt(8)
	s_waitcnt lgkmcnt(0)
	s_barrier
	v_mfma_f32_16x16x32_bf16 v[124:127], v[144:147], v[168:171], v[124:127]
	v_mfma_f32_16x16x32_bf16 v[120:123], v[160:163], v[168:171], v[120:123]
	v_mfma_f32_16x16x32_bf16 v[108:111], v[144:147], v[176:179], v[108:111]
	v_mfma_f32_16x16x32_bf16 v[104:107], v[160:163], v[176:179], v[104:107]
	v_mfma_f32_16x16x32_bf16 v[92:95], v[144:147], v[184:187], v[92:95]
	v_mfma_f32_16x16x32_bf16 v[88:91], v[160:163], v[184:187], v[88:91]
	v_mfma_f32_16x16x32_bf16 v[76:79], v[144:147], v[192:195], v[76:79]
	v_mfma_f32_16x16x32_bf16 v[72:75], v[160:163], v[192:195], v[72:75]
	v_mfma_f32_16x16x32_bf16 v[124:127], v[156:159], v[172:175], v[124:127]
	v_mfma_f32_16x16x32_bf16 v[120:123], v[164:167], v[172:175], v[120:123]
	v_mfma_f32_16x16x32_bf16 v[108:111], v[156:159], v[180:183], v[108:111]
	v_mfma_f32_16x16x32_bf16 v[104:107], v[164:167], v[180:183], v[104:107]
	v_mfma_f32_16x16x32_bf16 v[92:95], v[156:159], v[188:191], v[92:95]
	v_mfma_f32_16x16x32_bf16 v[88:91], v[164:167], v[188:191], v[88:91]
	v_mfma_f32_16x16x32_bf16 v[76:79], v[156:159], v[196:199], v[76:79]
	v_mfma_f32_16x16x32_bf16 v[72:75], v[164:167], v[196:199], v[72:75]
	v_mfma_f32_16x16x32_bf16 v[116:119], v[200:203], v[168:171], v[116:119]
	v_mfma_f32_16x16x32_bf16 v[112:115], v[208:211], v[168:171], v[112:115]
	v_mfma_f32_16x16x32_bf16 v[100:103], v[200:203], v[176:179], v[100:103]
	v_mfma_f32_16x16x32_bf16 v[96:99], v[208:211], v[176:179], v[96:99]
	v_mfma_f32_16x16x32_bf16 v[84:87], v[200:203], v[184:187], v[84:87]
	v_mfma_f32_16x16x32_bf16 v[80:83], v[208:211], v[184:187], v[80:83]
	v_mfma_f32_16x16x32_bf16 v[68:71], v[200:203], v[192:195], v[68:71]
	v_mfma_f32_16x16x32_bf16 v[64:67], v[208:211], v[192:195], v[64:67]
	v_mfma_f32_16x16x32_bf16 v[116:119], v[204:207], v[172:175], v[116:119]
	v_mfma_f32_16x16x32_bf16 v[112:115], v[212:215], v[172:175], v[112:115]
	v_mfma_f32_16x16x32_bf16 v[100:103], v[204:207], v[180:183], v[100:103]
	v_mfma_f32_16x16x32_bf16 v[96:99], v[212:215], v[180:183], v[96:99]
	v_mfma_f32_16x16x32_bf16 v[84:87], v[204:207], v[188:191], v[84:87]
	v_mfma_f32_16x16x32_bf16 v[80:83], v[212:215], v[188:191], v[80:83]
	v_mfma_f32_16x16x32_bf16 v[68:71], v[204:207], v[196:199], v[68:71]
	v_mfma_f32_16x16x32_bf16 v[64:67], v[212:215], v[196:199], v[64:67]
	s_barrier
	global_load_lds_dwordx4 v128, s[28:29]
	s_add_i32 m0, s24, 0x2000
	s_nop 0
	global_load_lds_dwordx4 v132, s[28:29]
	s_mov_b32 m0, s51
	v_lshl_add_u64 v[148:149], s[30:31], 0, v[130:131]
	ds_read_b128 v[168:171], v154 offset:16384
	ds_read_b128 v[172:175], v154 offset:17408
	ds_read_b128 v[176:179], v154 offset:18432
	ds_read_b128 v[180:183], v154 offset:19456
	ds_read_b128 v[184:187], v154 offset:20480
	ds_read_b128 v[188:191], v154 offset:21504
	ds_read_b128 v[192:195], v154 offset:22528
	ds_read_b128 v[196:199], v154 offset:23552
	global_load_lds_dwordx4 v[148:149], off
	v_lshl_add_u64 v[216:217], s[30:31], 0, v[134:135]
	s_mov_b32 m0, s52
	s_nop 0
	global_load_lds_dwordx4 v[216:217], off
	s_add_u32 s24, s28, 0x4000
	s_addc_u32 s25, s29, 0
	s_add_i32 s68, s60, s50
	s_mov_b32 m0, s68
	s_nop 0
	global_load_lds_dwordx4 v128, s[24:25]
	s_add_i32 m0, s68, 0x2000
	s_nop 0
	global_load_lds_dwordx4 v132, s[24:25]
	s_waitcnt vmcnt(8)
	s_waitcnt lgkmcnt(0)
	s_barrier
	v_mfma_f32_16x16x32_bf16 v[60:63], v[144:147], v[168:171], v[60:63]
	v_mfma_f32_16x16x32_bf16 v[56:59], v[160:163], v[168:171], v[56:59]
	v_mfma_f32_16x16x32_bf16 v[44:47], v[144:147], v[176:179], v[44:47]
	v_mfma_f32_16x16x32_bf16 v[40:43], v[160:163], v[176:179], v[40:43]
	v_mfma_f32_16x16x32_bf16 v[28:31], v[144:147], v[184:187], v[28:31]
	v_mfma_f32_16x16x32_bf16 v[24:27], v[160:163], v[184:187], v[24:27]
	v_mfma_f32_16x16x32_bf16 v[12:15], v[144:147], v[192:195], v[12:15]
	v_mfma_f32_16x16x32_bf16 v[8:11], v[160:163], v[192:195], v[8:11]
	v_mfma_f32_16x16x32_bf16 v[60:63], v[156:159], v[172:175], v[60:63]
	v_mfma_f32_16x16x32_bf16 v[56:59], v[164:167], v[172:175], v[56:59]
	v_mfma_f32_16x16x32_bf16 v[44:47], v[156:159], v[180:183], v[44:47]
	v_mfma_f32_16x16x32_bf16 v[40:43], v[164:167], v[180:183], v[40:43]
	v_mfma_f32_16x16x32_bf16 v[28:31], v[156:159], v[188:191], v[28:31]
	v_mfma_f32_16x16x32_bf16 v[24:27], v[164:167], v[188:191], v[24:27]
	v_mfma_f32_16x16x32_bf16 v[12:15], v[156:159], v[196:199], v[12:15]
	v_mfma_f32_16x16x32_bf16 v[8:11], v[164:167], v[196:199], v[8:11]
	v_mfma_f32_16x16x32_bf16 v[52:55], v[200:203], v[168:171], v[52:55]
	v_mfma_f32_16x16x32_bf16 v[48:51], v[208:211], v[168:171], v[48:51]
	v_mfma_f32_16x16x32_bf16 v[36:39], v[200:203], v[176:179], v[36:39]
	v_mfma_f32_16x16x32_bf16 v[32:35], v[208:211], v[176:179], v[32:35]
	v_mfma_f32_16x16x32_bf16 v[20:23], v[200:203], v[184:187], v[20:23]
	v_mfma_f32_16x16x32_bf16 v[16:19], v[208:211], v[184:187], v[16:19]
	v_mfma_f32_16x16x32_bf16 v[4:7], v[200:203], v[192:195], v[4:7]
	v_mfma_f32_16x16x32_bf16 v[0:3], v[208:211], v[192:195], v[0:3]
	v_mfma_f32_16x16x32_bf16 v[52:55], v[204:207], v[172:175], v[52:55]
	v_mfma_f32_16x16x32_bf16 v[48:51], v[212:215], v[172:175], v[48:51]
	v_mfma_f32_16x16x32_bf16 v[36:39], v[204:207], v[180:183], v[36:39]
	v_mfma_f32_16x16x32_bf16 v[32:35], v[212:215], v[180:183], v[32:35]
	v_mfma_f32_16x16x32_bf16 v[20:23], v[204:207], v[188:191], v[20:23]
	v_mfma_f32_16x16x32_bf16 v[16:19], v[212:215], v[188:191], v[16:19]
	v_mfma_f32_16x16x32_bf16 v[4:7], v[204:207], v[196:199], v[4:7]
	v_mfma_f32_16x16x32_bf16 v[0:3], v[212:215], v[196:199], v[0:3]
	s_barrier
; #define PG8_STAGE(bufoff, gbase, voff) do { _Pragma("unroll") for (int _i = 0; _i < 2; ++_i) \
;         __builtin_amdgcn_global_load_lds((const unsigned*)((const char*)(gbase) + (voff)[_i]), (PG8_LAS unsigned*)(lds + (bufoff) + ldsw + _i * 8192), 16, 0, 0); } while (0)
; #define PG8_LDA(dst, b, h) do { _Pragma("unroll") for (int m = 0; m < 4; ++m) _Pragma("unroll") for (int k = 0; k < 2; ++k) dst[m][k] = *(const PG8_LAS bf16x8*)(lds + PG8_SA(b, h) + aoff + m * 2048 + k * 1024); } while (0)
; #define PG8_LDB(dst, b, h) do { _Pragma("unroll") for (int n = 0; n < 2; ++n) _Pragma("unroll") for (int k = 0; k < 2; ++k) dst[n][k] = *(const PG8_LAS bf16x8*)(lds + PG8_SB(b, h) + boff + n * 2048 + k * 1024); } while (0)
; #define PG8_MMA(ai, bj, At, Bt) do { __builtin_amdgcn_s_setprio(1); _Pragma("unroll") for (int m = 0; m < 4; ++m) _Pragma("unroll") for (int n = 0; n < 2; ++n) _Pragma("unroll") for (int k = 0; k < 2; ++k) \
;         acc[ai][bj][m][n] = __builtin_amdgcn_mfma_f32_16x16x32_bf16(Bt[n][k], At[m][k], acc[ai][bj][m][n], 0, 0, 0); __builtin_amdgcn_s_setprio(0); } while (0)
; #define PG8_WAIT_V(n) asm volatile("s_waitcnt vmcnt(" #n ")" ::: "memory")
; #define PG8_WAIT_L(n) asm volatile("s_waitcnt lgkmcnt(" #n ")" ::: "memory")
; #define PG8_BAR __builtin_amdgcn_s_barrier()
; #define PG8_SCHED __builtin_amdgcn_sched_barrier(0)
; template <class Epi, class Sched>
; __device__ __forceinline__ void gemm_phase(PG8_LAS unsigned char* lds, const Gemm g, const Sched& S, const Epi& E) {
;     ...
;             PG8_LDB(B0, 1, 0); PG8_SCHED; PG8_LDA(At, 1, 0); PG8_STAGE(PG8_SA(0, 1), a2 + hstep, voffA);
;             PG8_WAIT_L(8); PG8_BAR; PG8_WAIT_L(0); PG8_MMA(0, 0, At, B0); PG8_BAR; PG8_SCHED;
;             PG8_LDB(B1, 1, 1); PG8_STAGE(PG8_SB(1, 0), b3, voffB);
;             PG8_BAR; PG8_WAIT_L(0); PG8_MMA(0, 1, At, B1); PG8_BAR;
;             PG8_LDA(At, 1, 1); PG8_STAGE(PG8_SA(1, 0), a3, voffA);
;             PG8_BAR; PG8_WAIT_L(0); PG8_MMA(1, 0, At, B0); PG8_BAR; PG8_SCHED;
;             PG8_STAGE(PG8_SB(1, 1), b3 + hstepB, voffB);
;             PG8_WAIT_V(6); PG8_BAR; PG8_MMA(1, 1, At, B1); PG8_BAR;
	s_add_i32 s68, 0, 0x18000
	v_add_u32_e32 v164, s68, v151
	ds_read_b128 v[144:147], v164
	ds_read_b128 v[156:159], v164 offset:1024
	ds_read_b128 v[160:163], v164 offset:2048
	ds_read_b128 v[164:167], v164 offset:3072
	s_add_u32 s24, s30, 0x158000
	s_addc_u32 s25, s31, 0
	s_mov_b32 m0, s53
	ds_read_b128 v[168:171], v154 offset:32768
	ds_read_b128 v[172:175], v154 offset:33792
	ds_read_b128 v[176:179], v154 offset:34816
	ds_read_b128 v[180:183], v154 offset:35840
	ds_read_b128 v[184:187], v154 offset:36864
	ds_read_b128 v[188:191], v154 offset:37888
	ds_read_b128 v[192:195], v154 offset:38912
	ds_read_b128 v[196:199], v154 offset:39936
	global_load_lds_dwordx4 v130, s[24:25]
	s_mov_b32 m0, s54
	s_nop 0
	global_load_lds_dwordx4 v134, s[24:25]
	s_add_i32 s30, 0, 0x1c000
	s_add_u32 s24, s28, 0x8000
	s_addc_u32 s25, s29, 0
	s_add_i32 s31, s68, s50
	v_add_u32_e32 v212, s30, v151
	s_mov_b32 m0, s31
	ds_read_b128 v[200:203], v212
	ds_read_b128 v[204:207], v212 offset:1024
	ds_read_b128 v[208:211], v212 offset:2048
	ds_read_b128 v[212:215], v212 offset:3072
	s_waitcnt vmcnt(8)
	s_waitcnt lgkmcnt(0)
	s_barrier
	v_mfma_f32_16x16x32_bf16 v[124:127], v[144:147], v[168:171], v[124:127]
	v_mfma_f32_16x16x32_bf16 v[120:123], v[160:163], v[168:171], v[120:123]
	v_mfma_f32_16x16x32_bf16 v[108:111], v[144:147], v[176:179], v[108:111]
	v_mfma_f32_16x16x32_bf16 v[104:107], v[160:163], v[176:179], v[104:107]
	v_mfma_f32_16x16x32_bf16 v[92:95], v[144:147], v[184:187], v[92:95]
	v_mfma_f32_16x16x32_bf16 v[88:91], v[160:163], v[184:187], v[88:91]
	v_mfma_f32_16x16x32_bf16 v[76:79], v[144:147], v[192:195], v[76:79]
	v_mfma_f32_16x16x32_bf16 v[72:75], v[160:163], v[192:195], v[72:75]
	v_mfma_f32_16x16x32_bf16 v[124:127], v[156:159], v[172:175], v[124:127]
	v_mfma_f32_16x16x32_bf16 v[120:123], v[164:167], v[172:175], v[120:123]
	v_mfma_f32_16x16x32_bf16 v[108:111], v[156:159], v[180:183], v[108:111]
	v_mfma_f32_16x16x32_bf16 v[104:107], v[164:167], v[180:183], v[104:107]
	v_mfma_f32_16x16x32_bf16 v[92:95], v[156:159], v[188:191], v[92:95]
	v_mfma_f32_16x16x32_bf16 v[88:91], v[164:167], v[188:191], v[88:91]
	v_mfma_f32_16x16x32_bf16 v[76:79], v[156:159], v[196:199], v[76:79]
	v_mfma_f32_16x16x32_bf16 v[72:75], v[164:167], v[196:199], v[72:75]
	v_mfma_f32_16x16x32_bf16 v[116:119], v[200:203], v[168:171], v[116:119]
	v_mfma_f32_16x16x32_bf16 v[112:115], v[208:211], v[168:171], v[112:115]
	v_mfma_f32_16x16x32_bf16 v[100:103], v[200:203], v[176:179], v[100:103]
	v_mfma_f32_16x16x32_bf16 v[96:99], v[208:211], v[176:179], v[96:99]
	v_mfma_f32_16x16x32_bf16 v[84:87], v[200:203], v[184:187], v[84:87]
	v_mfma_f32_16x16x32_bf16 v[80:83], v[208:211], v[184:187], v[80:83]
	v_mfma_f32_16x16x32_bf16 v[68:71], v[200:203], v[192:195], v[68:71]
	v_mfma_f32_16x16x32_bf16 v[64:67], v[208:211], v[192:195], v[64:67]
	v_mfma_f32_16x16x32_bf16 v[116:119], v[204:207], v[172:175], v[116:119]
	v_mfma_f32_16x16x32_bf16 v[112:115], v[212:215], v[172:175], v[112:115]
	v_mfma_f32_16x16x32_bf16 v[100:103], v[204:207], v[180:183], v[100:103]
	v_mfma_f32_16x16x32_bf16 v[96:99], v[212:215], v[180:183], v[96:99]
	v_mfma_f32_16x16x32_bf16 v[84:87], v[204:207], v[188:191], v[84:87]
	v_mfma_f32_16x16x32_bf16 v[80:83], v[212:215], v[188:191], v[80:83]
	v_mfma_f32_16x16x32_bf16 v[68:71], v[204:207], v[196:199], v[68:71]
	v_mfma_f32_16x16x32_bf16 v[64:67], v[212:215], v[196:199], v[64:67]
	s_barrier
	global_load_lds_dwordx4 v128, s[24:25]
	s_add_i32 m0, s31, 0x2000
	s_nop 0
	global_load_lds_dwordx4 v132, s[24:25]
	s_mov_b32 m0, s56
	v_lshl_add_u64 v[148:149], v[148:149], 0, s[14:15]
	ds_read_b128 v[168:171], v154 offset:49152
	ds_read_b128 v[172:175], v154 offset:50176
	ds_read_b128 v[176:179], v154 offset:51200
	ds_read_b128 v[180:183], v154 offset:52224
	ds_read_b128 v[184:187], v154 offset:53248
	ds_read_b128 v[188:191], v154 offset:54272
	ds_read_b128 v[192:195], v154 offset:55296
	ds_read_b128 v[196:199], v154 offset:56320
	global_load_lds_dwordx4 v[148:149], off
	v_lshl_add_u64 v[148:149], v[216:217], 0, s[14:15]
	s_mov_b32 m0, s57
	s_nop 0
	global_load_lds_dwordx4 v[148:149], off
	s_add_u32 s24, s28, 0xc000
	s_addc_u32 s25, s29, 0
	s_add_i32 s28, s30, s50
	s_mov_b32 m0, s28
	s_nop 0
	global_load_lds_dwordx4 v128, s[24:25]
	s_add_i32 m0, s28, 0x2000
	s_nop 0
	global_load_lds_dwordx4 v132, s[24:25]
	s_add_i32 s67, s67, 2
	s_add_u32 s65, s65, 0x10000
	s_addc_u32 s66, s66, 0
	s_cmpk_gt_u32 s67, 0x53
	s_mov_b64 s[24:25], s[26:27]
	s_waitcnt vmcnt(8)
	s_waitcnt lgkmcnt(0)
	s_barrier
	v_mfma_f32_16x16x32_bf16 v[60:63], v[144:147], v[168:171], v[60:63]
	v_mfma_f32_16x16x32_bf16 v[56:59], v[160:163], v[168:171], v[56:59]
	v_mfma_f32_16x16x32_bf16 v[44:47], v[144:147], v[176:179], v[44:47]
	v_mfma_f32_16x16x32_bf16 v[40:43], v[160:163], v[176:179], v[40:43]
	v_mfma_f32_16x16x32_bf16 v[28:31], v[144:147], v[184:187], v[28:31]
	v_mfma_f32_16x16x32_bf16 v[24:27], v[160:163], v[184:187], v[24:27]
	v_mfma_f32_16x16x32_bf16 v[12:15], v[144:147], v[192:195], v[12:15]
	v_mfma_f32_16x16x32_bf16 v[8:11], v[160:163], v[192:195], v[8:11]
	v_mfma_f32_16x16x32_bf16 v[60:63], v[156:159], v[172:175], v[60:63]
	v_mfma_f32_16x16x32_bf16 v[56:59], v[164:167], v[172:175], v[56:59]
	v_mfma_f32_16x16x32_bf16 v[44:47], v[156:159], v[180:183], v[44:47]
	v_mfma_f32_16x16x32_bf16 v[40:43], v[164:167], v[180:183], v[40:43]
	v_mfma_f32_16x16x32_bf16 v[28:31], v[156:159], v[188:191], v[28:31]
	v_mfma_f32_16x16x32_bf16 v[24:27], v[164:167], v[188:191], v[24:27]
	v_mfma_f32_16x16x32_bf16 v[12:15], v[156:159], v[196:199], v[12:15]
	v_mfma_f32_16x16x32_bf16 v[8:11], v[164:167], v[196:199], v[8:11]
	v_mfma_f32_16x16x32_bf16 v[52:55], v[200:203], v[168:171], v[52:55]
	v_mfma_f32_16x16x32_bf16 v[48:51], v[208:211], v[168:171], v[48:51]
	v_mfma_f32_16x16x32_bf16 v[36:39], v[200:203], v[176:179], v[36:39]
	v_mfma_f32_16x16x32_bf16 v[32:35], v[208:211], v[176:179], v[32:35]
	v_mfma_f32_16x16x32_bf16 v[20:23], v[200:203], v[184:187], v[20:23]
	v_mfma_f32_16x16x32_bf16 v[16:19], v[208:211], v[184:187], v[16:19]
	v_mfma_f32_16x16x32_bf16 v[4:7], v[200:203], v[192:195], v[4:7]
	v_mfma_f32_16x16x32_bf16 v[0:3], v[208:211], v[192:195], v[0:3]
	v_mfma_f32_16x16x32_bf16 v[52:55], v[204:207], v[172:175], v[52:55]
	v_mfma_f32_16x16x32_bf16 v[48:51], v[212:215], v[172:175], v[48:51]
	v_mfma_f32_16x16x32_bf16 v[36:39], v[204:207], v[180:183], v[36:39]
	v_mfma_f32_16x16x32_bf16 v[32:35], v[212:215], v[180:183], v[32:35]
	s_cbranch_scc1 .Lunit_exit_1
	v_mfma_f32_16x16x32_bf16 v[20:23], v[204:207], v[188:191], v[20:23]
	v_mfma_f32_16x16x32_bf16 v[16:19], v[212:215], v[188:191], v[16:19]
	v_mfma_f32_16x16x32_bf16 v[4:7], v[204:207], v[196:199], v[4:7]
	v_mfma_f32_16x16x32_bf16 v[0:3], v[212:215], v[196:199], v[0:3]
	s_barrier
	s_branch .LBB0_155

; #define PG8_STAGE(bufoff, gbase, voff) do { _Pragma("unroll") for (int _i = 0; _i < 2; ++_i) \
;         __builtin_amdgcn_global_load_lds((const unsigned*)((const char*)(gbase) + (voff)[_i]), (PG8_LAS unsigned*)(lds + (bufoff) + ldsw + _i * 8192), 16, 0, 0); } while (0)
; #define PG8_LDA(dst, b, h) do { _Pragma("unroll") for (int m = 0; m < 4; ++m) _Pragma("unroll") for (int k = 0; k < 2; ++k) dst[m][k] = *(const PG8_LAS bf16x8*)(lds + PG8_SA(b, h) + aoff + m * 2048 + k * 1024); } while (0)
; #define PG8_LDB(dst, b, h) do { _Pragma("unroll") for (int n = 0; n < 2; ++n) _Pragma("unroll") for (int k = 0; k < 2; ++k) dst[n][k] = *(const PG8_LAS bf16x8*)(lds + PG8_SB(b, h) + boff + n * 2048 + k * 1024); } while (0)
; #define PG8_MMA(ai, bj, At, Bt) do { __builtin_amdgcn_s_setprio(1); _Pragma("unroll") for (int m = 0; m < 4; ++m) _Pragma("unroll") for (int n = 0; n < 2; ++n) _Pragma("unroll") for (int k = 0; k < 2; ++k) \
;         acc[ai][bj][m][n] = __builtin_amdgcn_mfma_f32_16x16x32_bf16(Bt[n][k], At[m][k], acc[ai][bj][m][n], 0, 0, 0); __builtin_amdgcn_s_setprio(0); } while (0)
; #define PG8_WAIT_V(n) asm volatile("s_waitcnt vmcnt(" #n ")" ::: "memory")
; template <class Epi, class Sched>
; __device__ __forceinline__ void gemm_phase(PG8_LAS unsigned char* lds, const Gemm g, const Sched& S, const Epi& E) {
;     ...
;         for (int t = 0; t < nt; t += 2) {
;             const bool last = (t == nt - 2);
;             const char* a1 = cA + (size_t)(t + 1) * kstep;
;             const char* a2 = last ? nA : cA + (size_t)(t + 2) * kstep; const char* b2 = last ? nB : cB + (size_t)(t + 2) * kstepB;
;             const char* a3 = a2 + kstep; const char* b3 = b2 + kstepB;
;             if (last && has_next) S.a_ready(nxt);
;             PG8_LDB(B0, 0, 0); PG8_SCHED; PG8_LDA(At, 0, 0); PG8_STAGE(PG8_SA(1, 1), a1 + hstep, voffA);
;             PG8_WAIT_L(8); PG8_BAR; PG8_WAIT_L(0); PG8_MMA(0, 0, At, B0); PG8_BAR; PG8_SCHED;
;             PG8_LDB(B1, 0, 1); PG8_STAGE(PG8_SB(0, 0), b2, voffB);
;             PG8_BAR; PG8_WAIT_L(0); PG8_MMA(0, 1, At, B1); PG8_BAR;
;             PG8_LDA(At, 0, 1); PG8_STAGE(PG8_SA(0, 0), a2, voffA);
;             PG8_BAR; PG8_WAIT_L(0); PG8_MMA(1, 0, At, B0); PG8_BAR; PG8_SCHED;
;             PG8_STAGE(PG8_SB(0, 1), b2 + hstepB, voffB);
;             PG8_WAIT_V(6); PG8_BAR; PG8_MMA(1, 1, At, B1); PG8_BAR;
.Lhalf_skip_y_2:
.LBB0_280:
	ds_read_b128 v[150:153], v147
	ds_read_b128 v[154:157], v147 offset:1024
	ds_read_b128 v[158:161], v147 offset:2048
	ds_read_b128 v[162:165], v147 offset:3072
	s_add_u32 s48, s6, 0xfff80080
	s_addc_u32 s49, s7, -1
	s_cmp_eq_u32 s69, 28
	s_cselect_b32 s51, s9, s49
	s_cselect_b32 s50, s29, s48
	s_cselect_b32 s49, s31, s68
	s_cselect_b32 s48, s47, s67
	s_add_i32 m0, s54, 0xc000
	ds_read_b128 v[166:169], v148
	ds_read_b128 v[170:173], v148 offset:1024
	ds_read_b128 v[174:177], v148 offset:2048
	ds_read_b128 v[178:181], v148 offset:3072
	ds_read_b128 v[182:185], v148 offset:4096
	ds_read_b128 v[186:189], v148 offset:5120
	ds_read_b128 v[190:193], v148 offset:6144
	ds_read_b128 v[194:197], v148 offset:7168
	global_load_lds_dwordx4 v136, s[6:7]
	s_add_i32 m0, s54, 0xe000
	s_nop 0
	global_load_lds_dwordx4 v138, s[6:7]
	s_add_i32 s70, s63, s53
	s_mov_b32 m0, s70
	ds_read_b128 v[198:201], v149
	ds_read_b128 v[202:205], v149 offset:1024
	ds_read_b128 v[206:209], v149 offset:2048
	ds_read_b128 v[210:213], v149 offset:3072
	s_waitcnt vmcnt(8)
	s_waitcnt lgkmcnt(0)
	s_barrier
	v_mfma_f32_16x16x32_bf16 v[124:127], v[150:153], v[166:169], v[124:127]
	v_mfma_f32_16x16x32_bf16 v[120:123], v[158:161], v[166:169], v[120:123]
	v_mfma_f32_16x16x32_bf16 v[108:111], v[150:153], v[174:177], v[108:111]
	v_mfma_f32_16x16x32_bf16 v[104:107], v[158:161], v[174:177], v[104:107]
	v_mfma_f32_16x16x32_bf16 v[92:95], v[150:153], v[182:185], v[92:95]
	v_mfma_f32_16x16x32_bf16 v[88:91], v[158:161], v[182:185], v[88:91]
	v_mfma_f32_16x16x32_bf16 v[76:79], v[150:153], v[190:193], v[76:79]
	v_mfma_f32_16x16x32_bf16 v[72:75], v[158:161], v[190:193], v[72:75]
	v_mfma_f32_16x16x32_bf16 v[124:127], v[154:157], v[170:173], v[124:127]
	v_mfma_f32_16x16x32_bf16 v[120:123], v[162:165], v[170:173], v[120:123]
	v_mfma_f32_16x16x32_bf16 v[108:111], v[154:157], v[178:181], v[108:111]
	v_mfma_f32_16x16x32_bf16 v[104:107], v[162:165], v[178:181], v[104:107]
	v_mfma_f32_16x16x32_bf16 v[92:95], v[154:157], v[186:189], v[92:95]
	v_mfma_f32_16x16x32_bf16 v[88:91], v[162:165], v[186:189], v[88:91]
	v_mfma_f32_16x16x32_bf16 v[76:79], v[154:157], v[194:197], v[76:79]
	v_mfma_f32_16x16x32_bf16 v[72:75], v[162:165], v[194:197], v[72:75]
	v_mfma_f32_16x16x32_bf16 v[116:119], v[198:201], v[166:169], v[116:119]
	v_mfma_f32_16x16x32_bf16 v[112:115], v[206:209], v[166:169], v[112:115]
	v_mfma_f32_16x16x32_bf16 v[100:103], v[198:201], v[174:177], v[100:103]
	v_mfma_f32_16x16x32_bf16 v[96:99], v[206:209], v[174:177], v[96:99]
	v_mfma_f32_16x16x32_bf16 v[84:87], v[198:201], v[182:185], v[84:87]
	v_mfma_f32_16x16x32_bf16 v[80:83], v[206:209], v[182:185], v[80:83]
	v_mfma_f32_16x16x32_bf16 v[68:71], v[198:201], v[190:193], v[68:71]
	v_mfma_f32_16x16x32_bf16 v[64:67], v[206:209], v[190:193], v[64:67]
	v_mfma_f32_16x16x32_bf16 v[116:119], v[202:205], v[170:173], v[116:119]
	v_mfma_f32_16x16x32_bf16 v[112:115], v[210:213], v[170:173], v[112:115]
	v_mfma_f32_16x16x32_bf16 v[100:103], v[202:205], v[178:181], v[100:103]
	v_mfma_f32_16x16x32_bf16 v[96:99], v[210:213], v[178:181], v[96:99]
	v_mfma_f32_16x16x32_bf16 v[84:87], v[202:205], v[186:189], v[84:87]
	v_mfma_f32_16x16x32_bf16 v[80:83], v[210:213], v[186:189], v[80:83]
	v_mfma_f32_16x16x32_bf16 v[68:71], v[202:205], v[194:197], v[68:71]
	v_mfma_f32_16x16x32_bf16 v[64:67], v[210:213], v[194:197], v[64:67]
	s_barrier
	global_load_lds_dwordx4 v128, s[48:49]
	s_add_i32 m0, s70, 0x2000
	s_nop 0
	global_load_lds_dwordx4 v132, s[48:49]
	s_mov_b32 m0, s54
	v_lshl_add_u64 v[214:215], s[50:51], 0, v[130:131]
	ds_read_b128 v[166:169], v148 offset:16384
	ds_read_b128 v[170:173], v148 offset:17408
	ds_read_b128 v[174:177], v148 offset:18432
	ds_read_b128 v[178:181], v148 offset:19456
	ds_read_b128 v[182:185], v148 offset:20480
	ds_read_b128 v[186:189], v148 offset:21504
	ds_read_b128 v[190:193], v148 offset:22528
	ds_read_b128 v[194:197], v148 offset:23552
	global_load_lds_dwordx4 v[214:215], off
	v_lshl_add_u64 v[216:217], s[50:51], 0, v[134:135]
	s_mov_b32 m0, s55
	s_nop 0
	global_load_lds_dwordx4 v[216:217], off
	s_add_u32 s70, s48, 0x4000
	s_addc_u32 s71, s49, 0
	s_add_i32 s72, s64, s53
	s_mov_b32 m0, s72
	s_nop 0
	global_load_lds_dwordx4 v128, s[70:71]
	s_add_i32 m0, s72, 0x2000
	s_nop 0
	global_load_lds_dwordx4 v132, s[70:71]
	s_waitcnt vmcnt(8)
	s_waitcnt lgkmcnt(0)
	s_barrier
	v_mfma_f32_16x16x32_bf16 v[60:63], v[150:153], v[166:169], v[60:63]
	v_mfma_f32_16x16x32_bf16 v[56:59], v[158:161], v[166:169], v[56:59]
	v_mfma_f32_16x16x32_bf16 v[44:47], v[150:153], v[174:177], v[44:47]
	v_mfma_f32_16x16x32_bf16 v[40:43], v[158:161], v[174:177], v[40:43]
	v_mfma_f32_16x16x32_bf16 v[28:31], v[150:153], v[182:185], v[28:31]
	v_mfma_f32_16x16x32_bf16 v[24:27], v[158:161], v[182:185], v[24:27]
	v_mfma_f32_16x16x32_bf16 v[12:15], v[150:153], v[190:193], v[12:15]
	v_mfma_f32_16x16x32_bf16 v[8:11], v[158:161], v[190:193], v[8:11]
	v_mfma_f32_16x16x32_bf16 v[60:63], v[154:157], v[170:173], v[60:63]
	v_mfma_f32_16x16x32_bf16 v[56:59], v[162:165], v[170:173], v[56:59]
	v_mfma_f32_16x16x32_bf16 v[44:47], v[154:157], v[178:181], v[44:47]
	v_mfma_f32_16x16x32_bf16 v[40:43], v[162:165], v[178:181], v[40:43]
	v_mfma_f32_16x16x32_bf16 v[28:31], v[154:157], v[186:189], v[28:31]
	v_mfma_f32_16x16x32_bf16 v[24:27], v[162:165], v[186:189], v[24:27]
	v_mfma_f32_16x16x32_bf16 v[12:15], v[154:157], v[194:197], v[12:15]
	v_mfma_f32_16x16x32_bf16 v[8:11], v[162:165], v[194:197], v[8:11]
	v_mfma_f32_16x16x32_bf16 v[52:55], v[198:201], v[166:169], v[52:55]
	v_mfma_f32_16x16x32_bf16 v[48:51], v[206:209], v[166:169], v[48:51]
	v_mfma_f32_16x16x32_bf16 v[36:39], v[198:201], v[174:177], v[36:39]
	v_mfma_f32_16x16x32_bf16 v[32:35], v[206:209], v[174:177], v[32:35]
	v_mfma_f32_16x16x32_bf16 v[20:23], v[198:201], v[182:185], v[20:23]
	v_mfma_f32_16x16x32_bf16 v[16:19], v[206:209], v[182:185], v[16:19]
	v_mfma_f32_16x16x32_bf16 v[4:7], v[198:201], v[190:193], v[4:7]
	v_mfma_f32_16x16x32_bf16 v[0:3], v[206:209], v[190:193], v[0:3]
	v_mfma_f32_16x16x32_bf16 v[52:55], v[202:205], v[170:173], v[52:55]
	v_mfma_f32_16x16x32_bf16 v[48:51], v[210:213], v[170:173], v[48:51]
	v_mfma_f32_16x16x32_bf16 v[36:39], v[202:205], v[178:181], v[36:39]
	v_mfma_f32_16x16x32_bf16 v[32:35], v[210:213], v[178:181], v[32:35]
	v_mfma_f32_16x16x32_bf16 v[20:23], v[202:205], v[186:189], v[20:23]
	v_mfma_f32_16x16x32_bf16 v[16:19], v[210:213], v[186:189], v[16:19]
	v_mfma_f32_16x16x32_bf16 v[4:7], v[202:205], v[194:197], v[4:7]
	v_mfma_f32_16x16x32_bf16 v[0:3], v[210:213], v[194:197], v[0:3]
	s_barrier
; #define PG8_STAGE(bufoff, gbase, voff) do { _Pragma("unroll") for (int _i = 0; _i < 2; ++_i) \
;         __builtin_amdgcn_global_load_lds((const unsigned*)((const char*)(gbase) + (voff)[_i]), (PG8_LAS unsigned*)(lds + (bufoff) + ldsw + _i * 8192), 16, 0, 0); } while (0)
; #define PG8_LDA(dst, b, h) do { _Pragma("unroll") for (int m = 0; m < 4; ++m) _Pragma("unroll") for (int k = 0; k < 2; ++k) dst[m][k] = *(const PG8_LAS bf16x8*)(lds + PG8_SA(b, h) + aoff + m * 2048 + k * 1024); } while (0)
; #define PG8_LDB(dst, b, h) do { _Pragma("unroll") for (int n = 0; n < 2; ++n) _Pragma("unroll") for (int k = 0; k < 2; ++k) dst[n][k] = *(const PG8_LAS bf16x8*)(lds + PG8_SB(b, h) + boff + n * 2048 + k * 1024); } while (0)
; #define PG8_MMA(ai, bj, At, Bt) do { __builtin_amdgcn_s_setprio(1); _Pragma("unroll") for (int m = 0; m < 4; ++m) _Pragma("unroll") for (int n = 0; n < 2; ++n) _Pragma("unroll") for (int k = 0; k < 2; ++k) \
;         acc[ai][bj][m][n] = __builtin_amdgcn_mfma_f32_16x16x32_bf16(Bt[n][k], At[m][k], acc[ai][bj][m][n], 0, 0, 0); __builtin_amdgcn_s_setprio(0); } while (0)
; #define PG8_WAIT_V(n) asm volatile("s_waitcnt vmcnt(" #n ")" ::: "memory")
; #define PG8_WAIT_L(n) asm volatile("s_waitcnt lgkmcnt(" #n ")" ::: "memory")
; #define PG8_BAR __builtin_amdgcn_s_barrier()
; #define PG8_SCHED __builtin_amdgcn_sched_barrier(0)
; template <class Epi, class Sched>
; __device__ __forceinline__ void gemm_phase(PG8_LAS unsigned char* lds, const Gemm g, const Sched& S, const Epi& E) {
;     ...
;             PG8_LDB(B0, 1, 0); PG8_SCHED; PG8_LDA(At, 1, 0); PG8_STAGE(PG8_SA(0, 1), a2 + hstep, voffA);
;             PG8_WAIT_L(8); PG8_BAR; PG8_WAIT_L(0); PG8_MMA(0, 0, At, B0); PG8_BAR; PG8_SCHED;
;             PG8_LDB(B1, 1, 1); PG8_STAGE(PG8_SB(1, 0), b3, voffB);
;             PG8_BAR; PG8_WAIT_L(0); PG8_MMA(0, 1, At, B1); PG8_BAR;
;             PG8_LDA(At, 1, 1); PG8_STAGE(PG8_SA(1, 0), a3, voffA);
;             PG8_BAR; PG8_WAIT_L(0); PG8_MMA(1, 0, At, B0); PG8_BAR; PG8_SCHED;
;             PG8_STAGE(PG8_SB(1, 1), b3 + hstepB, voffB);
;             PG8_WAIT_V(6); PG8_BAR; PG8_MMA(1, 1, At, B1); PG8_BAR;
	s_add_i32 s70, 0, 0x18000
	v_add_u32_e32 v162, s70, v145
	ds_read_b128 v[150:153], v162
	ds_read_b128 v[154:157], v162 offset:1024
	ds_read_b128 v[158:161], v162 offset:2048
	ds_read_b128 v[162:165], v162 offset:3072
	s_add_u32 s50, s50, 0x80000
	s_addc_u32 s51, s51, 0
	s_mov_b32 m0, s56
	ds_read_b128 v[166:169], v148 offset:32768
	ds_read_b128 v[170:173], v148 offset:33792
	ds_read_b128 v[174:177], v148 offset:34816
	ds_read_b128 v[178:181], v148 offset:35840
	ds_read_b128 v[182:185], v148 offset:36864
	ds_read_b128 v[186:189], v148 offset:37888
	ds_read_b128 v[190:193], v148 offset:38912
	ds_read_b128 v[194:197], v148 offset:39936
	global_load_lds_dwordx4 v130, s[50:51]
	s_mov_b32 m0, s57
	s_nop 0
	global_load_lds_dwordx4 v134, s[50:51]
	s_add_i32 s71, 0, 0x1c000
	s_add_u32 s50, s48, 0x8000
	s_addc_u32 s51, s49, 0
	s_add_i32 s70, s70, s53
	v_add_u32_e32 v210, s71, v145
	s_mov_b32 m0, s70
	ds_read_b128 v[198:201], v210
	ds_read_b128 v[202:205], v210 offset:1024
	ds_read_b128 v[206:209], v210 offset:2048
	ds_read_b128 v[210:213], v210 offset:3072
	s_waitcnt vmcnt(8)
	s_waitcnt lgkmcnt(0)
	s_barrier
	v_mfma_f32_16x16x32_bf16 v[124:127], v[150:153], v[166:169], v[124:127]
	v_mfma_f32_16x16x32_bf16 v[120:123], v[158:161], v[166:169], v[120:123]
	v_mfma_f32_16x16x32_bf16 v[108:111], v[150:153], v[174:177], v[108:111]
	v_mfma_f32_16x16x32_bf16 v[104:107], v[158:161], v[174:177], v[104:107]
	v_mfma_f32_16x16x32_bf16 v[92:95], v[150:153], v[182:185], v[92:95]
	v_mfma_f32_16x16x32_bf16 v[88:91], v[158:161], v[182:185], v[88:91]
	v_mfma_f32_16x16x32_bf16 v[76:79], v[150:153], v[190:193], v[76:79]
	v_mfma_f32_16x16x32_bf16 v[72:75], v[158:161], v[190:193], v[72:75]
	v_mfma_f32_16x16x32_bf16 v[124:127], v[154:157], v[170:173], v[124:127]
	v_mfma_f32_16x16x32_bf16 v[120:123], v[162:165], v[170:173], v[120:123]
	v_mfma_f32_16x16x32_bf16 v[108:111], v[154:157], v[178:181], v[108:111]
	v_mfma_f32_16x16x32_bf16 v[104:107], v[162:165], v[178:181], v[104:107]
	v_mfma_f32_16x16x32_bf16 v[92:95], v[154:157], v[186:189], v[92:95]
	v_mfma_f32_16x16x32_bf16 v[88:91], v[162:165], v[186:189], v[88:91]
	v_mfma_f32_16x16x32_bf16 v[76:79], v[154:157], v[194:197], v[76:79]
	v_mfma_f32_16x16x32_bf16 v[72:75], v[162:165], v[194:197], v[72:75]
	v_mfma_f32_16x16x32_bf16 v[116:119], v[198:201], v[166:169], v[116:119]
	v_mfma_f32_16x16x32_bf16 v[112:115], v[206:209], v[166:169], v[112:115]
	v_mfma_f32_16x16x32_bf16 v[100:103], v[198:201], v[174:177], v[100:103]
	v_mfma_f32_16x16x32_bf16 v[96:99], v[206:209], v[174:177], v[96:99]
	v_mfma_f32_16x16x32_bf16 v[84:87], v[198:201], v[182:185], v[84:87]
	v_mfma_f32_16x16x32_bf16 v[80:83], v[206:209], v[182:185], v[80:83]
	v_mfma_f32_16x16x32_bf16 v[68:71], v[198:201], v[190:193], v[68:71]
	v_mfma_f32_16x16x32_bf16 v[64:67], v[206:209], v[190:193], v[64:67]
	v_mfma_f32_16x16x32_bf16 v[116:119], v[202:205], v[170:173], v[116:119]
	v_mfma_f32_16x16x32_bf16 v[112:115], v[210:213], v[170:173], v[112:115]
	v_mfma_f32_16x16x32_bf16 v[100:103], v[202:205], v[178:181], v[100:103]
	v_mfma_f32_16x16x32_bf16 v[96:99], v[210:213], v[178:181], v[96:99]
	v_mfma_f32_16x16x32_bf16 v[84:87], v[202:205], v[186:189], v[84:87]
	v_mfma_f32_16x16x32_bf16 v[80:83], v[210:213], v[186:189], v[80:83]
	v_mfma_f32_16x16x32_bf16 v[68:71], v[202:205], v[194:197], v[68:71]
	v_mfma_f32_16x16x32_bf16 v[64:67], v[210:213], v[194:197], v[64:67]
	s_barrier
	global_load_lds_dwordx4 v128, s[50:51]
	s_add_i32 m0, s70, 0x2000
	s_nop 0
	global_load_lds_dwordx4 v132, s[50:51]
	s_mov_b32 m0, s59
	v_lshl_add_u64 v[214:215], v[214:215], 0, s[12:13]
	ds_read_b128 v[166:169], v148 offset:49152
	ds_read_b128 v[170:173], v148 offset:50176
	ds_read_b128 v[174:177], v148 offset:51200
	ds_read_b128 v[178:181], v148 offset:52224
	ds_read_b128 v[182:185], v148 offset:53248
	ds_read_b128 v[186:189], v148 offset:54272
	ds_read_b128 v[190:193], v148 offset:55296
	ds_read_b128 v[194:197], v148 offset:56320
	global_load_lds_dwordx4 v[214:215], off
	v_lshl_add_u64 v[214:215], v[216:217], 0, s[12:13]
	s_mov_b32 m0, s60
	s_nop 0
	global_load_lds_dwordx4 v[214:215], off
	s_add_u32 s48, s48, 0xc000
	s_addc_u32 s49, s49, 0
	s_add_i32 s50, s71, s53
	s_mov_b32 m0, s50
	s_nop 0
	global_load_lds_dwordx4 v128, s[48:49]
	s_add_i32 m0, s50, 0x2000
	s_nop 0
	global_load_lds_dwordx4 v132, s[48:49]
	s_add_i32 s69, s69, 2
	s_add_u32 s67, s67, 0x10000
	s_addc_u32 s68, s68, 0
	s_add_u32 s6, s6, 0x100
	s_addc_u32 s7, s7, 0
	s_cmp_gt_u32 s69, 29
	s_waitcnt vmcnt(8)
	s_waitcnt lgkmcnt(0)
	s_barrier
	v_mfma_f32_16x16x32_bf16 v[60:63], v[150:153], v[166:169], v[60:63]
	v_mfma_f32_16x16x32_bf16 v[56:59], v[158:161], v[166:169], v[56:59]
	v_mfma_f32_16x16x32_bf16 v[44:47], v[150:153], v[174:177], v[44:47]
	v_mfma_f32_16x16x32_bf16 v[40:43], v[158:161], v[174:177], v[40:43]
	v_mfma_f32_16x16x32_bf16 v[28:31], v[150:153], v[182:185], v[28:31]
	v_mfma_f32_16x16x32_bf16 v[24:27], v[158:161], v[182:185], v[24:27]
	v_mfma_f32_16x16x32_bf16 v[12:15], v[150:153], v[190:193], v[12:15]
	v_mfma_f32_16x16x32_bf16 v[8:11], v[158:161], v[190:193], v[8:11]
	v_mfma_f32_16x16x32_bf16 v[60:63], v[154:157], v[170:173], v[60:63]
	v_mfma_f32_16x16x32_bf16 v[56:59], v[162:165], v[170:173], v[56:59]
	v_mfma_f32_16x16x32_bf16 v[44:47], v[154:157], v[178:181], v[44:47]
	v_mfma_f32_16x16x32_bf16 v[40:43], v[162:165], v[178:181], v[40:43]
	v_mfma_f32_16x16x32_bf16 v[28:31], v[154:157], v[186:189], v[28:31]
	v_mfma_f32_16x16x32_bf16 v[24:27], v[162:165], v[186:189], v[24:27]
	v_mfma_f32_16x16x32_bf16 v[12:15], v[154:157], v[194:197], v[12:15]
	v_mfma_f32_16x16x32_bf16 v[8:11], v[162:165], v[194:197], v[8:11]
	v_mfma_f32_16x16x32_bf16 v[52:55], v[198:201], v[166:169], v[52:55]
	v_mfma_f32_16x16x32_bf16 v[48:51], v[206:209], v[166:169], v[48:51]
	v_mfma_f32_16x16x32_bf16 v[36:39], v[198:201], v[174:177], v[36:39]
	v_mfma_f32_16x16x32_bf16 v[32:35], v[206:209], v[174:177], v[32:35]
	v_mfma_f32_16x16x32_bf16 v[20:23], v[198:201], v[182:185], v[20:23]
	v_mfma_f32_16x16x32_bf16 v[16:19], v[206:209], v[182:185], v[16:19]
	v_mfma_f32_16x16x32_bf16 v[4:7], v[198:201], v[190:193], v[4:7]
	v_mfma_f32_16x16x32_bf16 v[0:3], v[206:209], v[190:193], v[0:3]
	v_mfma_f32_16x16x32_bf16 v[52:55], v[202:205], v[170:173], v[52:55]
	v_mfma_f32_16x16x32_bf16 v[48:51], v[210:213], v[170:173], v[48:51]
	v_mfma_f32_16x16x32_bf16 v[36:39], v[202:205], v[178:181], v[36:39]
	v_mfma_f32_16x16x32_bf16 v[32:35], v[210:213], v[178:181], v[32:35]
	s_cbranch_scc1 .Lunit_exit_2
	v_mfma_f32_16x16x32_bf16 v[20:23], v[202:205], v[186:189], v[20:23]
	v_mfma_f32_16x16x32_bf16 v[16:19], v[210:213], v[186:189], v[16:19]
	v_mfma_f32_16x16x32_bf16 v[4:7], v[202:205], v[194:197], v[4:7]
	v_mfma_f32_16x16x32_bf16 v[0:3], v[210:213], v[194:197], v[0:3]
	s_barrier
	s_branch .LBB0_280
; #define PG8_MMA(ai, bj, At, Bt) do { __builtin_amdgcn_s_setprio(1); _Pragma("unroll") for (int m = 0; m < 4; ++m) _Pragma("unroll") for (int n = 0; n < 2; ++n) _Pragma("unroll") for (int k = 0; k < 2; ++k) \
;         acc[ai][bj][m][n] = __builtin_amdgcn_mfma_f32_16x16x32_bf16(Bt[n][k], At[m][k], acc[ai][bj][m][n], 0, 0, 0); __builtin_amdgcn_s_setprio(0); } while (0)
; #define PG8_WAIT_V(n) asm volatile("s_waitcnt vmcnt(" #n ")" ::: "memory")
; #define PG8_BAR __builtin_amdgcn_s_barrier()
; template <class Epi, class Sched>
; __device__ __forceinline__ void gemm_phase(PG8_LAS unsigned char* lds, const Gemm g, const Sched& S, const Epi& E) {
;     ...
;             PG8_WAIT_V(6); PG8_BAR; PG8_MMA(1, 1, At, B1); PG8_BAR;
;         }
;         if constexpr (!Epi::AFTER_DRAIN) { E(acc, cur, wr, wc, fr, fq); if constexpr (Epi::IDEMP && EPI_REP > 1) { asm volatile("" ::: "memory"); E(acc, cur, wr, wc, fr, fq); } S.done(cur); }
;         if (!has_next) break;
.Lunit_exit_2:
	v_mfma_f32_16x16x32_bf16 v[20:23], v[202:205], v[186:189], v[20:23]
	v_mfma_f32_16x16x32_bf16 v[16:19], v[210:213], v[186:189], v[16:19]
	v_mfma_f32_16x16x32_bf16 v[4:7], v[202:205], v[194:197], v[4:7]
	v_mfma_f32_16x16x32_bf16 v[0:3], v[210:213], v[194:197], v[0:3]
	s_cmp_eq_u32 s78, 1
	s_cbranch_scc1 .Lunit_skipb_2
	s_barrier

; #define PG8_STAGE(bufoff, gbase, voff) do { _Pragma("unroll") for (int _i = 0; _i < 2; ++_i) \
;         __builtin_amdgcn_global_load_lds((const unsigned*)((const char*)(gbase) + (voff)[_i]), (PG8_LAS unsigned*)(lds + (bufoff) + ldsw + _i * 8192), 16, 0, 0); } while (0)
; #define PG8_LDA(dst, b, h) do { _Pragma("unroll") for (int m = 0; m < 4; ++m) _Pragma("unroll") for (int k = 0; k < 2; ++k) dst[m][k] = *(const PG8_LAS bf16x8*)(lds + PG8_SA(b, h) + aoff + m * 2048 + k * 1024); } while (0)
; #define PG8_LDB(dst, b, h) do { _Pragma("unroll") for (int n = 0; n < 2; ++n) _Pragma("unroll") for (int k = 0; k < 2; ++k) dst[n][k] = *(const PG8_LAS bf16x8*)(lds + PG8_SB(b, h) + boff + n * 2048 + k * 1024); } while (0)
; #define PG8_MMA(ai, bj, At, Bt) do { __builtin_amdgcn_s_setprio(1); _Pragma("unroll") for (int m = 0; m < 4; ++m) _Pragma("unroll") for (int n = 0; n < 2; ++n) _Pragma("unroll") for (int k = 0; k < 2; ++k) \
;         acc[ai][bj][m][n] = __builtin_amdgcn_mfma_f32_16x16x32_bf16(Bt[n][k], At[m][k], acc[ai][bj][m][n], 0, 0, 0); __builtin_amdgcn_s_setprio(0); } while (0)
; #define PG8_WAIT_V(n) asm volatile("s_waitcnt vmcnt(" #n ")" ::: "memory")
; template <class Epi, class Sched>
; __device__ __forceinline__ void gemm_phase(PG8_LAS unsigned char* lds, const Gemm g, const Sched& S, const Epi& E) {
;     ...
;         for (int t = 0; t < nt; t += 2) {
;             const bool last = (t == nt - 2);
;             const char* a1 = cA + (size_t)(t + 1) * kstep;
;             const char* a2 = last ? nA : cA + (size_t)(t + 2) * kstep; const char* b2 = last ? nB : cB + (size_t)(t + 2) * kstepB;
;             const char* a3 = a2 + kstep; const char* b3 = b2 + kstepB;
;             if (last && has_next) S.a_ready(nxt);
;             PG8_LDB(B0, 0, 0); PG8_SCHED; PG8_LDA(At, 0, 0); PG8_STAGE(PG8_SA(1, 1), a1 + hstep, voffA);
;             PG8_WAIT_L(8); PG8_BAR; PG8_WAIT_L(0); PG8_MMA(0, 0, At, B0); PG8_BAR; PG8_SCHED;
;             PG8_LDB(B1, 0, 1); PG8_STAGE(PG8_SB(0, 0), b2, voffB);
;             PG8_BAR; PG8_WAIT_L(0); PG8_MMA(0, 1, At, B1); PG8_BAR;
;             PG8_LDA(At, 0, 1); PG8_STAGE(PG8_SA(0, 0), a2, voffA);
;             PG8_BAR; PG8_WAIT_L(0); PG8_MMA(1, 0, At, B0); PG8_BAR; PG8_SCHED;
;             PG8_STAGE(PG8_SB(0, 1), b2 + hstepB, voffB);
;             PG8_WAIT_V(6); PG8_BAR; PG8_MMA(1, 1, At, B1); PG8_BAR;
.Lhalf_skip_y_3:
.LBB0_397:
	ds_read_b128 v[142:145], v150
	ds_read_b128 v[154:157], v150 offset:1024
	ds_read_b128 v[158:161], v150 offset:2048
	ds_read_b128 v[162:165], v150 offset:3072
	s_add_u32 s26, s24, 0xfff80080
	s_addc_u32 s27, s25, -1
	s_cmp_eq_u32 s66, 28
	s_cselect_b32 s29, s5, s27
	s_cselect_b32 s28, s15, s26
	s_cselect_b32 s27, s17, s65
	s_cselect_b32 s26, s23, s64
	s_add_i32 m0, s48, 0xc000
	ds_read_b128 v[166:169], v151
	ds_read_b128 v[170:173], v151 offset:1024
	ds_read_b128 v[174:177], v151 offset:2048
	ds_read_b128 v[178:181], v151 offset:3072
	ds_read_b128 v[182:185], v151 offset:4096
	ds_read_b128 v[186:189], v151 offset:5120
	ds_read_b128 v[190:193], v151 offset:6144
	ds_read_b128 v[194:197], v151 offset:7168
	global_load_lds_dwordx4 v138, s[24:25]
	s_add_i32 m0, s48, 0xe000
	s_nop 0
	global_load_lds_dwordx4 v140, s[24:25]
	s_add_i32 s67, s59, s39
	s_mov_b32 m0, s67
	ds_read_b128 v[198:201], v152
	ds_read_b128 v[202:205], v152 offset:1024
	ds_read_b128 v[206:209], v152 offset:2048
	ds_read_b128 v[210:213], v152 offset:3072
	s_waitcnt vmcnt(8)
	s_waitcnt lgkmcnt(0)
	s_barrier
	v_mfma_f32_16x16x32_bf16 v[124:127], v[142:145], v[166:169], v[124:127]
	v_mfma_f32_16x16x32_bf16 v[120:123], v[158:161], v[166:169], v[120:123]
	v_mfma_f32_16x16x32_bf16 v[108:111], v[142:145], v[174:177], v[108:111]
	v_mfma_f32_16x16x32_bf16 v[104:107], v[158:161], v[174:177], v[104:107]
	v_mfma_f32_16x16x32_bf16 v[92:95], v[142:145], v[182:185], v[92:95]
	v_mfma_f32_16x16x32_bf16 v[88:91], v[158:161], v[182:185], v[88:91]
	v_mfma_f32_16x16x32_bf16 v[76:79], v[142:145], v[190:193], v[76:79]
	v_mfma_f32_16x16x32_bf16 v[72:75], v[158:161], v[190:193], v[72:75]
	v_mfma_f32_16x16x32_bf16 v[124:127], v[154:157], v[170:173], v[124:127]
	v_mfma_f32_16x16x32_bf16 v[120:123], v[162:165], v[170:173], v[120:123]
	v_mfma_f32_16x16x32_bf16 v[108:111], v[154:157], v[178:181], v[108:111]
	v_mfma_f32_16x16x32_bf16 v[104:107], v[162:165], v[178:181], v[104:107]
	v_mfma_f32_16x16x32_bf16 v[92:95], v[154:157], v[186:189], v[92:95]
	v_mfma_f32_16x16x32_bf16 v[88:91], v[162:165], v[186:189], v[88:91]
	v_mfma_f32_16x16x32_bf16 v[76:79], v[154:157], v[194:197], v[76:79]
	v_mfma_f32_16x16x32_bf16 v[72:75], v[162:165], v[194:197], v[72:75]
	v_mfma_f32_16x16x32_bf16 v[116:119], v[198:201], v[166:169], v[116:119]
	v_mfma_f32_16x16x32_bf16 v[112:115], v[206:209], v[166:169], v[112:115]
	v_mfma_f32_16x16x32_bf16 v[100:103], v[198:201], v[174:177], v[100:103]
	v_mfma_f32_16x16x32_bf16 v[96:99], v[206:209], v[174:177], v[96:99]
	v_mfma_f32_16x16x32_bf16 v[84:87], v[198:201], v[182:185], v[84:87]
	v_mfma_f32_16x16x32_bf16 v[80:83], v[206:209], v[182:185], v[80:83]
	v_mfma_f32_16x16x32_bf16 v[68:71], v[198:201], v[190:193], v[68:71]
	v_mfma_f32_16x16x32_bf16 v[64:67], v[206:209], v[190:193], v[64:67]
	v_mfma_f32_16x16x32_bf16 v[116:119], v[202:205], v[170:173], v[116:119]
	v_mfma_f32_16x16x32_bf16 v[112:115], v[210:213], v[170:173], v[112:115]
	v_mfma_f32_16x16x32_bf16 v[100:103], v[202:205], v[178:181], v[100:103]
	v_mfma_f32_16x16x32_bf16 v[96:99], v[210:213], v[178:181], v[96:99]
	v_mfma_f32_16x16x32_bf16 v[84:87], v[202:205], v[186:189], v[84:87]
	v_mfma_f32_16x16x32_bf16 v[80:83], v[210:213], v[186:189], v[80:83]
	v_mfma_f32_16x16x32_bf16 v[68:71], v[202:205], v[194:197], v[68:71]
	v_mfma_f32_16x16x32_bf16 v[64:67], v[210:213], v[194:197], v[64:67]
	s_barrier
	global_load_lds_dwordx4 v128, s[26:27]
	s_add_i32 m0, s67, 0x2000
	s_nop 0
	global_load_lds_dwordx4 v132, s[26:27]
	s_mov_b32 m0, s48
	v_lshl_add_u64 v[214:215], s[28:29], 0, v[130:131]
	ds_read_b128 v[166:169], v151 offset:16384
	ds_read_b128 v[170:173], v151 offset:17408
	ds_read_b128 v[174:177], v151 offset:18432
	ds_read_b128 v[178:181], v151 offset:19456
	ds_read_b128 v[182:185], v151 offset:20480
	ds_read_b128 v[186:189], v151 offset:21504
	ds_read_b128 v[190:193], v151 offset:22528
	ds_read_b128 v[194:197], v151 offset:23552
	global_load_lds_dwordx4 v[214:215], off
	v_lshl_add_u64 v[216:217], s[28:29], 0, v[134:135]
	s_mov_b32 m0, s49
	s_nop 0
	global_load_lds_dwordx4 v[216:217], off
	s_add_u32 s68, s26, 0x4000
	s_addc_u32 s69, s27, 0
	s_add_i32 s67, s60, s39
	s_mov_b32 m0, s67
	s_nop 0
	global_load_lds_dwordx4 v128, s[68:69]
	s_add_i32 m0, s67, 0x2000
	s_nop 0
	global_load_lds_dwordx4 v132, s[68:69]
	s_waitcnt vmcnt(8)
	s_waitcnt lgkmcnt(0)
	s_barrier
	v_mfma_f32_16x16x32_bf16 v[60:63], v[142:145], v[166:169], v[60:63]
	v_mfma_f32_16x16x32_bf16 v[56:59], v[158:161], v[166:169], v[56:59]
	v_mfma_f32_16x16x32_bf16 v[44:47], v[142:145], v[174:177], v[44:47]
	v_mfma_f32_16x16x32_bf16 v[40:43], v[158:161], v[174:177], v[40:43]
	v_mfma_f32_16x16x32_bf16 v[28:31], v[142:145], v[182:185], v[28:31]
	v_mfma_f32_16x16x32_bf16 v[24:27], v[158:161], v[182:185], v[24:27]
	v_mfma_f32_16x16x32_bf16 v[12:15], v[142:145], v[190:193], v[12:15]
	v_mfma_f32_16x16x32_bf16 v[8:11], v[158:161], v[190:193], v[8:11]
	v_mfma_f32_16x16x32_bf16 v[60:63], v[154:157], v[170:173], v[60:63]
	v_mfma_f32_16x16x32_bf16 v[56:59], v[162:165], v[170:173], v[56:59]
	v_mfma_f32_16x16x32_bf16 v[44:47], v[154:157], v[178:181], v[44:47]
	v_mfma_f32_16x16x32_bf16 v[40:43], v[162:165], v[178:181], v[40:43]
	v_mfma_f32_16x16x32_bf16 v[28:31], v[154:157], v[186:189], v[28:31]
	v_mfma_f32_16x16x32_bf16 v[24:27], v[162:165], v[186:189], v[24:27]
	v_mfma_f32_16x16x32_bf16 v[12:15], v[154:157], v[194:197], v[12:15]
	v_mfma_f32_16x16x32_bf16 v[8:11], v[162:165], v[194:197], v[8:11]
	v_mfma_f32_16x16x32_bf16 v[52:55], v[198:201], v[166:169], v[52:55]
	v_mfma_f32_16x16x32_bf16 v[48:51], v[206:209], v[166:169], v[48:51]
	v_mfma_f32_16x16x32_bf16 v[36:39], v[198:201], v[174:177], v[36:39]
	v_mfma_f32_16x16x32_bf16 v[32:35], v[206:209], v[174:177], v[32:35]
	v_mfma_f32_16x16x32_bf16 v[20:23], v[198:201], v[182:185], v[20:23]
	v_mfma_f32_16x16x32_bf16 v[16:19], v[206:209], v[182:185], v[16:19]
	v_mfma_f32_16x16x32_bf16 v[4:7], v[198:201], v[190:193], v[4:7]
	v_mfma_f32_16x16x32_bf16 v[0:3], v[206:209], v[190:193], v[0:3]
	v_mfma_f32_16x16x32_bf16 v[52:55], v[202:205], v[170:173], v[52:55]
	v_mfma_f32_16x16x32_bf16 v[48:51], v[210:213], v[170:173], v[48:51]
	v_mfma_f32_16x16x32_bf16 v[36:39], v[202:205], v[178:181], v[36:39]
	v_mfma_f32_16x16x32_bf16 v[32:35], v[210:213], v[178:181], v[32:35]
	v_mfma_f32_16x16x32_bf16 v[20:23], v[202:205], v[186:189], v[20:23]
	v_mfma_f32_16x16x32_bf16 v[16:19], v[210:213], v[186:189], v[16:19]
	v_mfma_f32_16x16x32_bf16 v[4:7], v[202:205], v[194:197], v[4:7]
	v_mfma_f32_16x16x32_bf16 v[0:3], v[210:213], v[194:197], v[0:3]
	s_barrier
; #define PG8_STAGE(bufoff, gbase, voff) do { _Pragma("unroll") for (int _i = 0; _i < 2; ++_i) \
;         __builtin_amdgcn_global_load_lds((const unsigned*)((const char*)(gbase) + (voff)[_i]), (PG8_LAS unsigned*)(lds + (bufoff) + ldsw + _i * 8192), 16, 0, 0); } while (0)
; #define PG8_LDA(dst, b, h) do { _Pragma("unroll") for (int m = 0; m < 4; ++m) _Pragma("unroll") for (int k = 0; k < 2; ++k) dst[m][k] = *(const PG8_LAS bf16x8*)(lds + PG8_SA(b, h) + aoff + m * 2048 + k * 1024); } while (0)
; #define PG8_LDB(dst, b, h) do { _Pragma("unroll") for (int n = 0; n < 2; ++n) _Pragma("unroll") for (int k = 0; k < 2; ++k) dst[n][k] = *(const PG8_LAS bf16x8*)(lds + PG8_SB(b, h) + boff + n * 2048 + k * 1024); } while (0)
; #define PG8_WAIT_V(n) asm volatile("s_waitcnt vmcnt(" #n ")" ::: "memory")
; #define PG8_WAIT_L(n) asm volatile("s_waitcnt lgkmcnt(" #n ")" ::: "memory")
; #define PG8_BAR __builtin_amdgcn_s_barrier()
; #define PG8_SCHED __builtin_amdgcn_sched_barrier(0)
; template <class Epi, class Sched>
; __device__ __forceinline__ void gemm_phase(PG8_LAS unsigned char* lds, const Gemm g, const Sched& S, const Epi& E) {
;     ...
;             PG8_LDB(B0, 0, 0); PG8_SCHED; PG8_LDA(At, 0, 0); PG8_STAGE(PG8_SA(1, 1), a1 + hstep, voffA);
;             PG8_WAIT_L(8); PG8_BAR; PG8_WAIT_L(0); PG8_MMA(0, 0, At, B0); PG8_BAR; PG8_SCHED;
;             PG8_LDB(B1, 0, 1); PG8_STAGE(PG8_SB(0, 0), b2, voffB);
;             PG8_BAR; PG8_WAIT_L(0); PG8_MMA(0, 1, At, B1); PG8_BAR;
;             PG8_LDA(At, 0, 1); PG8_STAGE(PG8_SA(0, 0), a2, voffA);
;             PG8_BAR; PG8_WAIT_L(0); PG8_MMA(1, 0, At, B0); PG8_BAR; PG8_SCHED;
;             PG8_STAGE(PG8_SB(0, 1), b2 + hstepB, voffB);
;             PG8_WAIT_V(6); PG8_BAR; PG8_MMA(1, 1, At, B1); PG8_BAR;
;             PG8_LDB(B0, 1, 0); PG8_SCHED; PG8_LDA(At, 1, 0); PG8_STAGE(PG8_SA(0, 1), a2 + hstep, voffA);
;             PG8_WAIT_L(8); PG8_BAR; PG8_WAIT_L(0); PG8_MMA(0, 0, At, B0); PG8_BAR; PG8_SCHED;
;             PG8_LDB(B1, 1, 1); PG8_STAGE(PG8_SB(1, 0), b3, voffB);
;             PG8_BAR; PG8_WAIT_L(0); PG8_MMA(0, 1, At, B1); PG8_BAR;
;             PG8_LDA(At, 1, 1); PG8_STAGE(PG8_SA(1, 0), a3, voffA);
;             PG8_BAR; PG8_WAIT_L(0); PG8_MMA(1, 0, At, B0); PG8_BAR; PG8_SCHED;
;             PG8_STAGE(PG8_SB(1, 1), b3 + hstepB, voffB);
;             PG8_WAIT_V(6); PG8_BAR; PG8_MMA(1, 1, At, B1); PG8_BAR;
	s_add_i32 s67, 0, 0x18000
	v_add_u32_e32 v136, s67, v148
	ds_read_b128 v[142:145], v136
	ds_read_b128 v[154:157], v136 offset:1024
	ds_read_b128 v[158:161], v136 offset:2048
	ds_read_b128 v[162:165], v136 offset:3072
	s_add_u32 s28, s28, 0x80000
	s_addc_u32 s29, s29, 0
	s_mov_b32 m0, s50
	ds_read_b128 v[166:169], v151 offset:32768
	ds_read_b128 v[170:173], v151 offset:33792
	ds_read_b128 v[174:177], v151 offset:34816
	ds_read_b128 v[178:181], v151 offset:35840
	ds_read_b128 v[182:185], v151 offset:36864
	ds_read_b128 v[186:189], v151 offset:37888
	ds_read_b128 v[190:193], v151 offset:38912
	ds_read_b128 v[194:197], v151 offset:39936
	global_load_lds_dwordx4 v130, s[28:29]
	s_mov_b32 m0, s51
	s_nop 0
	global_load_lds_dwordx4 v134, s[28:29]
	s_add_i32 s68, 0, 0x1c000
	s_add_u32 s28, s26, 0x8000
	s_addc_u32 s29, s27, 0
	s_add_i32 s67, s67, s39
	v_add_u32_e32 v136, s68, v148
	s_mov_b32 m0, s67
	ds_read_b128 v[198:201], v136
	ds_read_b128 v[202:205], v136 offset:1024
	ds_read_b128 v[206:209], v136 offset:2048
	ds_read_b128 v[210:213], v136 offset:3072
	s_waitcnt vmcnt(8)
	s_waitcnt lgkmcnt(0)
	s_barrier
	v_mfma_f32_16x16x32_bf16 v[124:127], v[142:145], v[166:169], v[124:127]
	v_mfma_f32_16x16x32_bf16 v[120:123], v[158:161], v[166:169], v[120:123]
	v_mfma_f32_16x16x32_bf16 v[108:111], v[142:145], v[174:177], v[108:111]
	v_mfma_f32_16x16x32_bf16 v[104:107], v[158:161], v[174:177], v[104:107]
	v_mfma_f32_16x16x32_bf16 v[92:95], v[142:145], v[182:185], v[92:95]
	v_mfma_f32_16x16x32_bf16 v[88:91], v[158:161], v[182:185], v[88:91]
	v_mfma_f32_16x16x32_bf16 v[76:79], v[142:145], v[190:193], v[76:79]
	v_mfma_f32_16x16x32_bf16 v[72:75], v[158:161], v[190:193], v[72:75]
	v_mfma_f32_16x16x32_bf16 v[124:127], v[154:157], v[170:173], v[124:127]
	v_mfma_f32_16x16x32_bf16 v[120:123], v[162:165], v[170:173], v[120:123]
	v_mfma_f32_16x16x32_bf16 v[108:111], v[154:157], v[178:181], v[108:111]
	v_mfma_f32_16x16x32_bf16 v[104:107], v[162:165], v[178:181], v[104:107]
	v_mfma_f32_16x16x32_bf16 v[92:95], v[154:157], v[186:189], v[92:95]
	v_mfma_f32_16x16x32_bf16 v[88:91], v[162:165], v[186:189], v[88:91]
	v_mfma_f32_16x16x32_bf16 v[76:79], v[154:157], v[194:197], v[76:79]
	v_mfma_f32_16x16x32_bf16 v[72:75], v[162:165], v[194:197], v[72:75]
	v_mfma_f32_16x16x32_bf16 v[116:119], v[198:201], v[166:169], v[116:119]
	v_mfma_f32_16x16x32_bf16 v[112:115], v[206:209], v[166:169], v[112:115]
	v_mfma_f32_16x16x32_bf16 v[100:103], v[198:201], v[174:177], v[100:103]
	v_mfma_f32_16x16x32_bf16 v[96:99], v[206:209], v[174:177], v[96:99]
	v_mfma_f32_16x16x32_bf16 v[84:87], v[198:201], v[182:185], v[84:87]
	v_mfma_f32_16x16x32_bf16 v[80:83], v[206:209], v[182:185], v[80:83]
	v_mfma_f32_16x16x32_bf16 v[68:71], v[198:201], v[190:193], v[68:71]
	v_mfma_f32_16x16x32_bf16 v[64:67], v[206:209], v[190:193], v[64:67]
	v_mfma_f32_16x16x32_bf16 v[116:119], v[202:205], v[170:173], v[116:119]
	v_mfma_f32_16x16x32_bf16 v[112:115], v[210:213], v[170:173], v[112:115]
	v_mfma_f32_16x16x32_bf16 v[100:103], v[202:205], v[178:181], v[100:103]
	v_mfma_f32_16x16x32_bf16 v[96:99], v[210:213], v[178:181], v[96:99]
	v_mfma_f32_16x16x32_bf16 v[84:87], v[202:205], v[186:189], v[84:87]
	v_mfma_f32_16x16x32_bf16 v[80:83], v[210:213], v[186:189], v[80:83]
	v_mfma_f32_16x16x32_bf16 v[68:71], v[202:205], v[194:197], v[68:71]
	v_mfma_f32_16x16x32_bf16 v[64:67], v[210:213], v[194:197], v[64:67]
	s_barrier
	global_load_lds_dwordx4 v128, s[28:29]
	s_add_i32 m0, s67, 0x2000
	s_nop 0
	global_load_lds_dwordx4 v132, s[28:29]
	s_mov_b32 m0, s55
	v_lshl_add_u64 v[214:215], v[214:215], 0, s[10:11]
	ds_read_b128 v[166:169], v151 offset:49152
	ds_read_b128 v[170:173], v151 offset:50176
	ds_read_b128 v[174:177], v151 offset:51200
	ds_read_b128 v[178:181], v151 offset:52224
	ds_read_b128 v[182:185], v151 offset:53248
	ds_read_b128 v[186:189], v151 offset:54272
	ds_read_b128 v[190:193], v151 offset:55296
	ds_read_b128 v[194:197], v151 offset:56320
	global_load_lds_dwordx4 v[214:215], off
	v_lshl_add_u64 v[214:215], v[216:217], 0, s[10:11]
	s_mov_b32 m0, s56
	s_nop 0
	global_load_lds_dwordx4 v[214:215], off
	s_add_u32 s26, s26, 0xc000
	s_addc_u32 s27, s27, 0
	s_add_i32 s28, s68, s39
	s_mov_b32 m0, s28
	s_nop 0
	global_load_lds_dwordx4 v128, s[26:27]
	s_add_i32 m0, s28, 0x2000
	s_nop 0
	global_load_lds_dwordx4 v132, s[26:27]
	s_add_i32 s66, s66, 2
	s_add_u32 s64, s64, 0x10000
	s_addc_u32 s65, s65, 0
	s_add_u32 s24, s24, 0x100
	s_addc_u32 s25, s25, 0
	s_cmp_gt_u32 s66, 29
	s_waitcnt vmcnt(8)
	s_waitcnt lgkmcnt(0)
	s_barrier
	v_mfma_f32_16x16x32_bf16 v[60:63], v[142:145], v[166:169], v[60:63]
	v_mfma_f32_16x16x32_bf16 v[56:59], v[158:161], v[166:169], v[56:59]
	v_mfma_f32_16x16x32_bf16 v[44:47], v[142:145], v[174:177], v[44:47]
	v_mfma_f32_16x16x32_bf16 v[40:43], v[158:161], v[174:177], v[40:43]
	v_mfma_f32_16x16x32_bf16 v[28:31], v[142:145], v[182:185], v[28:31]
	v_mfma_f32_16x16x32_bf16 v[24:27], v[158:161], v[182:185], v[24:27]
	v_mfma_f32_16x16x32_bf16 v[12:15], v[142:145], v[190:193], v[12:15]
	v_mfma_f32_16x16x32_bf16 v[8:11], v[158:161], v[190:193], v[8:11]
	v_mfma_f32_16x16x32_bf16 v[60:63], v[154:157], v[170:173], v[60:63]
	v_mfma_f32_16x16x32_bf16 v[56:59], v[162:165], v[170:173], v[56:59]
	v_mfma_f32_16x16x32_bf16 v[44:47], v[154:157], v[178:181], v[44:47]
	v_mfma_f32_16x16x32_bf16 v[40:43], v[162:165], v[178:181], v[40:43]
	v_mfma_f32_16x16x32_bf16 v[28:31], v[154:157], v[186:189], v[28:31]
	v_mfma_f32_16x16x32_bf16 v[24:27], v[162:165], v[186:189], v[24:27]
	v_mfma_f32_16x16x32_bf16 v[12:15], v[154:157], v[194:197], v[12:15]
	v_mfma_f32_16x16x32_bf16 v[8:11], v[162:165], v[194:197], v[8:11]
	v_mfma_f32_16x16x32_bf16 v[52:55], v[198:201], v[166:169], v[52:55]
	v_mfma_f32_16x16x32_bf16 v[48:51], v[206:209], v[166:169], v[48:51]
	v_mfma_f32_16x16x32_bf16 v[36:39], v[198:201], v[174:177], v[36:39]
	v_mfma_f32_16x16x32_bf16 v[32:35], v[206:209], v[174:177], v[32:35]
	v_mfma_f32_16x16x32_bf16 v[20:23], v[198:201], v[182:185], v[20:23]
	v_mfma_f32_16x16x32_bf16 v[16:19], v[206:209], v[182:185], v[16:19]
	v_mfma_f32_16x16x32_bf16 v[4:7], v[198:201], v[190:193], v[4:7]
	v_mfma_f32_16x16x32_bf16 v[0:3], v[206:209], v[190:193], v[0:3]
	v_mfma_f32_16x16x32_bf16 v[52:55], v[202:205], v[170:173], v[52:55]
	v_mfma_f32_16x16x32_bf16 v[48:51], v[210:213], v[170:173], v[48:51]
	v_mfma_f32_16x16x32_bf16 v[36:39], v[202:205], v[178:181], v[36:39]
	v_mfma_f32_16x16x32_bf16 v[32:35], v[210:213], v[178:181], v[32:35]
	s_cbranch_scc1 .Lunit_exit_3
	v_mfma_f32_16x16x32_bf16 v[20:23], v[202:205], v[186:189], v[20:23]
	v_mfma_f32_16x16x32_bf16 v[16:19], v[210:213], v[186:189], v[16:19]
	v_mfma_f32_16x16x32_bf16 v[4:7], v[202:205], v[194:197], v[4:7]
	v_mfma_f32_16x16x32_bf16 v[0:3], v[210:213], v[194:197], v[0:3]
	s_barrier
	s_branch .LBB0_397

; #define PG8_STAGE(bufoff, gbase, voff) do { _Pragma("unroll") for (int _i = 0; _i < 2; ++_i) \
;         __builtin_amdgcn_global_load_lds((const unsigned*)((const char*)(gbase) + (voff)[_i]), (PG8_LAS unsigned*)(lds + (bufoff) + ldsw + _i * 8192), 16, 0, 0); } while (0)
; #define PG8_LDA(dst, b, h) do { _Pragma("unroll") for (int m = 0; m < 4; ++m) _Pragma("unroll") for (int k = 0; k < 2; ++k) dst[m][k] = *(const PG8_LAS bf16x8*)(lds + PG8_SA(b, h) + aoff + m * 2048 + k * 1024); } while (0)
; #define PG8_LDB(dst, b, h) do { _Pragma("unroll") for (int n = 0; n < 2; ++n) _Pragma("unroll") for (int k = 0; k < 2; ++k) dst[n][k] = *(const PG8_LAS bf16x8*)(lds + PG8_SB(b, h) + boff + n * 2048 + k * 1024); } while (0)
; #define PG8_MMA(ai, bj, At, Bt) do { __builtin_amdgcn_s_setprio(1); _Pragma("unroll") for (int m = 0; m < 4; ++m) _Pragma("unroll") for (int n = 0; n < 2; ++n) _Pragma("unroll") for (int k = 0; k < 2; ++k) \
;         acc[ai][bj][m][n] = __builtin_amdgcn_mfma_f32_16x16x32_bf16(Bt[n][k], At[m][k], acc[ai][bj][m][n], 0, 0, 0); __builtin_amdgcn_s_setprio(0); } while (0)
; #define PG8_WAIT_V(n) asm volatile("s_waitcnt vmcnt(" #n ")" ::: "memory")
; #define PG8_WAIT_L(n) asm volatile("s_waitcnt lgkmcnt(" #n ")" ::: "memory")
; template <class Epi, class Sched>
; __device__ __forceinline__ void gemm_phase(PG8_LAS unsigned char* lds, const Gemm g, const Sched& S, const Epi& E) {
;     ...
;             const bool last = (t == nt - 2);
;             const char* a1 = cA + (size_t)(t + 1) * kstep;
;             const char* a2 = last ? nA : cA + (size_t)(t + 2) * kstep; const char* b2 = last ? nB : cB + (size_t)(t + 2) * kstepB;
;             const char* a3 = a2 + kstep; const char* b3 = b2 + kstepB;
;             if (last && has_next) S.a_ready(nxt);
;             PG8_LDB(B0, 0, 0); PG8_SCHED; PG8_LDA(At, 0, 0); PG8_STAGE(PG8_SA(1, 1), a1 + hstep, voffA);
;             PG8_WAIT_L(8); PG8_BAR; PG8_WAIT_L(0); PG8_MMA(0, 0, At, B0); PG8_BAR; PG8_SCHED;
;             PG8_LDB(B1, 0, 1); PG8_STAGE(PG8_SB(0, 0), b2, voffB);
;             PG8_BAR; PG8_WAIT_L(0); PG8_MMA(0, 1, At, B1); PG8_BAR;
;             PG8_LDA(At, 0, 1); PG8_STAGE(PG8_SA(0, 0), a2, voffA);
;             PG8_BAR; PG8_WAIT_L(0); PG8_MMA(1, 0, At, B0); PG8_BAR; PG8_SCHED;
;             PG8_STAGE(PG8_SB(0, 1), b2 + hstepB, voffB);
;             PG8_WAIT_V(6); PG8_BAR; PG8_MMA(1, 1, At, B1); PG8_BAR;
.Lhalf_skip_y_4:
.LBB0_613:
	v_add_u32_e32 v1, s57, v231
	ds_read_b128 v[132:135], v1
	ds_read_b128 v[136:139], v1 offset:1024
	ds_read_b128 v[140:143], v1 offset:2048
	ds_read_b128 v[144:147], v1 offset:3072
	s_add_u32 s26, s24, 0xfffc0080
	s_addc_u32 s27, s25, -1
	s_cmp_eq_u32 s63, 12
	s_cselect_b32 s29, s7, s27
	s_cselect_b32 s28, s15, s26
	s_cselect_b32 s27, s17, s62
	s_cselect_b32 s26, s19, s61
	v_lshl_add_u64 v[2:3], s[24:25], 0, v[204:205]
	s_add_i32 m0, s49, 0xc000
	ds_read_b128 v[148:151], v233
	ds_read_b128 v[152:155], v233 offset:1024
	ds_read_b128 v[156:159], v233 offset:2048
	ds_read_b128 v[160:163], v233 offset:3072
	ds_read_b128 v[164:167], v233 offset:4096
	ds_read_b128 v[168:171], v233 offset:5120
	ds_read_b128 v[172:175], v233 offset:6144
	ds_read_b128 v[176:179], v233 offset:7168
	global_load_lds_dwordx4 v[2:3], off
	v_lshl_add_u64 v[2:3], s[24:25], 0, v[206:207]
	s_add_i32 m0, s49, 0xe000
	s_nop 0
	global_load_lds_dwordx4 v[2:3], off
	s_add_i32 s64, s57, s48
	v_add_u32_e32 v1, s58, v231
	v_lshl_add_u64 v[250:251], s[26:27], 0, v[196:197]
	s_mov_b32 m0, s64
	ds_read_b128 v[180:183], v1
	ds_read_b128 v[184:187], v1 offset:1024
	ds_read_b128 v[188:191], v1 offset:2048
	ds_read_b128 v[192:195], v1 offset:3072
	s_waitcnt vmcnt(8)
	s_waitcnt lgkmcnt(0)
	s_barrier
	v_mfma_f32_16x16x32_bf16 v[2:5], v[132:135], v[148:151], v[4:7]
	v_mfma_f32_16x16x32_bf16 v[6:9], v[140:143], v[148:151], v[8:11]
	v_mfma_f32_16x16x32_bf16 v[32:35], v[132:135], v[156:159], v[32:35]
	v_mfma_f32_16x16x32_bf16 v[28:31], v[140:143], v[156:159], v[28:31]
	v_mfma_f32_16x16x32_bf16 v[24:27], v[132:135], v[164:167], v[24:27]
	v_mfma_f32_16x16x32_bf16 v[20:23], v[140:143], v[164:167], v[20:23]
	v_mfma_f32_16x16x32_bf16 v[16:19], v[132:135], v[172:175], v[16:19]
	v_mfma_f32_16x16x32_bf16 v[12:15], v[140:143], v[172:175], v[12:15]
	v_mfma_f32_16x16x32_bf16 v[2:5], v[136:139], v[152:155], v[2:5]
	v_mfma_f32_16x16x32_bf16 v[8:11], v[144:147], v[152:155], v[6:9]
	v_mfma_f32_16x16x32_bf16 v[32:35], v[136:139], v[160:163], v[32:35]
	v_mfma_f32_16x16x32_bf16 v[28:31], v[144:147], v[160:163], v[28:31]
	v_mfma_f32_16x16x32_bf16 v[24:27], v[136:139], v[168:171], v[24:27]
	v_mfma_f32_16x16x32_bf16 v[20:23], v[144:147], v[168:171], v[20:23]
	v_mfma_f32_16x16x32_bf16 v[16:19], v[136:139], v[176:179], v[16:19]
	v_mfma_f32_16x16x32_bf16 v[12:15], v[144:147], v[176:179], v[12:15]
	v_mfma_f32_16x16x32_bf16 v[128:131], v[180:183], v[148:151], v[128:131]
	v_mfma_f32_16x16x32_bf16 v[124:127], v[188:191], v[148:151], v[124:127]
	v_mfma_f32_16x16x32_bf16 v[120:123], v[180:183], v[156:159], v[120:123]
	v_mfma_f32_16x16x32_bf16 v[116:119], v[188:191], v[156:159], v[116:119]
	v_mfma_f32_16x16x32_bf16 v[112:115], v[180:183], v[164:167], v[112:115]
	v_mfma_f32_16x16x32_bf16 v[108:111], v[188:191], v[164:167], v[108:111]
	v_mfma_f32_16x16x32_bf16 v[104:107], v[180:183], v[172:175], v[104:107]
	v_mfma_f32_16x16x32_bf16 v[100:103], v[188:191], v[172:175], v[100:103]
	v_mfma_f32_16x16x32_bf16 v[128:131], v[184:187], v[152:155], v[128:131]
	v_mfma_f32_16x16x32_bf16 v[124:127], v[192:195], v[152:155], v[124:127]
	v_mfma_f32_16x16x32_bf16 v[120:123], v[184:187], v[160:163], v[120:123]
	v_mfma_f32_16x16x32_bf16 v[116:119], v[192:195], v[160:163], v[116:119]
	v_mfma_f32_16x16x32_bf16 v[112:115], v[184:187], v[168:171], v[112:115]
	v_mfma_f32_16x16x32_bf16 v[108:111], v[192:195], v[168:171], v[108:111]
	v_mfma_f32_16x16x32_bf16 v[104:107], v[184:187], v[176:179], v[104:107]
	v_mfma_f32_16x16x32_bf16 v[100:103], v[192:195], v[176:179], v[100:103]
	s_barrier
	global_load_lds_dwordx4 v[250:251], off
	v_lshl_add_u64 v[250:251], s[26:27], 0, v[200:201]
	s_add_i32 m0, s64, 0x2000
	s_nop 0
	global_load_lds_dwordx4 v[250:251], off
	s_mov_b32 m0, s49
	v_lshl_add_u64 v[212:213], s[28:29], 0, v[198:199]
	ds_read_b128 v[148:151], v233 offset:16384
	ds_read_b128 v[152:155], v233 offset:17408
	ds_read_b128 v[156:159], v233 offset:18432
	ds_read_b128 v[160:163], v233 offset:19456
	ds_read_b128 v[164:167], v233 offset:20480
	ds_read_b128 v[168:171], v233 offset:21504
	ds_read_b128 v[172:175], v233 offset:22528
	ds_read_b128 v[176:179], v233 offset:23552
	global_load_lds_dwordx4 v[212:213], off
	v_lshl_add_u64 v[214:215], s[28:29], 0, v[202:203]
	s_mov_b32 m0, s50
	s_nop 0
	global_load_lds_dwordx4 v[214:215], off
	s_add_u32 s64, s26, 0x4000
	s_addc_u32 s65, s27, 0
	s_add_i32 s66, s58, s48
	v_lshl_add_u64 v[6:7], s[64:65], 0, v[196:197]
	s_mov_b32 m0, s66
	s_nop 0
	global_load_lds_dwordx4 v[6:7], off
	v_lshl_add_u64 v[6:7], s[64:65], 0, v[200:201]
	s_add_i32 m0, s66, 0x2000
	s_nop 0
	global_load_lds_dwordx4 v[6:7], off
	s_waitcnt vmcnt(8)
	s_waitcnt lgkmcnt(0)
	s_barrier
; #define PG8_STAGE(bufoff, gbase, voff) do { _Pragma("unroll") for (int _i = 0; _i < 2; ++_i) \
;         __builtin_amdgcn_global_load_lds((const unsigned*)((const char*)(gbase) + (voff)[_i]), (PG8_LAS unsigned*)(lds + (bufoff) + ldsw + _i * 8192), 16, 0, 0); } while (0)
; #define PG8_LDA(dst, b, h) do { _Pragma("unroll") for (int m = 0; m < 4; ++m) _Pragma("unroll") for (int k = 0; k < 2; ++k) dst[m][k] = *(const PG8_LAS bf16x8*)(lds + PG8_SA(b, h) + aoff + m * 2048 + k * 1024); } while (0)
; #define PG8_LDB(dst, b, h) do { _Pragma("unroll") for (int n = 0; n < 2; ++n) _Pragma("unroll") for (int k = 0; k < 2; ++k) dst[n][k] = *(const PG8_LAS bf16x8*)(lds + PG8_SB(b, h) + boff + n * 2048 + k * 1024); } while (0)
; #define PG8_MMA(ai, bj, At, Bt) do { __builtin_amdgcn_s_setprio(1); _Pragma("unroll") for (int m = 0; m < 4; ++m) _Pragma("unroll") for (int n = 0; n < 2; ++n) _Pragma("unroll") for (int k = 0; k < 2; ++k) \
;         acc[ai][bj][m][n] = __builtin_amdgcn_mfma_f32_16x16x32_bf16(Bt[n][k], At[m][k], acc[ai][bj][m][n], 0, 0, 0); __builtin_amdgcn_s_setprio(0); } while (0)
; #define PG8_WAIT_V(n) asm volatile("s_waitcnt vmcnt(" #n ")" ::: "memory")
; #define PG8_WAIT_L(n) asm volatile("s_waitcnt lgkmcnt(" #n ")" ::: "memory")
; #define PG8_BAR __builtin_amdgcn_s_barrier()
; #define PG8_SCHED __builtin_amdgcn_sched_barrier(0)
; template <class Epi, class Sched>
; __device__ __forceinline__ void gemm_phase(PG8_LAS unsigned char* lds, const Gemm g, const Sched& S, const Epi& E) {
;     ...
;             PG8_WAIT_V(6); PG8_BAR; PG8_MMA(1, 1, At, B1); PG8_BAR;
;             PG8_LDB(B0, 1, 0); PG8_SCHED; PG8_LDA(At, 1, 0); PG8_STAGE(PG8_SA(0, 1), a2 + hstep, voffA);
;             PG8_WAIT_L(8); PG8_BAR; PG8_WAIT_L(0); PG8_MMA(0, 0, At, B0); PG8_BAR; PG8_SCHED;
;             PG8_LDB(B1, 1, 1); PG8_STAGE(PG8_SB(1, 0), b3, voffB);
;             PG8_BAR; PG8_WAIT_L(0); PG8_MMA(0, 1, At, B1); PG8_BAR;
	v_mfma_f32_16x16x32_bf16 v[96:99], v[132:135], v[148:151], v[96:99]
	v_mfma_f32_16x16x32_bf16 v[92:95], v[140:143], v[148:151], v[92:95]
	v_mfma_f32_16x16x32_bf16 v[88:91], v[132:135], v[156:159], v[88:91]
	v_mfma_f32_16x16x32_bf16 v[84:87], v[140:143], v[156:159], v[84:87]
	v_mfma_f32_16x16x32_bf16 v[80:83], v[132:135], v[164:167], v[80:83]
	v_mfma_f32_16x16x32_bf16 v[76:79], v[140:143], v[164:167], v[76:79]
	v_mfma_f32_16x16x32_bf16 v[72:75], v[132:135], v[172:175], v[72:75]
	v_mfma_f32_16x16x32_bf16 v[68:71], v[140:143], v[172:175], v[68:71]
	v_mfma_f32_16x16x32_bf16 v[96:99], v[136:139], v[152:155], v[96:99]
	v_mfma_f32_16x16x32_bf16 v[92:95], v[144:147], v[152:155], v[92:95]
	v_mfma_f32_16x16x32_bf16 v[88:91], v[136:139], v[160:163], v[88:91]
	v_mfma_f32_16x16x32_bf16 v[84:87], v[144:147], v[160:163], v[84:87]
	v_mfma_f32_16x16x32_bf16 v[80:83], v[136:139], v[168:171], v[80:83]
	v_mfma_f32_16x16x32_bf16 v[76:79], v[144:147], v[168:171], v[76:79]
	v_mfma_f32_16x16x32_bf16 v[72:75], v[136:139], v[176:179], v[72:75]
	v_mfma_f32_16x16x32_bf16 v[68:71], v[144:147], v[176:179], v[68:71]
	v_mfma_f32_16x16x32_bf16 v[64:67], v[180:183], v[148:151], v[64:67]
	v_mfma_f32_16x16x32_bf16 v[60:63], v[188:191], v[148:151], v[60:63]
	v_mfma_f32_16x16x32_bf16 v[56:59], v[180:183], v[156:159], v[56:59]
	v_mfma_f32_16x16x32_bf16 v[52:55], v[188:191], v[156:159], v[52:55]
	v_mfma_f32_16x16x32_bf16 v[48:51], v[180:183], v[164:167], v[48:51]
	v_mfma_f32_16x16x32_bf16 v[44:47], v[188:191], v[164:167], v[44:47]
	v_mfma_f32_16x16x32_bf16 v[40:43], v[180:183], v[172:175], v[40:43]
	v_mfma_f32_16x16x32_bf16 v[36:39], v[188:191], v[172:175], v[36:39]
	v_mfma_f32_16x16x32_bf16 v[64:67], v[184:187], v[152:155], v[64:67]
	v_mfma_f32_16x16x32_bf16 v[60:63], v[192:195], v[152:155], v[60:63]
	v_mfma_f32_16x16x32_bf16 v[56:59], v[184:187], v[160:163], v[56:59]
	v_mfma_f32_16x16x32_bf16 v[52:55], v[192:195], v[160:163], v[52:55]
	v_mfma_f32_16x16x32_bf16 v[48:51], v[184:187], v[168:171], v[48:51]
	v_mfma_f32_16x16x32_bf16 v[44:47], v[192:195], v[168:171], v[44:47]
	v_mfma_f32_16x16x32_bf16 v[40:43], v[184:187], v[176:179], v[40:43]
	v_mfma_f32_16x16x32_bf16 v[36:39], v[192:195], v[176:179], v[36:39]
	s_barrier
	s_add_i32 s64, 0, 0x18000
	v_add_u32_e32 v1, s64, v231
	ds_read_b128 v[132:135], v1
	ds_read_b128 v[136:139], v1 offset:1024
	ds_read_b128 v[140:143], v1 offset:2048
	ds_read_b128 v[144:147], v1 offset:3072
	s_add_u32 s28, s28, 0x40000
	s_addc_u32 s29, s29, 0
	s_mov_b32 m0, s51
	v_lshl_add_u64 v[6:7], s[28:29], 0, v[198:199]
	ds_read_b128 v[148:151], v233 offset:32768
	ds_read_b128 v[152:155], v233 offset:33792
	ds_read_b128 v[156:159], v233 offset:34816
	ds_read_b128 v[160:163], v233 offset:35840
	ds_read_b128 v[164:167], v233 offset:36864
	ds_read_b128 v[168:171], v233 offset:37888
	ds_read_b128 v[172:175], v233 offset:38912
	ds_read_b128 v[176:179], v233 offset:39936
	global_load_lds_dwordx4 v[6:7], off
	v_lshl_add_u64 v[6:7], s[28:29], 0, v[202:203]
	s_mov_b32 m0, s52
	s_nop 0
	global_load_lds_dwordx4 v[6:7], off
	s_add_i32 s65, 0, 0x1c000
	s_add_u32 s28, s26, 0x8000
	s_addc_u32 s29, s27, 0
	s_add_i32 s64, s64, s48
	v_add_u32_e32 v1, s65, v231
	v_lshl_add_u64 v[252:253], s[28:29], 0, v[196:197]
	s_mov_b32 m0, s64
	ds_read_b128 v[180:183], v1
	ds_read_b128 v[184:187], v1 offset:1024
	ds_read_b128 v[188:191], v1 offset:2048
	ds_read_b128 v[192:195], v1 offset:3072
	s_waitcnt vmcnt(8)
	s_waitcnt lgkmcnt(0)
	s_barrier
	v_mfma_f32_16x16x32_bf16 v[2:5], v[132:135], v[148:151], v[2:5]
	v_mfma_f32_16x16x32_bf16 v[8:11], v[140:143], v[148:151], v[8:11]
	v_mfma_f32_16x16x32_bf16 v[32:35], v[132:135], v[156:159], v[32:35]
	v_mfma_f32_16x16x32_bf16 v[28:31], v[140:143], v[156:159], v[28:31]
	v_mfma_f32_16x16x32_bf16 v[24:27], v[132:135], v[164:167], v[24:27]
	v_mfma_f32_16x16x32_bf16 v[20:23], v[140:143], v[164:167], v[20:23]
	v_mfma_f32_16x16x32_bf16 v[16:19], v[132:135], v[172:175], v[16:19]
	v_mfma_f32_16x16x32_bf16 v[12:15], v[140:143], v[172:175], v[12:15]
	v_mfma_f32_16x16x32_bf16 v[4:7], v[136:139], v[152:155], v[2:5]
	v_mfma_f32_16x16x32_bf16 v[8:11], v[144:147], v[152:155], v[8:11]
	v_mfma_f32_16x16x32_bf16 v[32:35], v[136:139], v[160:163], v[32:35]
	v_mfma_f32_16x16x32_bf16 v[28:31], v[144:147], v[160:163], v[28:31]
	v_mfma_f32_16x16x32_bf16 v[24:27], v[136:139], v[168:171], v[24:27]
	v_mfma_f32_16x16x32_bf16 v[20:23], v[144:147], v[168:171], v[20:23]
	v_mfma_f32_16x16x32_bf16 v[16:19], v[136:139], v[176:179], v[16:19]
	v_mfma_f32_16x16x32_bf16 v[12:15], v[144:147], v[176:179], v[12:15]
	v_mfma_f32_16x16x32_bf16 v[128:131], v[180:183], v[148:151], v[128:131]
	v_mfma_f32_16x16x32_bf16 v[124:127], v[188:191], v[148:151], v[124:127]
	v_mfma_f32_16x16x32_bf16 v[120:123], v[180:183], v[156:159], v[120:123]
	v_mfma_f32_16x16x32_bf16 v[116:119], v[188:191], v[156:159], v[116:119]
	v_mfma_f32_16x16x32_bf16 v[112:115], v[180:183], v[164:167], v[112:115]
	v_mfma_f32_16x16x32_bf16 v[108:111], v[188:191], v[164:167], v[108:111]
	v_mfma_f32_16x16x32_bf16 v[104:107], v[180:183], v[172:175], v[104:107]
	v_mfma_f32_16x16x32_bf16 v[100:103], v[188:191], v[172:175], v[100:103]
	v_mfma_f32_16x16x32_bf16 v[128:131], v[184:187], v[152:155], v[128:131]
	v_mfma_f32_16x16x32_bf16 v[124:127], v[192:195], v[152:155], v[124:127]
	v_mfma_f32_16x16x32_bf16 v[120:123], v[184:187], v[160:163], v[120:123]
	v_mfma_f32_16x16x32_bf16 v[116:119], v[192:195], v[160:163], v[116:119]
	v_mfma_f32_16x16x32_bf16 v[112:115], v[184:187], v[168:171], v[112:115]
	v_mfma_f32_16x16x32_bf16 v[108:111], v[192:195], v[168:171], v[108:111]
	v_mfma_f32_16x16x32_bf16 v[104:107], v[184:187], v[176:179], v[104:107]
	v_mfma_f32_16x16x32_bf16 v[100:103], v[192:195], v[176:179], v[100:103]
	s_barrier
; #define PG8_STAGE(bufoff, gbase, voff) do { _Pragma("unroll") for (int _i = 0; _i < 2; ++_i) \
;         __builtin_amdgcn_global_load_lds((const unsigned*)((const char*)(gbase) + (voff)[_i]), (PG8_LAS unsigned*)(lds + (bufoff) + ldsw + _i * 8192), 16, 0, 0); } while (0)
; #define PG8_LDA(dst, b, h) do { _Pragma("unroll") for (int m = 0; m < 4; ++m) _Pragma("unroll") for (int k = 0; k < 2; ++k) dst[m][k] = *(const PG8_LAS bf16x8*)(lds + PG8_SA(b, h) + aoff + m * 2048 + k * 1024); } while (0)
; #define PG8_LDB(dst, b, h) do { _Pragma("unroll") for (int n = 0; n < 2; ++n) _Pragma("unroll") for (int k = 0; k < 2; ++k) dst[n][k] = *(const PG8_LAS bf16x8*)(lds + PG8_SB(b, h) + boff + n * 2048 + k * 1024); } while (0)
; #define PG8_MMA(ai, bj, At, Bt) do { __builtin_amdgcn_s_setprio(1); _Pragma("unroll") for (int m = 0; m < 4; ++m) _Pragma("unroll") for (int n = 0; n < 2; ++n) _Pragma("unroll") for (int k = 0; k < 2; ++k) \
;         acc[ai][bj][m][n] = __builtin_amdgcn_mfma_f32_16x16x32_bf16(Bt[n][k], At[m][k], acc[ai][bj][m][n], 0, 0, 0); __builtin_amdgcn_s_setprio(0); } while (0)
; #define PG8_WAIT_V(n) asm volatile("s_waitcnt vmcnt(" #n ")" ::: "memory")
; #define PG8_WAIT_L(n) asm volatile("s_waitcnt lgkmcnt(" #n ")" ::: "memory")
; #define PG8_BAR __builtin_amdgcn_s_barrier()
; #define PG8_SCHED __builtin_amdgcn_sched_barrier(0)
; template <class Epi, class Sched>
; __device__ __forceinline__ void gemm_phase(PG8_LAS unsigned char* lds, const Gemm g, const Sched& S, const Epi& E) {
;     ...
;             PG8_LDB(B1, 1, 1); PG8_STAGE(PG8_SB(1, 0), b3, voffB);
;             PG8_BAR; PG8_WAIT_L(0); PG8_MMA(0, 1, At, B1); PG8_BAR;
;             PG8_LDA(At, 1, 1); PG8_STAGE(PG8_SA(1, 0), a3, voffA);
;             PG8_BAR; PG8_WAIT_L(0); PG8_MMA(1, 0, At, B0); PG8_BAR; PG8_SCHED;
;             PG8_STAGE(PG8_SB(1, 1), b3 + hstepB, voffB);
;             PG8_WAIT_V(6); PG8_BAR; PG8_MMA(1, 1, At, B1); PG8_BAR;
;         }
;         if constexpr (!Epi::AFTER_DRAIN) { E(acc, cur, wr, wc, fr, fq); if constexpr (Epi::IDEMP && EPI_REP > 1) { asm volatile("" ::: "memory"); E(acc, cur, wr, wc, fr, fq); } S.done(cur); }
;         if (!has_next) break;
	global_load_lds_dwordx4 v[252:253], off
	v_lshl_add_u64 v[252:253], s[28:29], 0, v[200:201]
	s_add_i32 m0, s64, 0x2000
	s_nop 0
	global_load_lds_dwordx4 v[252:253], off
	s_mov_b32 m0, s55
	v_lshl_add_u64 v[2:3], v[212:213], 0, s[12:13]
	ds_read_b128 v[148:151], v233 offset:49152
	ds_read_b128 v[152:155], v233 offset:50176
	ds_read_b128 v[156:159], v233 offset:51200
	ds_read_b128 v[160:163], v233 offset:52224
	ds_read_b128 v[164:167], v233 offset:53248
	ds_read_b128 v[168:171], v233 offset:54272
	ds_read_b128 v[172:175], v233 offset:55296
	ds_read_b128 v[176:179], v233 offset:56320
	global_load_lds_dwordx4 v[2:3], off
	v_lshl_add_u64 v[2:3], v[214:215], 0, s[12:13]
	s_mov_b32 m0, s56
	s_nop 0
	global_load_lds_dwordx4 v[2:3], off
	s_add_u32 s26, s26, 0xc000
	s_addc_u32 s27, s27, 0
	s_add_i32 s28, s65, s48
	v_lshl_add_u64 v[2:3], s[26:27], 0, v[196:197]
	s_mov_b32 m0, s28
	s_nop 0
	global_load_lds_dwordx4 v[2:3], off
	v_lshl_add_u64 v[2:3], s[26:27], 0, v[200:201]
	s_add_i32 m0, s28, 0x2000
	s_nop 0
	global_load_lds_dwordx4 v[2:3], off
	s_add_i32 s63, s63, 2
	s_add_u32 s61, s61, 0x10000
	s_addc_u32 s62, s62, 0
	s_add_u32 s24, s24, 0x100
	s_addc_u32 s25, s25, 0
	s_cmp_gt_u32 s63, 13
	s_waitcnt vmcnt(8)
	s_waitcnt lgkmcnt(0)
	s_barrier
	v_mfma_f32_16x16x32_bf16 v[96:99], v[132:135], v[148:151], v[96:99]
	v_mfma_f32_16x16x32_bf16 v[92:95], v[140:143], v[148:151], v[92:95]
	v_mfma_f32_16x16x32_bf16 v[88:91], v[132:135], v[156:159], v[88:91]
	v_mfma_f32_16x16x32_bf16 v[84:87], v[140:143], v[156:159], v[84:87]
	v_mfma_f32_16x16x32_bf16 v[80:83], v[132:135], v[164:167], v[80:83]
	v_mfma_f32_16x16x32_bf16 v[76:79], v[140:143], v[164:167], v[76:79]
	v_mfma_f32_16x16x32_bf16 v[72:75], v[132:135], v[172:175], v[72:75]
	v_mfma_f32_16x16x32_bf16 v[68:71], v[140:143], v[172:175], v[68:71]
	v_mfma_f32_16x16x32_bf16 v[96:99], v[136:139], v[152:155], v[96:99]
	v_mfma_f32_16x16x32_bf16 v[92:95], v[144:147], v[152:155], v[92:95]
	v_mfma_f32_16x16x32_bf16 v[88:91], v[136:139], v[160:163], v[88:91]
	v_mfma_f32_16x16x32_bf16 v[84:87], v[144:147], v[160:163], v[84:87]
	v_mfma_f32_16x16x32_bf16 v[80:83], v[136:139], v[168:171], v[80:83]
	v_mfma_f32_16x16x32_bf16 v[76:79], v[144:147], v[168:171], v[76:79]
	v_mfma_f32_16x16x32_bf16 v[72:75], v[136:139], v[176:179], v[72:75]
	v_mfma_f32_16x16x32_bf16 v[68:71], v[144:147], v[176:179], v[68:71]
	v_mfma_f32_16x16x32_bf16 v[64:67], v[180:183], v[148:151], v[64:67]
	v_mfma_f32_16x16x32_bf16 v[60:63], v[188:191], v[148:151], v[60:63]
	v_mfma_f32_16x16x32_bf16 v[56:59], v[180:183], v[156:159], v[56:59]
	v_mfma_f32_16x16x32_bf16 v[52:55], v[188:191], v[156:159], v[52:55]
	v_mfma_f32_16x16x32_bf16 v[48:51], v[180:183], v[164:167], v[48:51]
	v_mfma_f32_16x16x32_bf16 v[44:47], v[188:191], v[164:167], v[44:47]
	v_mfma_f32_16x16x32_bf16 v[40:43], v[180:183], v[172:175], v[40:43]
	v_mfma_f32_16x16x32_bf16 v[36:39], v[188:191], v[172:175], v[36:39]
	v_mfma_f32_16x16x32_bf16 v[64:67], v[184:187], v[152:155], v[64:67]
	v_mfma_f32_16x16x32_bf16 v[60:63], v[192:195], v[152:155], v[60:63]
	v_mfma_f32_16x16x32_bf16 v[56:59], v[184:187], v[160:163], v[56:59]
	v_mfma_f32_16x16x32_bf16 v[52:55], v[192:195], v[160:163], v[52:55]
	s_cbranch_scc1 .Lunit_exit_4
	v_mfma_f32_16x16x32_bf16 v[48:51], v[184:187], v[168:171], v[48:51]
	v_mfma_f32_16x16x32_bf16 v[44:47], v[192:195], v[168:171], v[44:47]
	v_mfma_f32_16x16x32_bf16 v[40:43], v[184:187], v[176:179], v[40:43]
	v_mfma_f32_16x16x32_bf16 v[36:39], v[192:195], v[176:179], v[36:39]
	s_barrier
	s_branch .LBB0_613
.Lunit_exit_4:
	v_mfma_f32_16x16x32_bf16 v[48:51], v[184:187], v[168:171], v[48:51]
	v_mfma_f32_16x16x32_bf16 v[44:47], v[192:195], v[168:171], v[44:47]
	v_mfma_f32_16x16x32_bf16 v[40:43], v[184:187], v[176:179], v[40:43]
	v_mfma_f32_16x16x32_bf16 v[36:39], v[192:195], v[176:179], v[36:39]
	s_cmp_eq_u32 s78, 1
	s_cbranch_scc1 .Lunit_skipb_4
	s_barrier

; #define PG8_STAGE(bufoff, gbase, voff) do { _Pragma("unroll") for (int _i = 0; _i < 2; ++_i) \
;         __builtin_amdgcn_global_load_lds((const unsigned*)((const char*)(gbase) + (voff)[_i]), (PG8_LAS unsigned*)(lds + (bufoff) + ldsw + _i * 8192), 16, 0, 0); } while (0)
; #define PG8_LDA(dst, b, h) do { _Pragma("unroll") for (int m = 0; m < 4; ++m) _Pragma("unroll") for (int k = 0; k < 2; ++k) dst[m][k] = *(const PG8_LAS bf16x8*)(lds + PG8_SA(b, h) + aoff + m * 2048 + k * 1024); } while (0)
; #define PG8_LDB(dst, b, h) do { _Pragma("unroll") for (int n = 0; n < 2; ++n) _Pragma("unroll") for (int k = 0; k < 2; ++k) dst[n][k] = *(const PG8_LAS bf16x8*)(lds + PG8_SB(b, h) + boff + n * 2048 + k * 1024); } while (0)
; #define PG8_MMA(ai, bj, At, Bt) do { __builtin_amdgcn_s_setprio(1); _Pragma("unroll") for (int m = 0; m < 4; ++m) _Pragma("unroll") for (int n = 0; n < 2; ++n) _Pragma("unroll") for (int k = 0; k < 2; ++k) \
;         acc[ai][bj][m][n] = __builtin_amdgcn_mfma_f32_16x16x32_bf16(Bt[n][k], At[m][k], acc[ai][bj][m][n], 0, 0, 0); __builtin_amdgcn_s_setprio(0); } while (0)
; #define PG8_WAIT_V(n) asm volatile("s_waitcnt vmcnt(" #n ")" ::: "memory")
; #define PG8_WAIT_L(n) asm volatile("s_waitcnt lgkmcnt(" #n ")" ::: "memory")
; template <class Epi, class Sched>
; __device__ __forceinline__ void gemm_phase(PG8_LAS unsigned char* lds, const Gemm g, const Sched& S, const Epi& E) {
;     ...
;             const bool last = (t == nt - 2);
;             const char* a1 = cA + (size_t)(t + 1) * kstep;
;             const char* a2 = last ? nA : cA + (size_t)(t + 2) * kstep; const char* b2 = last ? nB : cB + (size_t)(t + 2) * kstepB;
;             const char* a3 = a2 + kstep; const char* b3 = b2 + kstepB;
;             if (last && has_next) S.a_ready(nxt);
;             PG8_LDB(B0, 0, 0); PG8_SCHED; PG8_LDA(At, 0, 0); PG8_STAGE(PG8_SA(1, 1), a1 + hstep, voffA);
;             PG8_WAIT_L(8); PG8_BAR; PG8_WAIT_L(0); PG8_MMA(0, 0, At, B0); PG8_BAR; PG8_SCHED;
;             PG8_LDB(B1, 0, 1); PG8_STAGE(PG8_SB(0, 0), b2, voffB);
;             PG8_BAR; PG8_WAIT_L(0); PG8_MMA(0, 1, At, B1); PG8_BAR;
;             PG8_LDA(At, 0, 1); PG8_STAGE(PG8_SA(0, 0), a2, voffA);
;             PG8_BAR; PG8_WAIT_L(0); PG8_MMA(1, 0, At, B0); PG8_BAR; PG8_SCHED;
;             PG8_STAGE(PG8_SB(0, 1), b2 + hstepB, voffB);
;             PG8_WAIT_V(6); PG8_BAR; PG8_MMA(1, 1, At, B1); PG8_BAR;
.Lhalf_skip_y_5:
.LBB0_783:
	ds_read_b128 v[128:131], v197
	ds_read_b128 v[132:135], v197 offset:1024
	ds_read_b128 v[136:139], v197 offset:2048
	ds_read_b128 v[140:143], v197 offset:3072
	s_add_u32 s30, s28, 0x100
	s_addc_u32 s31, s29, 0
	s_cmp_eq_u32 s69, 28
	s_cselect_b32 s39, s19, s31
	s_cselect_b32 s38, s65, s30
	s_cselect_b32 s37, s21, s68
	s_cselect_b32 s36, s66, s67
	v_lshl_add_u64 v[192:193], s[28:29], 0, v[172:173]
	s_add_i32 m0, s27, 0xc000
	ds_read_b128 v[144:147], v198
	ds_read_b128 v[148:151], v198 offset:1024
	ds_read_b128 v[152:155], v198 offset:2048
	ds_read_b128 v[156:159], v198 offset:3072
	ds_read_b128 v[160:163], v198 offset:4096
	ds_read_b128 v[180:183], v198 offset:5120
	ds_read_b128 v[184:187], v198 offset:6144
	ds_read_b128 v[188:191], v198 offset:7168
	global_load_lds_dwordx4 v[192:193], off
	v_lshl_add_u64 v[192:193], s[28:29], 0, v[174:175]
	s_add_i32 m0, s27, 0xe000
	s_nop 0
	global_load_lds_dwordx4 v[192:193], off
	s_add_i32 s28, s62, s54
	s_mov_b32 m0, s28
	ds_read_b128 v[200:203], v199
	ds_read_b128 v[204:207], v199 offset:1024
	ds_read_b128 v[208:211], v199 offset:2048
	ds_read_b128 v[212:215], v199 offset:3072
	s_waitcnt vmcnt(8)
	s_waitcnt lgkmcnt(0)
	s_barrier
	v_mfma_f32_16x16x32_bf16 v[124:127], v[128:131], v[144:147], v[124:127]
	v_mfma_f32_16x16x32_bf16 v[120:123], v[136:139], v[144:147], v[120:123]
	v_mfma_f32_16x16x32_bf16 v[116:119], v[128:131], v[152:155], v[116:119]
	v_mfma_f32_16x16x32_bf16 v[104:107], v[136:139], v[152:155], v[104:107]
	v_mfma_f32_16x16x32_bf16 v[92:95], v[128:131], v[160:163], v[92:95]
	v_mfma_f32_16x16x32_bf16 v[88:91], v[136:139], v[160:163], v[88:91]
	v_mfma_f32_16x16x32_bf16 v[76:79], v[128:131], v[184:187], v[76:79]
	v_mfma_f32_16x16x32_bf16 v[72:75], v[136:139], v[184:187], v[72:75]
	v_mfma_f32_16x16x32_bf16 v[124:127], v[132:135], v[148:151], v[124:127]
	v_mfma_f32_16x16x32_bf16 v[120:123], v[140:143], v[148:151], v[120:123]
	v_mfma_f32_16x16x32_bf16 v[116:119], v[132:135], v[156:159], v[116:119]
	v_mfma_f32_16x16x32_bf16 v[104:107], v[140:143], v[156:159], v[104:107]
	v_mfma_f32_16x16x32_bf16 v[92:95], v[132:135], v[180:183], v[92:95]
	v_mfma_f32_16x16x32_bf16 v[88:91], v[140:143], v[180:183], v[88:91]
	v_mfma_f32_16x16x32_bf16 v[76:79], v[132:135], v[188:191], v[76:79]
	v_mfma_f32_16x16x32_bf16 v[72:75], v[140:143], v[188:191], v[72:75]
	v_mfma_f32_16x16x32_bf16 v[112:115], v[200:203], v[144:147], v[112:115]
	v_mfma_f32_16x16x32_bf16 v[108:111], v[208:211], v[144:147], v[108:111]
	v_mfma_f32_16x16x32_bf16 v[100:103], v[200:203], v[152:155], v[100:103]
	v_mfma_f32_16x16x32_bf16 v[96:99], v[208:211], v[152:155], v[96:99]
	v_mfma_f32_16x16x32_bf16 v[84:87], v[200:203], v[160:163], v[84:87]
	v_mfma_f32_16x16x32_bf16 v[80:83], v[208:211], v[160:163], v[80:83]
	v_mfma_f32_16x16x32_bf16 v[68:71], v[200:203], v[184:187], v[68:71]
	v_mfma_f32_16x16x32_bf16 v[64:67], v[208:211], v[184:187], v[64:67]
	v_mfma_f32_16x16x32_bf16 v[112:115], v[204:207], v[148:151], v[112:115]
	v_mfma_f32_16x16x32_bf16 v[108:111], v[212:215], v[148:151], v[108:111]
	v_mfma_f32_16x16x32_bf16 v[100:103], v[204:207], v[156:159], v[100:103]
	v_mfma_f32_16x16x32_bf16 v[96:99], v[212:215], v[156:159], v[96:99]
	v_mfma_f32_16x16x32_bf16 v[84:87], v[204:207], v[180:183], v[84:87]
	v_mfma_f32_16x16x32_bf16 v[80:83], v[212:215], v[180:183], v[80:83]
	v_mfma_f32_16x16x32_bf16 v[68:71], v[204:207], v[188:191], v[68:71]
	v_mfma_f32_16x16x32_bf16 v[64:67], v[212:215], v[188:191], v[64:67]
	s_barrier
	global_load_lds_dwordx4 v164, s[36:37]
	s_add_i32 m0, s28, 0x2000
	s_nop 0
	global_load_lds_dwordx4 v168, s[36:37]
	s_mov_b32 m0, s27
	v_lshl_add_u64 v[192:193], s[38:39], 0, v[166:167]
	ds_read_b128 v[144:147], v198 offset:16384
	ds_read_b128 v[148:151], v198 offset:17408
	ds_read_b128 v[152:155], v198 offset:18432
	ds_read_b128 v[156:159], v198 offset:19456
	ds_read_b128 v[160:163], v198 offset:20480
	ds_read_b128 v[180:183], v198 offset:21504
	ds_read_b128 v[184:187], v198 offset:22528
	ds_read_b128 v[188:191], v198 offset:23552
	global_load_lds_dwordx4 v[192:193], off
	v_lshl_add_u64 v[216:217], s[38:39], 0, v[170:171]
	s_mov_b32 m0, s55
	s_nop 0
	global_load_lds_dwordx4 v[216:217], off
	s_add_u32 s28, s36, 0x4000
	s_addc_u32 s29, s37, 0
	s_add_i32 s70, s63, s54
	s_mov_b32 m0, s70
	s_nop 0
	global_load_lds_dwordx4 v164, s[28:29]
	s_add_i32 m0, s70, 0x2000
	s_nop 0
	global_load_lds_dwordx4 v168, s[28:29]
	s_waitcnt vmcnt(8)
	s_waitcnt lgkmcnt(0)
	s_barrier
	v_mfma_f32_16x16x32_bf16 v[60:63], v[128:131], v[144:147], v[60:63]
	v_mfma_f32_16x16x32_bf16 v[56:59], v[136:139], v[144:147], v[56:59]
	v_mfma_f32_16x16x32_bf16 v[44:47], v[128:131], v[152:155], v[44:47]
	v_mfma_f32_16x16x32_bf16 v[40:43], v[136:139], v[152:155], v[40:43]
	v_mfma_f32_16x16x32_bf16 v[28:31], v[128:131], v[160:163], v[28:31]
	v_mfma_f32_16x16x32_bf16 v[24:27], v[136:139], v[160:163], v[24:27]
	v_mfma_f32_16x16x32_bf16 v[12:15], v[128:131], v[184:187], v[12:15]
	v_mfma_f32_16x16x32_bf16 v[8:11], v[136:139], v[184:187], v[8:11]
	v_mfma_f32_16x16x32_bf16 v[60:63], v[132:135], v[148:151], v[60:63]
	v_mfma_f32_16x16x32_bf16 v[56:59], v[140:143], v[148:151], v[56:59]
	v_mfma_f32_16x16x32_bf16 v[44:47], v[132:135], v[156:159], v[44:47]
	v_mfma_f32_16x16x32_bf16 v[40:43], v[140:143], v[156:159], v[40:43]
	v_mfma_f32_16x16x32_bf16 v[28:31], v[132:135], v[180:183], v[28:31]
	v_mfma_f32_16x16x32_bf16 v[24:27], v[140:143], v[180:183], v[24:27]
	v_mfma_f32_16x16x32_bf16 v[12:15], v[132:135], v[188:191], v[12:15]
	v_mfma_f32_16x16x32_bf16 v[8:11], v[140:143], v[188:191], v[8:11]
	v_mfma_f32_16x16x32_bf16 v[52:55], v[200:203], v[144:147], v[52:55]
	v_mfma_f32_16x16x32_bf16 v[48:51], v[208:211], v[144:147], v[48:51]
	v_mfma_f32_16x16x32_bf16 v[36:39], v[200:203], v[152:155], v[36:39]
	v_mfma_f32_16x16x32_bf16 v[32:35], v[208:211], v[152:155], v[32:35]
	v_mfma_f32_16x16x32_bf16 v[20:23], v[200:203], v[160:163], v[20:23]
	v_mfma_f32_16x16x32_bf16 v[16:19], v[208:211], v[160:163], v[16:19]
	v_mfma_f32_16x16x32_bf16 v[4:7], v[200:203], v[184:187], v[4:7]
	v_mfma_f32_16x16x32_bf16 v[0:3], v[208:211], v[184:187], v[0:3]
	v_mfma_f32_16x16x32_bf16 v[52:55], v[204:207], v[148:151], v[52:55]
	v_mfma_f32_16x16x32_bf16 v[48:51], v[212:215], v[148:151], v[48:51]
	v_mfma_f32_16x16x32_bf16 v[36:39], v[204:207], v[156:159], v[36:39]
	v_mfma_f32_16x16x32_bf16 v[32:35], v[212:215], v[156:159], v[32:35]
	v_mfma_f32_16x16x32_bf16 v[20:23], v[204:207], v[180:183], v[20:23]
	v_mfma_f32_16x16x32_bf16 v[16:19], v[212:215], v[180:183], v[16:19]
	v_mfma_f32_16x16x32_bf16 v[4:7], v[204:207], v[188:191], v[4:7]
	v_mfma_f32_16x16x32_bf16 v[0:3], v[212:215], v[188:191], v[0:3]
	s_barrier
; #define PG8_STAGE(bufoff, gbase, voff) do { _Pragma("unroll") for (int _i = 0; _i < 2; ++_i) \
;         __builtin_amdgcn_global_load_lds((const unsigned*)((const char*)(gbase) + (voff)[_i]), (PG8_LAS unsigned*)(lds + (bufoff) + ldsw + _i * 8192), 16, 0, 0); } while (0)
; #define PG8_LDA(dst, b, h) do { _Pragma("unroll") for (int m = 0; m < 4; ++m) _Pragma("unroll") for (int k = 0; k < 2; ++k) dst[m][k] = *(const PG8_LAS bf16x8*)(lds + PG8_SA(b, h) + aoff + m * 2048 + k * 1024); } while (0)
; #define PG8_LDB(dst, b, h) do { _Pragma("unroll") for (int n = 0; n < 2; ++n) _Pragma("unroll") for (int k = 0; k < 2; ++k) dst[n][k] = *(const PG8_LAS bf16x8*)(lds + PG8_SB(b, h) + boff + n * 2048 + k * 1024); } while (0)
; #define PG8_MMA(ai, bj, At, Bt) do { __builtin_amdgcn_s_setprio(1); _Pragma("unroll") for (int m = 0; m < 4; ++m) _Pragma("unroll") for (int n = 0; n < 2; ++n) _Pragma("unroll") for (int k = 0; k < 2; ++k) \
;         acc[ai][bj][m][n] = __builtin_amdgcn_mfma_f32_16x16x32_bf16(Bt[n][k], At[m][k], acc[ai][bj][m][n], 0, 0, 0); __builtin_amdgcn_s_setprio(0); } while (0)
; #define PG8_WAIT_V(n) asm volatile("s_waitcnt vmcnt(" #n ")" ::: "memory")
; #define PG8_WAIT_L(n) asm volatile("s_waitcnt lgkmcnt(" #n ")" ::: "memory")
; #define PG8_BAR __builtin_amdgcn_s_barrier()
; #define PG8_SCHED __builtin_amdgcn_sched_barrier(0)
; template <class Epi, class Sched>
; __device__ __forceinline__ void gemm_phase(PG8_LAS unsigned char* lds, const Gemm g, const Sched& S, const Epi& E) {
;     ...
;             PG8_LDB(B0, 1, 0); PG8_SCHED; PG8_LDA(At, 1, 0); PG8_STAGE(PG8_SA(0, 1), a2 + hstep, voffA);
;             PG8_WAIT_L(8); PG8_BAR; PG8_WAIT_L(0); PG8_MMA(0, 0, At, B0); PG8_BAR; PG8_SCHED;
;             PG8_LDB(B1, 1, 1); PG8_STAGE(PG8_SB(1, 0), b3, voffB);
;             PG8_BAR; PG8_WAIT_L(0); PG8_MMA(0, 1, At, B1); PG8_BAR;
;             PG8_LDA(At, 1, 1); PG8_STAGE(PG8_SA(1, 0), a3, voffA);
;             PG8_BAR; PG8_WAIT_L(0); PG8_MMA(1, 0, At, B0); PG8_BAR; PG8_SCHED;
;             PG8_STAGE(PG8_SB(1, 1), b3 + hstepB, voffB);
;             PG8_WAIT_V(6); PG8_BAR; PG8_MMA(1, 1, At, B1); PG8_BAR;
	s_add_i32 s70, 0, 0x18000
	v_add_u32_e32 v140, s70, v195
	ds_read_b128 v[128:131], v140
	ds_read_b128 v[132:135], v140 offset:1024
	ds_read_b128 v[136:139], v140 offset:2048
	ds_read_b128 v[140:143], v140 offset:3072
	s_add_u32 s28, s38, 0x80000
	s_addc_u32 s29, s39, 0
	s_mov_b32 m0, s56
	ds_read_b128 v[144:147], v198 offset:32768
	ds_read_b128 v[148:151], v198 offset:33792
	ds_read_b128 v[152:155], v198 offset:34816
	ds_read_b128 v[156:159], v198 offset:35840
	ds_read_b128 v[160:163], v198 offset:36864
	ds_read_b128 v[180:183], v198 offset:37888
	ds_read_b128 v[184:187], v198 offset:38912
	ds_read_b128 v[188:191], v198 offset:39936
	global_load_lds_dwordx4 v166, s[28:29]
	s_mov_b32 m0, s57
	s_nop 0
	global_load_lds_dwordx4 v170, s[28:29]
	s_add_i32 s38, 0, 0x1c000
	s_add_u32 s28, s36, 0x8000
	s_addc_u32 s29, s37, 0
	s_add_i32 s39, s70, s54
	v_add_u32_e32 v212, s38, v195
	s_mov_b32 m0, s39
	ds_read_b128 v[200:203], v212
	ds_read_b128 v[204:207], v212 offset:1024
	ds_read_b128 v[208:211], v212 offset:2048
	ds_read_b128 v[212:215], v212 offset:3072
	s_waitcnt vmcnt(8)
	s_waitcnt lgkmcnt(0)
	s_barrier
	v_mfma_f32_16x16x32_bf16 v[124:127], v[128:131], v[144:147], v[124:127]
	v_mfma_f32_16x16x32_bf16 v[120:123], v[136:139], v[144:147], v[120:123]
	v_mfma_f32_16x16x32_bf16 v[116:119], v[128:131], v[152:155], v[116:119]
	v_mfma_f32_16x16x32_bf16 v[104:107], v[136:139], v[152:155], v[104:107]
	v_mfma_f32_16x16x32_bf16 v[92:95], v[128:131], v[160:163], v[92:95]
	v_mfma_f32_16x16x32_bf16 v[88:91], v[136:139], v[160:163], v[88:91]
	v_mfma_f32_16x16x32_bf16 v[76:79], v[128:131], v[184:187], v[76:79]
	v_mfma_f32_16x16x32_bf16 v[72:75], v[136:139], v[184:187], v[72:75]
	v_mfma_f32_16x16x32_bf16 v[124:127], v[132:135], v[148:151], v[124:127]
	v_mfma_f32_16x16x32_bf16 v[120:123], v[140:143], v[148:151], v[120:123]
	v_mfma_f32_16x16x32_bf16 v[116:119], v[132:135], v[156:159], v[116:119]
	v_mfma_f32_16x16x32_bf16 v[104:107], v[140:143], v[156:159], v[104:107]
	v_mfma_f32_16x16x32_bf16 v[92:95], v[132:135], v[180:183], v[92:95]
	v_mfma_f32_16x16x32_bf16 v[88:91], v[140:143], v[180:183], v[88:91]
	v_mfma_f32_16x16x32_bf16 v[76:79], v[132:135], v[188:191], v[76:79]
	v_mfma_f32_16x16x32_bf16 v[72:75], v[140:143], v[188:191], v[72:75]
	v_mfma_f32_16x16x32_bf16 v[112:115], v[200:203], v[144:147], v[112:115]
	v_mfma_f32_16x16x32_bf16 v[108:111], v[208:211], v[144:147], v[108:111]
	v_mfma_f32_16x16x32_bf16 v[100:103], v[200:203], v[152:155], v[100:103]
	v_mfma_f32_16x16x32_bf16 v[96:99], v[208:211], v[152:155], v[96:99]
	v_mfma_f32_16x16x32_bf16 v[84:87], v[200:203], v[160:163], v[84:87]
	v_mfma_f32_16x16x32_bf16 v[80:83], v[208:211], v[160:163], v[80:83]
	v_mfma_f32_16x16x32_bf16 v[68:71], v[200:203], v[184:187], v[68:71]
	v_mfma_f32_16x16x32_bf16 v[64:67], v[208:211], v[184:187], v[64:67]
	v_mfma_f32_16x16x32_bf16 v[112:115], v[204:207], v[148:151], v[112:115]
	v_mfma_f32_16x16x32_bf16 v[108:111], v[212:215], v[148:151], v[108:111]
	v_mfma_f32_16x16x32_bf16 v[100:103], v[204:207], v[156:159], v[100:103]
	v_mfma_f32_16x16x32_bf16 v[96:99], v[212:215], v[156:159], v[96:99]
	v_mfma_f32_16x16x32_bf16 v[84:87], v[204:207], v[180:183], v[84:87]
	v_mfma_f32_16x16x32_bf16 v[80:83], v[212:215], v[180:183], v[80:83]
	v_mfma_f32_16x16x32_bf16 v[68:71], v[204:207], v[188:191], v[68:71]
	v_mfma_f32_16x16x32_bf16 v[64:67], v[212:215], v[188:191], v[64:67]
	s_barrier
	global_load_lds_dwordx4 v164, s[28:29]
	s_add_i32 m0, s39, 0x2000
	s_nop 0
	global_load_lds_dwordx4 v168, s[28:29]
	s_mov_b32 m0, s59
	v_lshl_add_u64 v[192:193], v[192:193], 0, s[10:11]
	ds_read_b128 v[144:147], v198 offset:49152
	ds_read_b128 v[148:151], v198 offset:50176
	ds_read_b128 v[152:155], v198 offset:51200
	ds_read_b128 v[156:159], v198 offset:52224
	ds_read_b128 v[160:163], v198 offset:53248
	ds_read_b128 v[180:183], v198 offset:54272
	ds_read_b128 v[184:187], v198 offset:55296
	ds_read_b128 v[188:191], v198 offset:56320
	global_load_lds_dwordx4 v[192:193], off
	v_lshl_add_u64 v[192:193], v[216:217], 0, s[10:11]
	s_mov_b32 m0, s60
	s_nop 0
	global_load_lds_dwordx4 v[192:193], off
	s_add_u32 s28, s36, 0xc000
	s_addc_u32 s29, s37, 0
	s_add_i32 s36, s38, s54
	s_mov_b32 m0, s36
	s_nop 0
	global_load_lds_dwordx4 v164, s[28:29]
	s_add_i32 m0, s36, 0x2000
	s_nop 0
	global_load_lds_dwordx4 v168, s[28:29]
	s_add_i32 s69, s69, 2
	s_add_u32 s67, s67, 0x10000
	s_addc_u32 s68, s68, 0
	s_cmp_gt_u32 s69, 29
	s_mov_b64 s[28:29], s[30:31]
	s_waitcnt vmcnt(8)
	s_waitcnt lgkmcnt(0)
	s_barrier
	v_mfma_f32_16x16x32_bf16 v[60:63], v[128:131], v[144:147], v[60:63]
	v_mfma_f32_16x16x32_bf16 v[56:59], v[136:139], v[144:147], v[56:59]
	v_mfma_f32_16x16x32_bf16 v[44:47], v[128:131], v[152:155], v[44:47]
	v_mfma_f32_16x16x32_bf16 v[40:43], v[136:139], v[152:155], v[40:43]
	v_mfma_f32_16x16x32_bf16 v[28:31], v[128:131], v[160:163], v[28:31]
	v_mfma_f32_16x16x32_bf16 v[24:27], v[136:139], v[160:163], v[24:27]
	v_mfma_f32_16x16x32_bf16 v[12:15], v[128:131], v[184:187], v[12:15]
	v_mfma_f32_16x16x32_bf16 v[8:11], v[136:139], v[184:187], v[8:11]
	v_mfma_f32_16x16x32_bf16 v[60:63], v[132:135], v[148:151], v[60:63]
	v_mfma_f32_16x16x32_bf16 v[56:59], v[140:143], v[148:151], v[56:59]
	v_mfma_f32_16x16x32_bf16 v[44:47], v[132:135], v[156:159], v[44:47]
	v_mfma_f32_16x16x32_bf16 v[40:43], v[140:143], v[156:159], v[40:43]
	v_mfma_f32_16x16x32_bf16 v[28:31], v[132:135], v[180:183], v[28:31]
	v_mfma_f32_16x16x32_bf16 v[24:27], v[140:143], v[180:183], v[24:27]
	v_mfma_f32_16x16x32_bf16 v[12:15], v[132:135], v[188:191], v[12:15]
	v_mfma_f32_16x16x32_bf16 v[8:11], v[140:143], v[188:191], v[8:11]
	v_mfma_f32_16x16x32_bf16 v[52:55], v[200:203], v[144:147], v[52:55]
	v_mfma_f32_16x16x32_bf16 v[48:51], v[208:211], v[144:147], v[48:51]
	v_mfma_f32_16x16x32_bf16 v[36:39], v[200:203], v[152:155], v[36:39]
	v_mfma_f32_16x16x32_bf16 v[32:35], v[208:211], v[152:155], v[32:35]
	v_mfma_f32_16x16x32_bf16 v[20:23], v[200:203], v[160:163], v[20:23]
	v_mfma_f32_16x16x32_bf16 v[16:19], v[208:211], v[160:163], v[16:19]
	v_mfma_f32_16x16x32_bf16 v[4:7], v[200:203], v[184:187], v[4:7]
	v_mfma_f32_16x16x32_bf16 v[0:3], v[208:211], v[184:187], v[0:3]
	v_mfma_f32_16x16x32_bf16 v[52:55], v[204:207], v[148:151], v[52:55]
	v_mfma_f32_16x16x32_bf16 v[48:51], v[212:215], v[148:151], v[48:51]
	v_mfma_f32_16x16x32_bf16 v[36:39], v[204:207], v[156:159], v[36:39]
	v_mfma_f32_16x16x32_bf16 v[32:35], v[212:215], v[156:159], v[32:35]
	s_cbranch_scc1 .Lunit_exit_5
	v_mfma_f32_16x16x32_bf16 v[20:23], v[204:207], v[180:183], v[20:23]
	v_mfma_f32_16x16x32_bf16 v[16:19], v[212:215], v[180:183], v[16:19]
	v_mfma_f32_16x16x32_bf16 v[4:7], v[204:207], v[188:191], v[4:7]
	v_mfma_f32_16x16x32_bf16 v[0:3], v[212:215], v[188:191], v[0:3]
	s_barrier
	s_branch .LBB0_783
; #define PG8_MMA(ai, bj, At, Bt) do { __builtin_amdgcn_s_setprio(1); _Pragma("unroll") for (int m = 0; m < 4; ++m) _Pragma("unroll") for (int n = 0; n < 2; ++n) _Pragma("unroll") for (int k = 0; k < 2; ++k) \
;         acc[ai][bj][m][n] = __builtin_amdgcn_mfma_f32_16x16x32_bf16(Bt[n][k], At[m][k], acc[ai][bj][m][n], 0, 0, 0); __builtin_amdgcn_s_setprio(0); } while (0)
; #define PG8_WAIT_V(n) asm volatile("s_waitcnt vmcnt(" #n ")" ::: "memory")
; #define PG8_BAR __builtin_amdgcn_s_barrier()
; template <class Epi, class Sched>
; __device__ __forceinline__ void gemm_phase(PG8_LAS unsigned char* lds, const Gemm g, const Sched& S, const Epi& E) {
;     ...
;             PG8_WAIT_V(6); PG8_BAR; PG8_MMA(1, 1, At, B1); PG8_BAR;
;         }
;         if constexpr (!Epi::AFTER_DRAIN) { E(acc, cur, wr, wc, fr, fq); if constexpr (Epi::IDEMP && EPI_REP > 1) { asm volatile("" ::: "memory"); E(acc, cur, wr, wc, fr, fq); } S.done(cur); }
.Lunit_exit_5:
	v_mfma_f32_16x16x32_bf16 v[20:23], v[204:207], v[180:183], v[20:23]
	v_mfma_f32_16x16x32_bf16 v[16:19], v[212:215], v[180:183], v[16:19]
	v_mfma_f32_16x16x32_bf16 v[4:7], v[204:207], v[188:191], v[4:7]
	v_mfma_f32_16x16x32_bf16 v[0:3], v[212:215], v[188:191], v[0:3]
	s_cmp_eq_u32 s78, 1
	s_cbranch_scc1 .Lunit_skipb_5
	s_barrier

; #define PG8_STAGE(bufoff, gbase, voff) do { _Pragma("unroll") for (int _i = 0; _i < 2; ++_i) \
;         __builtin_amdgcn_global_load_lds((const unsigned*)((const char*)(gbase) + (voff)[_i]), (PG8_LAS unsigned*)(lds + (bufoff) + ldsw + _i * 8192), 16, 0, 0); } while (0)
; #define PG8_LDA(dst, b, h) do { _Pragma("unroll") for (int m = 0; m < 4; ++m) _Pragma("unroll") for (int k = 0; k < 2; ++k) dst[m][k] = *(const PG8_LAS bf16x8*)(lds + PG8_SA(b, h) + aoff + m * 2048 + k * 1024); } while (0)
; #define PG8_LDB(dst, b, h) do { _Pragma("unroll") for (int n = 0; n < 2; ++n) _Pragma("unroll") for (int k = 0; k < 2; ++k) dst[n][k] = *(const PG8_LAS bf16x8*)(lds + PG8_SB(b, h) + boff + n * 2048 + k * 1024); } while (0)
; #define PG8_MMA(ai, bj, At, Bt) do { __builtin_amdgcn_s_setprio(1); _Pragma("unroll") for (int m = 0; m < 4; ++m) _Pragma("unroll") for (int n = 0; n < 2; ++n) _Pragma("unroll") for (int k = 0; k < 2; ++k) \
;         acc[ai][bj][m][n] = __builtin_amdgcn_mfma_f32_16x16x32_bf16(Bt[n][k], At[m][k], acc[ai][bj][m][n], 0, 0, 0); __builtin_amdgcn_s_setprio(0); } while (0)
; #define PG8_WAIT_V(n) asm volatile("s_waitcnt vmcnt(" #n ")" ::: "memory")
; #define PG8_WAIT_L(n) asm volatile("s_waitcnt lgkmcnt(" #n ")" ::: "memory")
; template <class Epi, class Sched>
; __device__ __forceinline__ void gemm_phase(PG8_LAS unsigned char* lds, const Gemm g, const Sched& S, const Epi& E) {
;     ...
;             const bool last = (t == nt - 2);
;             const char* a1 = cA + (size_t)(t + 1) * kstep;
;             const char* a2 = last ? nA : cA + (size_t)(t + 2) * kstep; const char* b2 = last ? nB : cB + (size_t)(t + 2) * kstepB;
;             const char* a3 = a2 + kstep; const char* b3 = b2 + kstepB;
;             if (last && has_next) S.a_ready(nxt);
;             PG8_LDB(B0, 0, 0); PG8_SCHED; PG8_LDA(At, 0, 0); PG8_STAGE(PG8_SA(1, 1), a1 + hstep, voffA);
;             PG8_WAIT_L(8); PG8_BAR; PG8_WAIT_L(0); PG8_MMA(0, 0, At, B0); PG8_BAR; PG8_SCHED;
;             PG8_LDB(B1, 0, 1); PG8_STAGE(PG8_SB(0, 0), b2, voffB);
;             PG8_BAR; PG8_WAIT_L(0); PG8_MMA(0, 1, At, B1); PG8_BAR;
;             PG8_LDA(At, 0, 1); PG8_STAGE(PG8_SA(0, 0), a2, voffA);
;             PG8_BAR; PG8_WAIT_L(0); PG8_MMA(1, 0, At, B0); PG8_BAR; PG8_SCHED;
;             PG8_STAGE(PG8_SB(0, 1), b2 + hstepB, voffB);
;             PG8_WAIT_V(6); PG8_BAR; PG8_MMA(1, 1, At, B1); PG8_BAR;
.Lhalf_skip_y_6:
.LBB0_904:
	ds_read_b128 v[152:155], v149
	ds_read_b128 v[156:159], v149 offset:1024
	ds_read_b128 v[160:163], v149 offset:2048
	ds_read_b128 v[164:167], v149 offset:3072
	s_add_u32 s22, s20, 0xfff80080
	s_addc_u32 s23, s21, -1
	s_cmp_eq_u32 s61, 28
	s_cselect_b32 s25, s11, s23
	s_cselect_b32 s24, s57, s22
	s_cselect_b32 s23, s13, s60
	s_cselect_b32 s22, s58, s59
	s_add_i32 m0, s19, 0xc000
	ds_read_b128 v[168:171], v150
	ds_read_b128 v[172:175], v150 offset:1024
	ds_read_b128 v[176:179], v150 offset:2048
	ds_read_b128 v[180:183], v150 offset:3072
	ds_read_b128 v[184:187], v150 offset:4096
	ds_read_b128 v[188:191], v150 offset:5120
	ds_read_b128 v[192:195], v150 offset:6144
	ds_read_b128 v[196:199], v150 offset:7168
	global_load_lds_dwordx4 v136, s[20:21]
	s_add_i32 m0, s19, 0xe000
	s_nop 0
	global_load_lds_dwordx4 v138, s[20:21]
	s_add_i32 s62, s53, s38
	s_mov_b32 m0, s62
	ds_read_b128 v[200:203], v151
	ds_read_b128 v[204:207], v151 offset:1024
	ds_read_b128 v[208:211], v151 offset:2048
	ds_read_b128 v[212:215], v151 offset:3072
	s_waitcnt vmcnt(8)
	s_waitcnt lgkmcnt(0)
	s_barrier
	v_mfma_f32_16x16x32_bf16 v[124:127], v[152:155], v[168:171], v[124:127]
	v_mfma_f32_16x16x32_bf16 v[120:123], v[160:163], v[168:171], v[120:123]
	v_mfma_f32_16x16x32_bf16 v[108:111], v[152:155], v[176:179], v[108:111]
	v_mfma_f32_16x16x32_bf16 v[104:107], v[160:163], v[176:179], v[104:107]
	v_mfma_f32_16x16x32_bf16 v[92:95], v[152:155], v[184:187], v[92:95]
	v_mfma_f32_16x16x32_bf16 v[88:91], v[160:163], v[184:187], v[88:91]
	v_mfma_f32_16x16x32_bf16 v[76:79], v[152:155], v[192:195], v[76:79]
	v_mfma_f32_16x16x32_bf16 v[72:75], v[160:163], v[192:195], v[72:75]
	v_mfma_f32_16x16x32_bf16 v[124:127], v[156:159], v[172:175], v[124:127]
	v_mfma_f32_16x16x32_bf16 v[120:123], v[164:167], v[172:175], v[120:123]
	v_mfma_f32_16x16x32_bf16 v[108:111], v[156:159], v[180:183], v[108:111]
	v_mfma_f32_16x16x32_bf16 v[104:107], v[164:167], v[180:183], v[104:107]
	v_mfma_f32_16x16x32_bf16 v[92:95], v[156:159], v[188:191], v[92:95]
	v_mfma_f32_16x16x32_bf16 v[88:91], v[164:167], v[188:191], v[88:91]
	v_mfma_f32_16x16x32_bf16 v[76:79], v[156:159], v[196:199], v[76:79]
	v_mfma_f32_16x16x32_bf16 v[72:75], v[164:167], v[196:199], v[72:75]
	v_mfma_f32_16x16x32_bf16 v[116:119], v[200:203], v[168:171], v[116:119]
	v_mfma_f32_16x16x32_bf16 v[112:115], v[208:211], v[168:171], v[112:115]
	v_mfma_f32_16x16x32_bf16 v[100:103], v[200:203], v[176:179], v[100:103]
	v_mfma_f32_16x16x32_bf16 v[96:99], v[208:211], v[176:179], v[96:99]
	v_mfma_f32_16x16x32_bf16 v[84:87], v[200:203], v[184:187], v[84:87]
	v_mfma_f32_16x16x32_bf16 v[80:83], v[208:211], v[184:187], v[80:83]
	v_mfma_f32_16x16x32_bf16 v[68:71], v[200:203], v[192:195], v[68:71]
	v_mfma_f32_16x16x32_bf16 v[64:67], v[208:211], v[192:195], v[64:67]
	v_mfma_f32_16x16x32_bf16 v[116:119], v[204:207], v[172:175], v[116:119]
	v_mfma_f32_16x16x32_bf16 v[112:115], v[212:215], v[172:175], v[112:115]
	v_mfma_f32_16x16x32_bf16 v[100:103], v[204:207], v[180:183], v[100:103]
	v_mfma_f32_16x16x32_bf16 v[96:99], v[212:215], v[180:183], v[96:99]
	v_mfma_f32_16x16x32_bf16 v[84:87], v[204:207], v[188:191], v[84:87]
	v_mfma_f32_16x16x32_bf16 v[80:83], v[212:215], v[188:191], v[80:83]
	v_mfma_f32_16x16x32_bf16 v[68:71], v[204:207], v[196:199], v[68:71]
	v_mfma_f32_16x16x32_bf16 v[64:67], v[212:215], v[196:199], v[64:67]
	s_barrier
	global_load_lds_dwordx4 v128, s[22:23]
	s_add_i32 m0, s62, 0x2000
	s_nop 0
	global_load_lds_dwordx4 v130, s[22:23]
	s_mov_b32 m0, s19
	v_lshl_add_u64 v[144:145], s[24:25], 0, v[134:135]
	ds_read_b128 v[168:171], v150 offset:16384
	ds_read_b128 v[172:175], v150 offset:17408
	ds_read_b128 v[176:179], v150 offset:18432
	ds_read_b128 v[180:183], v150 offset:19456
	ds_read_b128 v[184:187], v150 offset:20480
	ds_read_b128 v[188:191], v150 offset:21504
	ds_read_b128 v[192:195], v150 offset:22528
	ds_read_b128 v[196:199], v150 offset:23552
	global_load_lds_dwordx4 v[144:145], off
	v_lshl_add_u64 v[216:217], s[24:25], 0, v[132:133]
	s_mov_b32 m0, s46
	s_nop 0
	global_load_lds_dwordx4 v[216:217], off
	s_add_u32 s62, s22, 0x4000
	s_addc_u32 s63, s23, 0
	s_add_i32 s64, s54, s38
	s_mov_b32 m0, s64
	s_nop 0
	global_load_lds_dwordx4 v128, s[62:63]
	s_add_i32 m0, s64, 0x2000
	s_nop 0
	global_load_lds_dwordx4 v130, s[62:63]
	s_waitcnt vmcnt(8)
	s_waitcnt lgkmcnt(0)
	s_barrier
	v_mfma_f32_16x16x32_bf16 v[60:63], v[152:155], v[168:171], v[60:63]
	v_mfma_f32_16x16x32_bf16 v[56:59], v[160:163], v[168:171], v[56:59]
	v_mfma_f32_16x16x32_bf16 v[44:47], v[152:155], v[176:179], v[44:47]
	v_mfma_f32_16x16x32_bf16 v[40:43], v[160:163], v[176:179], v[40:43]
	v_mfma_f32_16x16x32_bf16 v[28:31], v[152:155], v[184:187], v[28:31]
	v_mfma_f32_16x16x32_bf16 v[24:27], v[160:163], v[184:187], v[24:27]
	v_mfma_f32_16x16x32_bf16 v[12:15], v[152:155], v[192:195], v[12:15]
	v_mfma_f32_16x16x32_bf16 v[8:11], v[160:163], v[192:195], v[8:11]
	v_mfma_f32_16x16x32_bf16 v[60:63], v[156:159], v[172:175], v[60:63]
	v_mfma_f32_16x16x32_bf16 v[56:59], v[164:167], v[172:175], v[56:59]
	v_mfma_f32_16x16x32_bf16 v[44:47], v[156:159], v[180:183], v[44:47]
	v_mfma_f32_16x16x32_bf16 v[40:43], v[164:167], v[180:183], v[40:43]
	v_mfma_f32_16x16x32_bf16 v[28:31], v[156:159], v[188:191], v[28:31]
	v_mfma_f32_16x16x32_bf16 v[24:27], v[164:167], v[188:191], v[24:27]
	v_mfma_f32_16x16x32_bf16 v[12:15], v[156:159], v[196:199], v[12:15]
	v_mfma_f32_16x16x32_bf16 v[8:11], v[164:167], v[196:199], v[8:11]
	v_mfma_f32_16x16x32_bf16 v[52:55], v[200:203], v[168:171], v[52:55]
	v_mfma_f32_16x16x32_bf16 v[48:51], v[208:211], v[168:171], v[48:51]
	v_mfma_f32_16x16x32_bf16 v[36:39], v[200:203], v[176:179], v[36:39]
	v_mfma_f32_16x16x32_bf16 v[32:35], v[208:211], v[176:179], v[32:35]
	v_mfma_f32_16x16x32_bf16 v[20:23], v[200:203], v[184:187], v[20:23]
	v_mfma_f32_16x16x32_bf16 v[16:19], v[208:211], v[184:187], v[16:19]
	v_mfma_f32_16x16x32_bf16 v[4:7], v[200:203], v[192:195], v[4:7]
	v_mfma_f32_16x16x32_bf16 v[0:3], v[208:211], v[192:195], v[0:3]
	v_mfma_f32_16x16x32_bf16 v[52:55], v[204:207], v[172:175], v[52:55]
	v_mfma_f32_16x16x32_bf16 v[48:51], v[212:215], v[172:175], v[48:51]
	v_mfma_f32_16x16x32_bf16 v[36:39], v[204:207], v[180:183], v[36:39]
	v_mfma_f32_16x16x32_bf16 v[32:35], v[212:215], v[180:183], v[32:35]
	v_mfma_f32_16x16x32_bf16 v[20:23], v[204:207], v[188:191], v[20:23]
	v_mfma_f32_16x16x32_bf16 v[16:19], v[212:215], v[188:191], v[16:19]
	v_mfma_f32_16x16x32_bf16 v[4:7], v[204:207], v[196:199], v[4:7]
	v_mfma_f32_16x16x32_bf16 v[0:3], v[212:215], v[196:199], v[0:3]
	s_barrier
; #define PG8_STAGE(bufoff, gbase, voff) do { _Pragma("unroll") for (int _i = 0; _i < 2; ++_i) \
;         __builtin_amdgcn_global_load_lds((const unsigned*)((const char*)(gbase) + (voff)[_i]), (PG8_LAS unsigned*)(lds + (bufoff) + ldsw + _i * 8192), 16, 0, 0); } while (0)
; #define PG8_LDA(dst, b, h) do { _Pragma("unroll") for (int m = 0; m < 4; ++m) _Pragma("unroll") for (int k = 0; k < 2; ++k) dst[m][k] = *(const PG8_LAS bf16x8*)(lds + PG8_SA(b, h) + aoff + m * 2048 + k * 1024); } while (0)
; #define PG8_LDB(dst, b, h) do { _Pragma("unroll") for (int n = 0; n < 2; ++n) _Pragma("unroll") for (int k = 0; k < 2; ++k) dst[n][k] = *(const PG8_LAS bf16x8*)(lds + PG8_SB(b, h) + boff + n * 2048 + k * 1024); } while (0)
; #define PG8_MMA(ai, bj, At, Bt) do { __builtin_amdgcn_s_setprio(1); _Pragma("unroll") for (int m = 0; m < 4; ++m) _Pragma("unroll") for (int n = 0; n < 2; ++n) _Pragma("unroll") for (int k = 0; k < 2; ++k) \
;         acc[ai][bj][m][n] = __builtin_amdgcn_mfma_f32_16x16x32_bf16(Bt[n][k], At[m][k], acc[ai][bj][m][n], 0, 0, 0); __builtin_amdgcn_s_setprio(0); } while (0)
; #define PG8_WAIT_V(n) asm volatile("s_waitcnt vmcnt(" #n ")" ::: "memory")
; #define PG8_WAIT_L(n) asm volatile("s_waitcnt lgkmcnt(" #n ")" ::: "memory")
; #define PG8_BAR __builtin_amdgcn_s_barrier()
; #define PG8_SCHED __builtin_amdgcn_sched_barrier(0)
; template <class Epi, class Sched>
; __device__ __forceinline__ void gemm_phase(PG8_LAS unsigned char* lds, const Gemm g, const Sched& S, const Epi& E) {
;     ...
;             PG8_LDB(B0, 1, 0); PG8_SCHED; PG8_LDA(At, 1, 0); PG8_STAGE(PG8_SA(0, 1), a2 + hstep, voffA);
;             PG8_WAIT_L(8); PG8_BAR; PG8_WAIT_L(0); PG8_MMA(0, 0, At, B0); PG8_BAR; PG8_SCHED;
;             PG8_LDB(B1, 1, 1); PG8_STAGE(PG8_SB(1, 0), b3, voffB);
;             PG8_BAR; PG8_WAIT_L(0); PG8_MMA(0, 1, At, B1); PG8_BAR;
;             PG8_LDA(At, 1, 1); PG8_STAGE(PG8_SA(1, 0), a3, voffA);
;             PG8_BAR; PG8_WAIT_L(0); PG8_MMA(1, 0, At, B0); PG8_BAR; PG8_SCHED;
;             PG8_STAGE(PG8_SB(1, 1), b3 + hstepB, voffB);
;             PG8_WAIT_V(6); PG8_BAR; PG8_MMA(1, 1, At, B1); PG8_BAR;
	s_add_i32 s62, 0, 0x18000
	v_add_u32_e32 v164, s62, v147
	ds_read_b128 v[152:155], v164
	ds_read_b128 v[156:159], v164 offset:1024
	ds_read_b128 v[160:163], v164 offset:2048
	ds_read_b128 v[164:167], v164 offset:3072
	s_add_u32 s24, s24, 0x80000
	s_addc_u32 s25, s25, 0
	s_mov_b32 m0, s47
	ds_read_b128 v[168:171], v150 offset:32768
	ds_read_b128 v[172:175], v150 offset:33792
	ds_read_b128 v[176:179], v150 offset:34816
	ds_read_b128 v[180:183], v150 offset:35840
	ds_read_b128 v[184:187], v150 offset:36864
	ds_read_b128 v[188:191], v150 offset:37888
	ds_read_b128 v[192:195], v150 offset:38912
	ds_read_b128 v[196:199], v150 offset:39936
	global_load_lds_dwordx4 v134, s[24:25]
	s_mov_b32 m0, s48
	s_nop 0
	global_load_lds_dwordx4 v132, s[24:25]
	s_add_i32 s63, 0, 0x1c000
	s_add_u32 s24, s22, 0x8000
	s_addc_u32 s25, s23, 0
	s_add_i32 s62, s62, s38
	v_add_u32_e32 v212, s63, v147
	s_mov_b32 m0, s62
	ds_read_b128 v[200:203], v212
	ds_read_b128 v[204:207], v212 offset:1024
	ds_read_b128 v[208:211], v212 offset:2048
	ds_read_b128 v[212:215], v212 offset:3072
	s_waitcnt vmcnt(8)
	s_waitcnt lgkmcnt(0)
	s_barrier
	v_mfma_f32_16x16x32_bf16 v[124:127], v[152:155], v[168:171], v[124:127]
	v_mfma_f32_16x16x32_bf16 v[120:123], v[160:163], v[168:171], v[120:123]
	v_mfma_f32_16x16x32_bf16 v[108:111], v[152:155], v[176:179], v[108:111]
	v_mfma_f32_16x16x32_bf16 v[104:107], v[160:163], v[176:179], v[104:107]
	v_mfma_f32_16x16x32_bf16 v[92:95], v[152:155], v[184:187], v[92:95]
	v_mfma_f32_16x16x32_bf16 v[88:91], v[160:163], v[184:187], v[88:91]
	v_mfma_f32_16x16x32_bf16 v[76:79], v[152:155], v[192:195], v[76:79]
	v_mfma_f32_16x16x32_bf16 v[72:75], v[160:163], v[192:195], v[72:75]
	v_mfma_f32_16x16x32_bf16 v[124:127], v[156:159], v[172:175], v[124:127]
	v_mfma_f32_16x16x32_bf16 v[120:123], v[164:167], v[172:175], v[120:123]
	v_mfma_f32_16x16x32_bf16 v[108:111], v[156:159], v[180:183], v[108:111]
	v_mfma_f32_16x16x32_bf16 v[104:107], v[164:167], v[180:183], v[104:107]
	v_mfma_f32_16x16x32_bf16 v[92:95], v[156:159], v[188:191], v[92:95]
	v_mfma_f32_16x16x32_bf16 v[88:91], v[164:167], v[188:191], v[88:91]
	v_mfma_f32_16x16x32_bf16 v[76:79], v[156:159], v[196:199], v[76:79]
	v_mfma_f32_16x16x32_bf16 v[72:75], v[164:167], v[196:199], v[72:75]
	v_mfma_f32_16x16x32_bf16 v[116:119], v[200:203], v[168:171], v[116:119]
	v_mfma_f32_16x16x32_bf16 v[112:115], v[208:211], v[168:171], v[112:115]
	v_mfma_f32_16x16x32_bf16 v[100:103], v[200:203], v[176:179], v[100:103]
	v_mfma_f32_16x16x32_bf16 v[96:99], v[208:211], v[176:179], v[96:99]
	v_mfma_f32_16x16x32_bf16 v[84:87], v[200:203], v[184:187], v[84:87]
	v_mfma_f32_16x16x32_bf16 v[80:83], v[208:211], v[184:187], v[80:83]
	v_mfma_f32_16x16x32_bf16 v[68:71], v[200:203], v[192:195], v[68:71]
	v_mfma_f32_16x16x32_bf16 v[64:67], v[208:211], v[192:195], v[64:67]
	v_mfma_f32_16x16x32_bf16 v[116:119], v[204:207], v[172:175], v[116:119]
	v_mfma_f32_16x16x32_bf16 v[112:115], v[212:215], v[172:175], v[112:115]
	v_mfma_f32_16x16x32_bf16 v[100:103], v[204:207], v[180:183], v[100:103]
	v_mfma_f32_16x16x32_bf16 v[96:99], v[212:215], v[180:183], v[96:99]
	v_mfma_f32_16x16x32_bf16 v[84:87], v[204:207], v[188:191], v[84:87]
	v_mfma_f32_16x16x32_bf16 v[80:83], v[212:215], v[188:191], v[80:83]
	v_mfma_f32_16x16x32_bf16 v[68:71], v[204:207], v[196:199], v[68:71]
	v_mfma_f32_16x16x32_bf16 v[64:67], v[212:215], v[196:199], v[64:67]
	s_barrier
	global_load_lds_dwordx4 v128, s[24:25]
	s_add_i32 m0, s62, 0x2000
	s_nop 0
	global_load_lds_dwordx4 v130, s[24:25]
	s_mov_b32 m0, s50
	v_lshl_add_u64 v[144:145], v[144:145], 0, s[8:9]
	ds_read_b128 v[168:171], v150 offset:49152
	ds_read_b128 v[172:175], v150 offset:50176
	ds_read_b128 v[176:179], v150 offset:51200
	ds_read_b128 v[180:183], v150 offset:52224
	ds_read_b128 v[184:187], v150 offset:53248
	ds_read_b128 v[188:191], v150 offset:54272
	ds_read_b128 v[192:195], v150 offset:55296
	ds_read_b128 v[196:199], v150 offset:56320
	global_load_lds_dwordx4 v[144:145], off
	v_lshl_add_u64 v[144:145], v[216:217], 0, s[8:9]
	s_mov_b32 m0, s51
	s_nop 0
	global_load_lds_dwordx4 v[144:145], off
	s_add_u32 s22, s22, 0xc000
	s_addc_u32 s23, s23, 0
	s_add_i32 s24, s63, s38
	s_mov_b32 m0, s24
	s_nop 0
	global_load_lds_dwordx4 v128, s[22:23]
	s_add_i32 m0, s24, 0x2000
	s_nop 0
	global_load_lds_dwordx4 v130, s[22:23]
	s_add_i32 s61, s61, 2
	s_add_u32 s59, s59, 0x10000
	s_addc_u32 s60, s60, 0
	s_add_u32 s20, s20, 0x100
	s_addc_u32 s21, s21, 0
	s_cmp_gt_u32 s61, 29
	s_waitcnt vmcnt(8)
	s_waitcnt lgkmcnt(0)
	s_barrier
	v_mfma_f32_16x16x32_bf16 v[60:63], v[152:155], v[168:171], v[60:63]
	v_mfma_f32_16x16x32_bf16 v[56:59], v[160:163], v[168:171], v[56:59]
	v_mfma_f32_16x16x32_bf16 v[44:47], v[152:155], v[176:179], v[44:47]
	v_mfma_f32_16x16x32_bf16 v[40:43], v[160:163], v[176:179], v[40:43]
	v_mfma_f32_16x16x32_bf16 v[28:31], v[152:155], v[184:187], v[28:31]
	v_mfma_f32_16x16x32_bf16 v[24:27], v[160:163], v[184:187], v[24:27]
	v_mfma_f32_16x16x32_bf16 v[12:15], v[152:155], v[192:195], v[12:15]
	v_mfma_f32_16x16x32_bf16 v[8:11], v[160:163], v[192:195], v[8:11]
	v_mfma_f32_16x16x32_bf16 v[60:63], v[156:159], v[172:175], v[60:63]
	v_mfma_f32_16x16x32_bf16 v[56:59], v[164:167], v[172:175], v[56:59]
	v_mfma_f32_16x16x32_bf16 v[44:47], v[156:159], v[180:183], v[44:47]
	v_mfma_f32_16x16x32_bf16 v[40:43], v[164:167], v[180:183], v[40:43]
	v_mfma_f32_16x16x32_bf16 v[28:31], v[156:159], v[188:191], v[28:31]
	v_mfma_f32_16x16x32_bf16 v[24:27], v[164:167], v[188:191], v[24:27]
	v_mfma_f32_16x16x32_bf16 v[12:15], v[156:159], v[196:199], v[12:15]
	v_mfma_f32_16x16x32_bf16 v[8:11], v[164:167], v[196:199], v[8:11]
	v_mfma_f32_16x16x32_bf16 v[52:55], v[200:203], v[168:171], v[52:55]
	v_mfma_f32_16x16x32_bf16 v[48:51], v[208:211], v[168:171], v[48:51]
	v_mfma_f32_16x16x32_bf16 v[36:39], v[200:203], v[176:179], v[36:39]
	v_mfma_f32_16x16x32_bf16 v[32:35], v[208:211], v[176:179], v[32:35]
	v_mfma_f32_16x16x32_bf16 v[20:23], v[200:203], v[184:187], v[20:23]
	v_mfma_f32_16x16x32_bf16 v[16:19], v[208:211], v[184:187], v[16:19]
	v_mfma_f32_16x16x32_bf16 v[4:7], v[200:203], v[192:195], v[4:7]
	v_mfma_f32_16x16x32_bf16 v[0:3], v[208:211], v[192:195], v[0:3]
	v_mfma_f32_16x16x32_bf16 v[52:55], v[204:207], v[172:175], v[52:55]
	v_mfma_f32_16x16x32_bf16 v[48:51], v[212:215], v[172:175], v[48:51]
	v_mfma_f32_16x16x32_bf16 v[36:39], v[204:207], v[180:183], v[36:39]
	v_mfma_f32_16x16x32_bf16 v[32:35], v[212:215], v[180:183], v[32:35]
	s_cbranch_scc1 .Lunit_exit_6
	v_mfma_f32_16x16x32_bf16 v[20:23], v[204:207], v[188:191], v[20:23]
	v_mfma_f32_16x16x32_bf16 v[16:19], v[212:215], v[188:191], v[16:19]
	v_mfma_f32_16x16x32_bf16 v[4:7], v[204:207], v[196:199], v[4:7]
	v_mfma_f32_16x16x32_bf16 v[0:3], v[212:215], v[196:199], v[0:3]
	s_barrier
	s_branch .LBB0_904

; #define PG8_STAGE(bufoff, gbase, voff) do { _Pragma("unroll") for (int _i = 0; _i < 2; ++_i) \
;         __builtin_amdgcn_global_load_lds((const unsigned*)((const char*)(gbase) + (voff)[_i]), (PG8_LAS unsigned*)(lds + (bufoff) + ldsw + _i * 8192), 16, 0, 0); } while (0)
; #define PG8_LDA(dst, b, h) do { _Pragma("unroll") for (int m = 0; m < 4; ++m) _Pragma("unroll") for (int k = 0; k < 2; ++k) dst[m][k] = *(const PG8_LAS bf16x8*)(lds + PG8_SA(b, h) + aoff + m * 2048 + k * 1024); } while (0)
; #define PG8_LDB(dst, b, h) do { _Pragma("unroll") for (int n = 0; n < 2; ++n) _Pragma("unroll") for (int k = 0; k < 2; ++k) dst[n][k] = *(const PG8_LAS bf16x8*)(lds + PG8_SB(b, h) + boff + n * 2048 + k * 1024); } while (0)
; #define PG8_MMA(ai, bj, At, Bt) do { __builtin_amdgcn_s_setprio(1); _Pragma("unroll") for (int m = 0; m < 4; ++m) _Pragma("unroll") for (int n = 0; n < 2; ++n) _Pragma("unroll") for (int k = 0; k < 2; ++k) \
;         acc[ai][bj][m][n] = __builtin_amdgcn_mfma_f32_16x16x32_bf16(Bt[n][k], At[m][k], acc[ai][bj][m][n], 0, 0, 0); __builtin_amdgcn_s_setprio(0); } while (0)
; #define PG8_WAIT_V(n) asm volatile("s_waitcnt vmcnt(" #n ")" ::: "memory")
; #define PG8_WAIT_L(n) asm volatile("s_waitcnt lgkmcnt(" #n ")" ::: "memory")
; template <class Epi, class Sched>
; __device__ __forceinline__ void gemm_phase(PG8_LAS unsigned char* lds, const Gemm g, const Sched& S, const Epi& E) {
;     ...
;             const bool last = (t == nt - 2);
;             const char* a1 = cA + (size_t)(t + 1) * kstep;
;             const char* a2 = last ? nA : cA + (size_t)(t + 2) * kstep; const char* b2 = last ? nB : cB + (size_t)(t + 2) * kstepB;
;             const char* a3 = a2 + kstep; const char* b3 = b2 + kstepB;
;             if (last && has_next) S.a_ready(nxt);
;             PG8_LDB(B0, 0, 0); PG8_SCHED; PG8_LDA(At, 0, 0); PG8_STAGE(PG8_SA(1, 1), a1 + hstep, voffA);
;             PG8_WAIT_L(8); PG8_BAR; PG8_WAIT_L(0); PG8_MMA(0, 0, At, B0); PG8_BAR; PG8_SCHED;
;             PG8_LDB(B1, 0, 1); PG8_STAGE(PG8_SB(0, 0), b2, voffB);
;             PG8_BAR; PG8_WAIT_L(0); PG8_MMA(0, 1, At, B1); PG8_BAR;
;             PG8_LDA(At, 0, 1); PG8_STAGE(PG8_SA(0, 0), a2, voffA);
;             PG8_BAR; PG8_WAIT_L(0); PG8_MMA(1, 0, At, B0); PG8_BAR; PG8_SCHED;
;             PG8_STAGE(PG8_SB(0, 1), b2 + hstepB, voffB);
;             PG8_WAIT_V(6); PG8_BAR; PG8_MMA(1, 1, At, B1); PG8_BAR;
.Lhalf_skip_y_7:
.LBB0_980:
	ds_read_b128 v[128:131], v197
	ds_read_b128 v[132:135], v197 offset:1024
	ds_read_b128 v[136:139], v197 offset:2048
	ds_read_b128 v[140:143], v197 offset:3072
	s_add_u32 s24, s22, 0x100
	s_addc_u32 s25, s23, 0
	s_cmpk_eq_i32 s65, 0x52
	s_cselect_b32 s29, s7, s25
	s_cselect_b32 s28, s6, s24
	s_cselect_b32 s27, s9, s64
	s_cselect_b32 s26, s8, s63
	v_lshl_add_u64 v[192:193], s[22:23], 0, v[172:173]
	s_add_i32 m0, s49, 0xc000
	ds_read_b128 v[144:147], v198
	ds_read_b128 v[148:151], v198 offset:1024
	ds_read_b128 v[152:155], v198 offset:2048
	ds_read_b128 v[156:159], v198 offset:3072
	ds_read_b128 v[160:163], v198 offset:4096
	ds_read_b128 v[180:183], v198 offset:5120
	ds_read_b128 v[184:187], v198 offset:6144
	ds_read_b128 v[188:191], v198 offset:7168
	global_load_lds_dwordx4 v[192:193], off
	v_lshl_add_u64 v[192:193], s[22:23], 0, v[174:175]
	s_add_i32 m0, s49, 0xe000
	s_nop 0
	global_load_lds_dwordx4 v[192:193], off
	s_add_i32 s22, s57, s48
	s_mov_b32 m0, s22
	ds_read_b128 v[200:203], v199
	ds_read_b128 v[204:207], v199 offset:1024
	ds_read_b128 v[208:211], v199 offset:2048
	ds_read_b128 v[212:215], v199 offset:3072
	s_waitcnt vmcnt(8)
	s_waitcnt lgkmcnt(0)
	s_barrier
	v_mfma_f32_16x16x32_bf16 v[124:127], v[128:131], v[144:147], v[124:127]
	v_mfma_f32_16x16x32_bf16 v[120:123], v[136:139], v[144:147], v[120:123]
	v_mfma_f32_16x16x32_bf16 v[116:119], v[128:131], v[152:155], v[116:119]
	v_mfma_f32_16x16x32_bf16 v[104:107], v[136:139], v[152:155], v[104:107]
	v_mfma_f32_16x16x32_bf16 v[92:95], v[128:131], v[160:163], v[92:95]
	v_mfma_f32_16x16x32_bf16 v[88:91], v[136:139], v[160:163], v[88:91]
	v_mfma_f32_16x16x32_bf16 v[76:79], v[128:131], v[184:187], v[76:79]
	v_mfma_f32_16x16x32_bf16 v[72:75], v[136:139], v[184:187], v[72:75]
	v_mfma_f32_16x16x32_bf16 v[124:127], v[132:135], v[148:151], v[124:127]
	v_mfma_f32_16x16x32_bf16 v[120:123], v[140:143], v[148:151], v[120:123]
	v_mfma_f32_16x16x32_bf16 v[116:119], v[132:135], v[156:159], v[116:119]
	v_mfma_f32_16x16x32_bf16 v[104:107], v[140:143], v[156:159], v[104:107]
	v_mfma_f32_16x16x32_bf16 v[92:95], v[132:135], v[180:183], v[92:95]
	v_mfma_f32_16x16x32_bf16 v[88:91], v[140:143], v[180:183], v[88:91]
	v_mfma_f32_16x16x32_bf16 v[76:79], v[132:135], v[188:191], v[76:79]
	v_mfma_f32_16x16x32_bf16 v[72:75], v[140:143], v[188:191], v[72:75]
	v_mfma_f32_16x16x32_bf16 v[112:115], v[200:203], v[144:147], v[112:115]
	v_mfma_f32_16x16x32_bf16 v[108:111], v[208:211], v[144:147], v[108:111]
	v_mfma_f32_16x16x32_bf16 v[100:103], v[200:203], v[152:155], v[100:103]
	v_mfma_f32_16x16x32_bf16 v[96:99], v[208:211], v[152:155], v[96:99]
	v_mfma_f32_16x16x32_bf16 v[84:87], v[200:203], v[160:163], v[84:87]
	v_mfma_f32_16x16x32_bf16 v[80:83], v[208:211], v[160:163], v[80:83]
	v_mfma_f32_16x16x32_bf16 v[68:71], v[200:203], v[184:187], v[68:71]
	v_mfma_f32_16x16x32_bf16 v[64:67], v[208:211], v[184:187], v[64:67]
	v_mfma_f32_16x16x32_bf16 v[112:115], v[204:207], v[148:151], v[112:115]
	v_mfma_f32_16x16x32_bf16 v[108:111], v[212:215], v[148:151], v[108:111]
	v_mfma_f32_16x16x32_bf16 v[100:103], v[204:207], v[156:159], v[100:103]
	v_mfma_f32_16x16x32_bf16 v[96:99], v[212:215], v[156:159], v[96:99]
	v_mfma_f32_16x16x32_bf16 v[84:87], v[204:207], v[180:183], v[84:87]
	v_mfma_f32_16x16x32_bf16 v[80:83], v[212:215], v[180:183], v[80:83]
	v_mfma_f32_16x16x32_bf16 v[68:71], v[204:207], v[188:191], v[68:71]
	v_mfma_f32_16x16x32_bf16 v[64:67], v[212:215], v[188:191], v[64:67]
	s_barrier
	global_load_lds_dwordx4 v164, s[26:27]
	s_add_i32 m0, s22, 0x2000
	s_nop 0
	global_load_lds_dwordx4 v168, s[26:27]
	s_mov_b32 m0, s49
	v_lshl_add_u64 v[192:193], s[28:29], 0, v[166:167]
	ds_read_b128 v[144:147], v198 offset:16384
	ds_read_b128 v[148:151], v198 offset:17408
	ds_read_b128 v[152:155], v198 offset:18432
	ds_read_b128 v[156:159], v198 offset:19456
	ds_read_b128 v[160:163], v198 offset:20480
	ds_read_b128 v[180:183], v198 offset:21504
	ds_read_b128 v[184:187], v198 offset:22528
	ds_read_b128 v[188:191], v198 offset:23552
	global_load_lds_dwordx4 v[192:193], off
	v_lshl_add_u64 v[216:217], s[28:29], 0, v[170:171]
	s_mov_b32 m0, s50
	s_nop 0
	global_load_lds_dwordx4 v[216:217], off
	s_add_u32 s22, s26, 0x4000
	s_addc_u32 s23, s27, 0
	s_add_i32 s66, s58, s48
	s_mov_b32 m0, s66
	s_nop 0
	global_load_lds_dwordx4 v164, s[22:23]
	s_add_i32 m0, s66, 0x2000
	s_nop 0
	global_load_lds_dwordx4 v168, s[22:23]
	s_waitcnt vmcnt(8)
	s_waitcnt lgkmcnt(0)
	s_barrier
	v_mfma_f32_16x16x32_bf16 v[60:63], v[128:131], v[144:147], v[60:63]
	v_mfma_f32_16x16x32_bf16 v[56:59], v[136:139], v[144:147], v[56:59]
	v_mfma_f32_16x16x32_bf16 v[44:47], v[128:131], v[152:155], v[44:47]
	v_mfma_f32_16x16x32_bf16 v[40:43], v[136:139], v[152:155], v[40:43]
	v_mfma_f32_16x16x32_bf16 v[28:31], v[128:131], v[160:163], v[28:31]
	v_mfma_f32_16x16x32_bf16 v[24:27], v[136:139], v[160:163], v[24:27]
	v_mfma_f32_16x16x32_bf16 v[12:15], v[128:131], v[184:187], v[12:15]
	v_mfma_f32_16x16x32_bf16 v[8:11], v[136:139], v[184:187], v[8:11]
	v_mfma_f32_16x16x32_bf16 v[60:63], v[132:135], v[148:151], v[60:63]
	v_mfma_f32_16x16x32_bf16 v[56:59], v[140:143], v[148:151], v[56:59]
	v_mfma_f32_16x16x32_bf16 v[44:47], v[132:135], v[156:159], v[44:47]
	v_mfma_f32_16x16x32_bf16 v[40:43], v[140:143], v[156:159], v[40:43]
	v_mfma_f32_16x16x32_bf16 v[28:31], v[132:135], v[180:183], v[28:31]
	v_mfma_f32_16x16x32_bf16 v[24:27], v[140:143], v[180:183], v[24:27]
	v_mfma_f32_16x16x32_bf16 v[12:15], v[132:135], v[188:191], v[12:15]
	v_mfma_f32_16x16x32_bf16 v[8:11], v[140:143], v[188:191], v[8:11]
	v_mfma_f32_16x16x32_bf16 v[52:55], v[200:203], v[144:147], v[52:55]
	v_mfma_f32_16x16x32_bf16 v[48:51], v[208:211], v[144:147], v[48:51]
	v_mfma_f32_16x16x32_bf16 v[36:39], v[200:203], v[152:155], v[36:39]
	v_mfma_f32_16x16x32_bf16 v[32:35], v[208:211], v[152:155], v[32:35]
	v_mfma_f32_16x16x32_bf16 v[20:23], v[200:203], v[160:163], v[20:23]
	v_mfma_f32_16x16x32_bf16 v[16:19], v[208:211], v[160:163], v[16:19]
	v_mfma_f32_16x16x32_bf16 v[4:7], v[200:203], v[184:187], v[4:7]
	v_mfma_f32_16x16x32_bf16 v[0:3], v[208:211], v[184:187], v[0:3]
	v_mfma_f32_16x16x32_bf16 v[52:55], v[204:207], v[148:151], v[52:55]
	v_mfma_f32_16x16x32_bf16 v[48:51], v[212:215], v[148:151], v[48:51]
	v_mfma_f32_16x16x32_bf16 v[36:39], v[204:207], v[156:159], v[36:39]
	v_mfma_f32_16x16x32_bf16 v[32:35], v[212:215], v[156:159], v[32:35]
	v_mfma_f32_16x16x32_bf16 v[20:23], v[204:207], v[180:183], v[20:23]
	v_mfma_f32_16x16x32_bf16 v[16:19], v[212:215], v[180:183], v[16:19]
	v_mfma_f32_16x16x32_bf16 v[4:7], v[204:207], v[188:191], v[4:7]
	v_mfma_f32_16x16x32_bf16 v[0:3], v[212:215], v[188:191], v[0:3]
	s_barrier
; #define PG8_STAGE(bufoff, gbase, voff) do { _Pragma("unroll") for (int _i = 0; _i < 2; ++_i) \
;         __builtin_amdgcn_global_load_lds((const unsigned*)((const char*)(gbase) + (voff)[_i]), (PG8_LAS unsigned*)(lds + (bufoff) + ldsw + _i * 8192), 16, 0, 0); } while (0)
; #define PG8_LDA(dst, b, h) do { _Pragma("unroll") for (int m = 0; m < 4; ++m) _Pragma("unroll") for (int k = 0; k < 2; ++k) dst[m][k] = *(const PG8_LAS bf16x8*)(lds + PG8_SA(b, h) + aoff + m * 2048 + k * 1024); } while (0)
; #define PG8_LDB(dst, b, h) do { _Pragma("unroll") for (int n = 0; n < 2; ++n) _Pragma("unroll") for (int k = 0; k < 2; ++k) dst[n][k] = *(const PG8_LAS bf16x8*)(lds + PG8_SB(b, h) + boff + n * 2048 + k * 1024); } while (0)
; #define PG8_MMA(ai, bj, At, Bt) do { __builtin_amdgcn_s_setprio(1); _Pragma("unroll") for (int m = 0; m < 4; ++m) _Pragma("unroll") for (int n = 0; n < 2; ++n) _Pragma("unroll") for (int k = 0; k < 2; ++k) \
;         acc[ai][bj][m][n] = __builtin_amdgcn_mfma_f32_16x16x32_bf16(Bt[n][k], At[m][k], acc[ai][bj][m][n], 0, 0, 0); __builtin_amdgcn_s_setprio(0); } while (0)
; #define PG8_WAIT_V(n) asm volatile("s_waitcnt vmcnt(" #n ")" ::: "memory")
; #define PG8_WAIT_L(n) asm volatile("s_waitcnt lgkmcnt(" #n ")" ::: "memory")
; #define PG8_BAR __builtin_amdgcn_s_barrier()
; #define PG8_SCHED __builtin_amdgcn_sched_barrier(0)
; template <class Epi, class Sched>
; __device__ __forceinline__ void gemm_phase(PG8_LAS unsigned char* lds, const Gemm g, const Sched& S, const Epi& E) {
;     ...
;             PG8_LDB(B0, 1, 0); PG8_SCHED; PG8_LDA(At, 1, 0); PG8_STAGE(PG8_SA(0, 1), a2 + hstep, voffA);
;             PG8_WAIT_L(8); PG8_BAR; PG8_WAIT_L(0); PG8_MMA(0, 0, At, B0); PG8_BAR; PG8_SCHED;
;             PG8_LDB(B1, 1, 1); PG8_STAGE(PG8_SB(1, 0), b3, voffB);
;             PG8_BAR; PG8_WAIT_L(0); PG8_MMA(0, 1, At, B1); PG8_BAR;
;             PG8_LDA(At, 1, 1); PG8_STAGE(PG8_SA(1, 0), a3, voffA);
;             PG8_BAR; PG8_WAIT_L(0); PG8_MMA(1, 0, At, B0); PG8_BAR; PG8_SCHED;
;             PG8_STAGE(PG8_SB(1, 1), b3 + hstepB, voffB);
;             PG8_WAIT_V(6); PG8_BAR; PG8_MMA(1, 1, At, B1); PG8_BAR;
	s_add_i32 s66, 0, 0x18000
	v_add_u32_e32 v140, s66, v195
	ds_read_b128 v[128:131], v140
	ds_read_b128 v[132:135], v140 offset:1024
	ds_read_b128 v[136:139], v140 offset:2048
	ds_read_b128 v[140:143], v140 offset:3072
	s_add_u32 s22, s28, 0x158000
	s_addc_u32 s23, s29, 0
	s_mov_b32 m0, s51
	ds_read_b128 v[144:147], v198 offset:32768
	ds_read_b128 v[148:151], v198 offset:33792
	ds_read_b128 v[152:155], v198 offset:34816
	ds_read_b128 v[156:159], v198 offset:35840
	ds_read_b128 v[160:163], v198 offset:36864
	ds_read_b128 v[180:183], v198 offset:37888
	ds_read_b128 v[184:187], v198 offset:38912
	ds_read_b128 v[188:191], v198 offset:39936
	global_load_lds_dwordx4 v166, s[22:23]
	s_mov_b32 m0, s52
	s_nop 0
	global_load_lds_dwordx4 v170, s[22:23]
	s_add_i32 s28, 0, 0x1c000
	s_add_u32 s22, s26, 0x8000
	s_addc_u32 s23, s27, 0
	s_add_i32 s29, s66, s48
	v_add_u32_e32 v212, s28, v195
	s_mov_b32 m0, s29
	ds_read_b128 v[200:203], v212
	ds_read_b128 v[204:207], v212 offset:1024
	ds_read_b128 v[208:211], v212 offset:2048
	ds_read_b128 v[212:215], v212 offset:3072
	s_waitcnt vmcnt(8)
	s_waitcnt lgkmcnt(0)
	s_barrier
	v_mfma_f32_16x16x32_bf16 v[124:127], v[128:131], v[144:147], v[124:127]
	v_mfma_f32_16x16x32_bf16 v[120:123], v[136:139], v[144:147], v[120:123]
	v_mfma_f32_16x16x32_bf16 v[116:119], v[128:131], v[152:155], v[116:119]
	v_mfma_f32_16x16x32_bf16 v[104:107], v[136:139], v[152:155], v[104:107]
	v_mfma_f32_16x16x32_bf16 v[92:95], v[128:131], v[160:163], v[92:95]
	v_mfma_f32_16x16x32_bf16 v[88:91], v[136:139], v[160:163], v[88:91]
	v_mfma_f32_16x16x32_bf16 v[76:79], v[128:131], v[184:187], v[76:79]
	v_mfma_f32_16x16x32_bf16 v[72:75], v[136:139], v[184:187], v[72:75]
	v_mfma_f32_16x16x32_bf16 v[124:127], v[132:135], v[148:151], v[124:127]
	v_mfma_f32_16x16x32_bf16 v[120:123], v[140:143], v[148:151], v[120:123]
	v_mfma_f32_16x16x32_bf16 v[116:119], v[132:135], v[156:159], v[116:119]
	v_mfma_f32_16x16x32_bf16 v[104:107], v[140:143], v[156:159], v[104:107]
	v_mfma_f32_16x16x32_bf16 v[92:95], v[132:135], v[180:183], v[92:95]
	v_mfma_f32_16x16x32_bf16 v[88:91], v[140:143], v[180:183], v[88:91]
	v_mfma_f32_16x16x32_bf16 v[76:79], v[132:135], v[188:191], v[76:79]
	v_mfma_f32_16x16x32_bf16 v[72:75], v[140:143], v[188:191], v[72:75]
	v_mfma_f32_16x16x32_bf16 v[112:115], v[200:203], v[144:147], v[112:115]
	v_mfma_f32_16x16x32_bf16 v[108:111], v[208:211], v[144:147], v[108:111]
	v_mfma_f32_16x16x32_bf16 v[100:103], v[200:203], v[152:155], v[100:103]
	v_mfma_f32_16x16x32_bf16 v[96:99], v[208:211], v[152:155], v[96:99]
	v_mfma_f32_16x16x32_bf16 v[84:87], v[200:203], v[160:163], v[84:87]
	v_mfma_f32_16x16x32_bf16 v[80:83], v[208:211], v[160:163], v[80:83]
	v_mfma_f32_16x16x32_bf16 v[68:71], v[200:203], v[184:187], v[68:71]
	v_mfma_f32_16x16x32_bf16 v[64:67], v[208:211], v[184:187], v[64:67]
	v_mfma_f32_16x16x32_bf16 v[112:115], v[204:207], v[148:151], v[112:115]
	v_mfma_f32_16x16x32_bf16 v[108:111], v[212:215], v[148:151], v[108:111]
	v_mfma_f32_16x16x32_bf16 v[100:103], v[204:207], v[156:159], v[100:103]
	v_mfma_f32_16x16x32_bf16 v[96:99], v[212:215], v[156:159], v[96:99]
	v_mfma_f32_16x16x32_bf16 v[84:87], v[204:207], v[180:183], v[84:87]
	v_mfma_f32_16x16x32_bf16 v[80:83], v[212:215], v[180:183], v[80:83]
	v_mfma_f32_16x16x32_bf16 v[68:71], v[204:207], v[188:191], v[68:71]
	v_mfma_f32_16x16x32_bf16 v[64:67], v[212:215], v[188:191], v[64:67]
	s_barrier
	global_load_lds_dwordx4 v164, s[22:23]
	s_add_i32 m0, s29, 0x2000
	s_nop 0
	global_load_lds_dwordx4 v168, s[22:23]
	s_mov_b32 m0, s54
	v_lshl_add_u64 v[192:193], v[192:193], 0, s[12:13]
	ds_read_b128 v[144:147], v198 offset:49152
	ds_read_b128 v[148:151], v198 offset:50176
	ds_read_b128 v[152:155], v198 offset:51200
	ds_read_b128 v[156:159], v198 offset:52224
	ds_read_b128 v[160:163], v198 offset:53248
	ds_read_b128 v[180:183], v198 offset:54272
	ds_read_b128 v[184:187], v198 offset:55296
	ds_read_b128 v[188:191], v198 offset:56320
	global_load_lds_dwordx4 v[192:193], off
	v_lshl_add_u64 v[192:193], v[216:217], 0, s[12:13]
	s_mov_b32 m0, s55
	s_nop 0
	global_load_lds_dwordx4 v[192:193], off
	s_add_u32 s22, s26, 0xc000
	s_addc_u32 s23, s27, 0
	s_add_i32 s26, s28, s48
	s_mov_b32 m0, s26
	s_nop 0
	global_load_lds_dwordx4 v164, s[22:23]
	s_add_i32 m0, s26, 0x2000
	s_nop 0
	global_load_lds_dwordx4 v168, s[22:23]
	s_add_i32 s65, s65, 2
	s_add_u32 s63, s63, 0x10000
	s_addc_u32 s64, s64, 0
	s_cmpk_gt_u32 s65, 0x53
	s_mov_b64 s[22:23], s[24:25]
	s_waitcnt vmcnt(8)
	s_waitcnt lgkmcnt(0)
	s_barrier
	v_mfma_f32_16x16x32_bf16 v[60:63], v[128:131], v[144:147], v[60:63]
	v_mfma_f32_16x16x32_bf16 v[56:59], v[136:139], v[144:147], v[56:59]
	v_mfma_f32_16x16x32_bf16 v[44:47], v[128:131], v[152:155], v[44:47]
	v_mfma_f32_16x16x32_bf16 v[40:43], v[136:139], v[152:155], v[40:43]
	v_mfma_f32_16x16x32_bf16 v[28:31], v[128:131], v[160:163], v[28:31]
	v_mfma_f32_16x16x32_bf16 v[24:27], v[136:139], v[160:163], v[24:27]
	v_mfma_f32_16x16x32_bf16 v[12:15], v[128:131], v[184:187], v[12:15]
	v_mfma_f32_16x16x32_bf16 v[8:11], v[136:139], v[184:187], v[8:11]
	v_mfma_f32_16x16x32_bf16 v[60:63], v[132:135], v[148:151], v[60:63]
	v_mfma_f32_16x16x32_bf16 v[56:59], v[140:143], v[148:151], v[56:59]
	v_mfma_f32_16x16x32_bf16 v[44:47], v[132:135], v[156:159], v[44:47]
	v_mfma_f32_16x16x32_bf16 v[40:43], v[140:143], v[156:159], v[40:43]
	v_mfma_f32_16x16x32_bf16 v[28:31], v[132:135], v[180:183], v[28:31]
	v_mfma_f32_16x16x32_bf16 v[24:27], v[140:143], v[180:183], v[24:27]
	v_mfma_f32_16x16x32_bf16 v[12:15], v[132:135], v[188:191], v[12:15]
	v_mfma_f32_16x16x32_bf16 v[8:11], v[140:143], v[188:191], v[8:11]
	v_mfma_f32_16x16x32_bf16 v[52:55], v[200:203], v[144:147], v[52:55]
	v_mfma_f32_16x16x32_bf16 v[48:51], v[208:211], v[144:147], v[48:51]
	v_mfma_f32_16x16x32_bf16 v[36:39], v[200:203], v[152:155], v[36:39]
	v_mfma_f32_16x16x32_bf16 v[32:35], v[208:211], v[152:155], v[32:35]
	v_mfma_f32_16x16x32_bf16 v[20:23], v[200:203], v[160:163], v[20:23]
	v_mfma_f32_16x16x32_bf16 v[16:19], v[208:211], v[160:163], v[16:19]
	v_mfma_f32_16x16x32_bf16 v[4:7], v[200:203], v[184:187], v[4:7]
	v_mfma_f32_16x16x32_bf16 v[0:3], v[208:211], v[184:187], v[0:3]
	v_mfma_f32_16x16x32_bf16 v[52:55], v[204:207], v[148:151], v[52:55]
	v_mfma_f32_16x16x32_bf16 v[48:51], v[212:215], v[148:151], v[48:51]
	v_mfma_f32_16x16x32_bf16 v[36:39], v[204:207], v[156:159], v[36:39]
	v_mfma_f32_16x16x32_bf16 v[32:35], v[212:215], v[156:159], v[32:35]
	s_cbranch_scc1 .Lunit_exit_7
	v_mfma_f32_16x16x32_bf16 v[20:23], v[204:207], v[180:183], v[20:23]
	v_mfma_f32_16x16x32_bf16 v[16:19], v[212:215], v[180:183], v[16:19]
	v_mfma_f32_16x16x32_bf16 v[4:7], v[204:207], v[188:191], v[4:7]
	v_mfma_f32_16x16x32_bf16 v[0:3], v[212:215], v[188:191], v[0:3]
	s_barrier
	s_branch .LBB0_980
